# GEMM loops: A-fragment LDS base add hoisted out of the loop (ds_read offsets carry the stage constant), s_nop after M0 writes replaced by a ds_read / scalar add / the vmcnt wait
# speedup vs baseline: 1.0293x; 1.0066x over previous
.LBB0_57:
	s_add_u32 s20, s44, 0x100
	v_mov_b32_e32 v4, 0
	s_addc_u32 s21, s45, 0
	s_mov_b32 s22, -2
	v_mov_b32_e32 v5, v4
	v_mov_b32_e32 v6, v4
	v_mov_b32_e32 v7, v4
	v_mov_b32_e32 v8, v4
	v_mov_b32_e32 v9, v4
	v_mov_b32_e32 v10, v4
	v_mov_b32_e32 v11, v4
	v_mov_b32_e32 v12, v4
	v_mov_b32_e32 v13, v4
	v_mov_b32_e32 v14, v4
	v_mov_b32_e32 v15, v4
	v_mov_b32_e32 v20, v4
	v_mov_b32_e32 v21, v4
	v_mov_b32_e32 v22, v4
	v_mov_b32_e32 v23, v4
	v_mov_b32_e32 v28, v4
	v_mov_b32_e32 v29, v4
	v_mov_b32_e32 v30, v4
	v_mov_b32_e32 v31, v4
	v_mov_b32_e32 v32, v4
	v_mov_b32_e32 v33, v4
	v_mov_b32_e32 v34, v4
	v_mov_b32_e32 v35, v4
	v_mov_b32_e32 v44, v4
	v_mov_b32_e32 v45, v4
	v_mov_b32_e32 v46, v4
	v_mov_b32_e32 v47, v4
	v_mov_b32_e32 v48, v4
	v_mov_b32_e32 v49, v4
	v_mov_b32_e32 v50, v4
	v_mov_b32_e32 v51, v4
	v_mov_b32_e32 v16, v4
	v_mov_b32_e32 v17, v4
	v_mov_b32_e32 v18, v4
	v_mov_b32_e32 v19, v4
	v_mov_b32_e32 v24, v4
	v_mov_b32_e32 v25, v4
	v_mov_b32_e32 v26, v4
	v_mov_b32_e32 v27, v4
	v_mov_b32_e32 v36, v4
	v_mov_b32_e32 v37, v4
	v_mov_b32_e32 v38, v4
	v_mov_b32_e32 v39, v4
	v_mov_b32_e32 v40, v4
	v_mov_b32_e32 v41, v4
	v_mov_b32_e32 v42, v4
	v_mov_b32_e32 v43, v4
	v_mov_b32_e32 v52, v4
	v_mov_b32_e32 v53, v4
	v_mov_b32_e32 v54, v4
	v_mov_b32_e32 v55, v4
	v_mov_b32_e32 v56, v4
	v_mov_b32_e32 v57, v4
	v_mov_b32_e32 v58, v4
	v_mov_b32_e32 v59, v4
	v_mov_b32_e32 v60, v4
	v_mov_b32_e32 v61, v4
	v_mov_b32_e32 v62, v4
	v_mov_b32_e32 v63, v4
	v_mov_b32_e32 v64, v4
	v_mov_b32_e32 v65, v4
	v_mov_b32_e32 v66, v4
	v_mov_b32_e32 v67, v4
	v_mov_b32_e32 v68, v4
	v_mov_b32_e32 v69, v4
	v_mov_b32_e32 v70, v4
	v_mov_b32_e32 v71, v4
	v_mov_b32_e32 v72, v4
	v_mov_b32_e32 v73, v4
	v_mov_b32_e32 v74, v4
	v_mov_b32_e32 v75, v4
	v_mov_b32_e32 v76, v4
	v_mov_b32_e32 v77, v4
	v_mov_b32_e32 v78, v4
	v_mov_b32_e32 v79, v4
	v_mov_b32_e32 v80, v4
	v_mov_b32_e32 v81, v4
	v_mov_b32_e32 v82, v4
	v_mov_b32_e32 v83, v4
	v_mov_b32_e32 v92, v4
	v_mov_b32_e32 v93, v4
	v_mov_b32_e32 v94, v4
	v_mov_b32_e32 v95, v4
	v_mov_b32_e32 v96, v4
	v_mov_b32_e32 v97, v4
	v_mov_b32_e32 v98, v4
	v_mov_b32_e32 v99, v4
	v_mov_b32_e32 v108, v4
	v_mov_b32_e32 v109, v4
	v_mov_b32_e32 v110, v4
	v_mov_b32_e32 v111, v4
	v_mov_b32_e32 v112, v4
	v_mov_b32_e32 v113, v4
	v_mov_b32_e32 v114, v4
	v_mov_b32_e32 v115, v4
	v_mov_b32_e32 v84, v4
	v_mov_b32_e32 v85, v4
	v_mov_b32_e32 v86, v4
	v_mov_b32_e32 v87, v4
	v_mov_b32_e32 v88, v4
	v_mov_b32_e32 v89, v4
	v_mov_b32_e32 v90, v4
	v_mov_b32_e32 v91, v4
	v_mov_b32_e32 v100, v4
	v_mov_b32_e32 v101, v4
	v_mov_b32_e32 v102, v4
	v_mov_b32_e32 v103, v4
	v_mov_b32_e32 v104, v4
	v_mov_b32_e32 v105, v4
	v_mov_b32_e32 v106, v4
	v_mov_b32_e32 v107, v4
	v_mov_b32_e32 v116, v4
	v_mov_b32_e32 v117, v4
	v_mov_b32_e32 v118, v4
	v_mov_b32_e32 v119, v4
	v_mov_b32_e32 v120, v4
	v_mov_b32_e32 v121, v4
	v_mov_b32_e32 v122, v4
	v_mov_b32_e32 v123, v4
	v_mov_b32_e32 v124, v4
	v_mov_b32_e32 v125, v4
	v_mov_b32_e32 v126, v4
	v_mov_b32_e32 v127, v4
	v_mov_b32_e32 v128, v4
	v_mov_b32_e32 v129, v4
	v_mov_b32_e32 v130, v4
	v_mov_b32_e32 v131, v4
	v_add_u32_e32 v194, 0x10000, v143
.LBB0_58:
	s_add_u32 s44, s42, 0x100
	s_addc_u32 s45, s43, 0
	s_add_i32 s23, 0, 0x10000
	ds_read_b128 v[146:149], v194
	ds_read_b128 v[150:153], v194 offset:1024
	ds_read_b128 v[154:157], v194 offset:2048
	ds_read_b128 v[158:161], v194 offset:3072
	s_cmp_eq_u32 s22, 40
	s_cselect_b32 s49, s1, s45
	s_cselect_b32 s48, s0, s44
	s_cselect_b32 s47, s41, s21
	s_cselect_b32 s46, s40, s20
	s_add_i32 m0, s52, 0xc000
	ds_read_b128 v[162:165], v144
	ds_read_b128 v[166:169], v144 offset:1024
	ds_read_b128 v[170:173], v144 offset:2048
	ds_read_b128 v[174:177], v144 offset:3072
	ds_read_b128 v[178:181], v144 offset:4096
	ds_read_b128 v[182:185], v144 offset:5120
	ds_read_b128 v[186:189], v144 offset:6144
	global_load_lds_dwordx4 v138, s[42:43]
	s_add_i32 m0, s52, 0xe000
	ds_read_b128 v[190:193], v144 offset:7168
	global_load_lds_dwordx4 v140, s[42:43]
	s_waitcnt lgkmcnt(8)
	s_barrier
	s_waitcnt lgkmcnt(0)
	v_mfma_f32_16x16x32_bf16 v[128:131], v[146:149], v[162:165], v[128:131]
	v_mfma_f32_16x16x32_bf16 v[124:127], v[154:157], v[162:165], v[124:127]
	v_mfma_f32_16x16x32_bf16 v[120:123], v[146:149], v[170:173], v[120:123]
	v_mfma_f32_16x16x32_bf16 v[116:119], v[154:157], v[170:173], v[116:119]
	v_mfma_f32_16x16x32_bf16 v[104:107], v[146:149], v[178:181], v[104:107]
	v_mfma_f32_16x16x32_bf16 v[100:103], v[154:157], v[178:181], v[100:103]
	v_mfma_f32_16x16x32_bf16 v[88:91], v[146:149], v[186:189], v[88:91]
	v_mfma_f32_16x16x32_bf16 v[84:87], v[154:157], v[186:189], v[84:87]
	v_mfma_f32_16x16x32_bf16 v[128:131], v[150:153], v[166:169], v[128:131]
	v_mfma_f32_16x16x32_bf16 v[124:127], v[158:161], v[166:169], v[124:127]
	v_mfma_f32_16x16x32_bf16 v[120:123], v[150:153], v[174:177], v[120:123]
	v_mfma_f32_16x16x32_bf16 v[116:119], v[158:161], v[174:177], v[116:119]
	v_mfma_f32_16x16x32_bf16 v[104:107], v[150:153], v[182:185], v[104:107]
	v_mfma_f32_16x16x32_bf16 v[100:103], v[158:161], v[182:185], v[100:103]
	v_mfma_f32_16x16x32_bf16 v[88:91], v[150:153], v[190:193], v[88:91]
	v_mfma_f32_16x16x32_bf16 v[84:87], v[158:161], v[190:193], v[84:87]
	s_barrier
	s_add_i32 s26, 0, 0x14000
	s_add_i32 s23, s23, s37
	s_mov_b32 m0, s23
	ds_read_b128 v[202:205], v194 offset:16384
	ds_read_b128 v[206:209], v194 offset:17408
	ds_read_b128 v[210:213], v194 offset:18432
	global_load_lds_dwordx4 v132, s[46:47]
	s_add_i32 m0, s23, 0x2000
	ds_read_b128 v[214:217], v194 offset:19456
	global_load_lds_dwordx4 v136, s[46:47]
	s_barrier
	s_waitcnt lgkmcnt(0)
	v_mfma_f32_16x16x32_bf16 v[112:115], v[202:205], v[162:165], v[112:115]
	v_mfma_f32_16x16x32_bf16 v[108:111], v[210:213], v[162:165], v[108:111]
	v_mfma_f32_16x16x32_bf16 v[96:99], v[202:205], v[170:173], v[96:99]
	v_mfma_f32_16x16x32_bf16 v[92:95], v[210:213], v[170:173], v[92:95]
	v_mfma_f32_16x16x32_bf16 v[80:83], v[202:205], v[178:181], v[80:83]
	v_mfma_f32_16x16x32_bf16 v[76:79], v[210:213], v[178:181], v[76:79]
	v_mfma_f32_16x16x32_bf16 v[72:75], v[202:205], v[186:189], v[72:75]
	v_mfma_f32_16x16x32_bf16 v[68:71], v[210:213], v[186:189], v[68:71]
	v_mfma_f32_16x16x32_bf16 v[112:115], v[206:209], v[166:169], v[112:115]
	v_mfma_f32_16x16x32_bf16 v[108:111], v[214:217], v[166:169], v[108:111]
	v_mfma_f32_16x16x32_bf16 v[96:99], v[206:209], v[174:177], v[96:99]
	v_mfma_f32_16x16x32_bf16 v[92:95], v[214:217], v[174:177], v[92:95]
	v_mfma_f32_16x16x32_bf16 v[80:83], v[206:209], v[182:185], v[80:83]
	v_mfma_f32_16x16x32_bf16 v[76:79], v[214:217], v[182:185], v[76:79]
	v_mfma_f32_16x16x32_bf16 v[72:75], v[206:209], v[190:193], v[72:75]
	v_mfma_f32_16x16x32_bf16 v[68:71], v[214:217], v[190:193], v[68:71]
	s_mov_b32 m0, s52
	s_barrier
	ds_read_b128 v[162:165], v144 offset:16384
	ds_read_b128 v[166:169], v144 offset:17408
	ds_read_b128 v[170:173], v144 offset:18432
	ds_read_b128 v[174:177], v144 offset:19456
	ds_read_b128 v[178:181], v144 offset:20480
	ds_read_b128 v[182:185], v144 offset:21504
	ds_read_b128 v[186:189], v144 offset:22528
	global_load_lds_dwordx4 v0, s[48:49]
	s_mov_b32 m0, s53
	ds_read_b128 v[190:193], v144 offset:23552
	global_load_lds_dwordx4 v134, s[48:49]
	s_barrier
	s_waitcnt lgkmcnt(0)
	v_mfma_f32_16x16x32_bf16 v[64:67], v[146:149], v[162:165], v[64:67]
	v_mfma_f32_16x16x32_bf16 v[60:63], v[154:157], v[162:165], v[60:63]
	v_mfma_f32_16x16x32_bf16 v[56:59], v[146:149], v[170:173], v[56:59]
	v_mfma_f32_16x16x32_bf16 v[52:55], v[154:157], v[170:173], v[52:55]
	v_mfma_f32_16x16x32_bf16 v[40:43], v[146:149], v[178:181], v[40:43]
	v_mfma_f32_16x16x32_bf16 v[36:39], v[154:157], v[178:181], v[36:39]
	v_mfma_f32_16x16x32_bf16 v[24:27], v[146:149], v[186:189], v[24:27]
	v_mfma_f32_16x16x32_bf16 v[16:19], v[154:157], v[186:189], v[16:19]
	v_mfma_f32_16x16x32_bf16 v[64:67], v[150:153], v[166:169], v[64:67]
	v_mfma_f32_16x16x32_bf16 v[60:63], v[158:161], v[166:169], v[60:63]
	v_mfma_f32_16x16x32_bf16 v[56:59], v[150:153], v[174:177], v[56:59]
	v_mfma_f32_16x16x32_bf16 v[52:55], v[158:161], v[174:177], v[52:55]
	v_mfma_f32_16x16x32_bf16 v[40:43], v[150:153], v[182:185], v[40:43]
	v_mfma_f32_16x16x32_bf16 v[36:39], v[158:161], v[182:185], v[36:39]
	v_mfma_f32_16x16x32_bf16 v[24:27], v[150:153], v[190:193], v[24:27]
	v_mfma_f32_16x16x32_bf16 v[16:19], v[158:161], v[190:193], v[16:19]
	s_barrier
	s_add_i32 s23, s26, s37
	s_mov_b32 m0, s23
	s_add_u32 s24, s46, 0xb0000
	s_addc_u32 s25, s47, 0
	global_load_lds_dwordx4 v132, s[24:25]
	s_add_i32 m0, s23, 0x2000
	s_waitcnt vmcnt(5)
	global_load_lds_dwordx4 v136, s[24:25]
	s_barrier
	v_mfma_f32_16x16x32_bf16 v[48:51], v[202:205], v[162:165], v[48:51]
	v_mfma_f32_16x16x32_bf16 v[44:47], v[210:213], v[162:165], v[44:47]
	v_mfma_f32_16x16x32_bf16 v[32:35], v[202:205], v[170:173], v[32:35]
	v_mfma_f32_16x16x32_bf16 v[28:31], v[210:213], v[170:173], v[28:31]
	v_mfma_f32_16x16x32_bf16 v[20:23], v[202:205], v[178:181], v[20:23]
	v_mfma_f32_16x16x32_bf16 v[12:15], v[210:213], v[178:181], v[12:15]
	v_mfma_f32_16x16x32_bf16 v[8:11], v[202:205], v[186:189], v[8:11]
	v_mfma_f32_16x16x32_bf16 v[4:7], v[210:213], v[186:189], v[4:7]
	v_mfma_f32_16x16x32_bf16 v[48:51], v[206:209], v[166:169], v[48:51]
	v_mfma_f32_16x16x32_bf16 v[44:47], v[214:217], v[166:169], v[44:47]
	v_mfma_f32_16x16x32_bf16 v[32:35], v[206:209], v[174:177], v[32:35]
	v_mfma_f32_16x16x32_bf16 v[28:31], v[214:217], v[174:177], v[28:31]
	v_mfma_f32_16x16x32_bf16 v[20:23], v[206:209], v[182:185], v[20:23]
	v_mfma_f32_16x16x32_bf16 v[12:15], v[214:217], v[182:185], v[12:15]
	v_mfma_f32_16x16x32_bf16 v[8:11], v[206:209], v[190:193], v[8:11]
	v_mfma_f32_16x16x32_bf16 v[4:7], v[214:217], v[190:193], v[4:7]
	s_add_i32 s23, 0, 0x18000
	s_barrier
	ds_read_b128 v[146:149], v194 offset:32768
	ds_read_b128 v[150:153], v194 offset:33792
	ds_read_b128 v[154:157], v194 offset:34816
	ds_read_b128 v[158:161], v194 offset:35840
	s_add_u32 s24, s48, 0xb0000
	s_addc_u32 s25, s49, 0
	s_mov_b32 m0, s54
	ds_read_b128 v[162:165], v144 offset:32768
	ds_read_b128 v[166:169], v144 offset:33792
	ds_read_b128 v[170:173], v144 offset:34816
	ds_read_b128 v[174:177], v144 offset:35840
	ds_read_b128 v[178:181], v144 offset:36864
	ds_read_b128 v[182:185], v144 offset:37888
	ds_read_b128 v[186:189], v144 offset:38912
	global_load_lds_dwordx4 v0, s[24:25]
	s_mov_b32 m0, s55
	ds_read_b128 v[190:193], v144 offset:39936
	global_load_lds_dwordx4 v134, s[24:25]
	s_waitcnt lgkmcnt(8)
	s_barrier
	s_waitcnt lgkmcnt(0)
	v_mfma_f32_16x16x32_bf16 v[128:131], v[146:149], v[162:165], v[128:131]
	v_mfma_f32_16x16x32_bf16 v[124:127], v[154:157], v[162:165], v[124:127]
	v_mfma_f32_16x16x32_bf16 v[120:123], v[146:149], v[170:173], v[120:123]
	v_mfma_f32_16x16x32_bf16 v[116:119], v[154:157], v[170:173], v[116:119]
	v_mfma_f32_16x16x32_bf16 v[104:107], v[146:149], v[178:181], v[104:107]
	v_mfma_f32_16x16x32_bf16 v[100:103], v[154:157], v[178:181], v[100:103]
	v_mfma_f32_16x16x32_bf16 v[88:91], v[146:149], v[186:189], v[88:91]
	v_mfma_f32_16x16x32_bf16 v[84:87], v[154:157], v[186:189], v[84:87]
	v_mfma_f32_16x16x32_bf16 v[128:131], v[150:153], v[166:169], v[128:131]
	v_mfma_f32_16x16x32_bf16 v[124:127], v[158:161], v[166:169], v[124:127]
	v_mfma_f32_16x16x32_bf16 v[120:123], v[150:153], v[174:177], v[120:123]
	v_mfma_f32_16x16x32_bf16 v[116:119], v[158:161], v[174:177], v[116:119]
	v_mfma_f32_16x16x32_bf16 v[104:107], v[150:153], v[182:185], v[104:107]
	v_mfma_f32_16x16x32_bf16 v[100:103], v[158:161], v[182:185], v[100:103]
	v_mfma_f32_16x16x32_bf16 v[88:91], v[150:153], v[190:193], v[88:91]
	v_mfma_f32_16x16x32_bf16 v[84:87], v[158:161], v[190:193], v[84:87]
	s_barrier
	s_add_i32 s26, 0, 0x1c000
	s_add_i32 s23, s23, s37
	s_mov_b32 m0, s23
	ds_read_b128 v[202:205], v194 offset:49152
	ds_read_b128 v[206:209], v194 offset:50176
	ds_read_b128 v[210:213], v194 offset:51200
	s_add_u32 s98, s46, 0x80
	s_addc_u32 s99, s47, 0
	global_load_lds_dwordx4 v132, s[98:99]
	s_add_i32 m0, s23, 0x2000
	ds_read_b128 v[214:217], v194 offset:52224
	global_load_lds_dwordx4 v136, s[98:99]
	s_barrier
	s_waitcnt lgkmcnt(0)
	v_mfma_f32_16x16x32_bf16 v[112:115], v[202:205], v[162:165], v[112:115]
	v_mfma_f32_16x16x32_bf16 v[108:111], v[210:213], v[162:165], v[108:111]
	v_mfma_f32_16x16x32_bf16 v[96:99], v[202:205], v[170:173], v[96:99]
	v_mfma_f32_16x16x32_bf16 v[92:95], v[210:213], v[170:173], v[92:95]
	v_mfma_f32_16x16x32_bf16 v[80:83], v[202:205], v[178:181], v[80:83]
	v_mfma_f32_16x16x32_bf16 v[76:79], v[210:213], v[178:181], v[76:79]
	v_mfma_f32_16x16x32_bf16 v[72:75], v[202:205], v[186:189], v[72:75]
	v_mfma_f32_16x16x32_bf16 v[68:71], v[210:213], v[186:189], v[68:71]
	v_mfma_f32_16x16x32_bf16 v[112:115], v[206:209], v[166:169], v[112:115]
	v_mfma_f32_16x16x32_bf16 v[108:111], v[214:217], v[166:169], v[108:111]
	v_mfma_f32_16x16x32_bf16 v[96:99], v[206:209], v[174:177], v[96:99]
	v_mfma_f32_16x16x32_bf16 v[92:95], v[214:217], v[174:177], v[92:95]
	v_mfma_f32_16x16x32_bf16 v[80:83], v[206:209], v[182:185], v[80:83]
	v_mfma_f32_16x16x32_bf16 v[76:79], v[214:217], v[182:185], v[76:79]
	v_mfma_f32_16x16x32_bf16 v[72:75], v[206:209], v[190:193], v[72:75]
	v_mfma_f32_16x16x32_bf16 v[68:71], v[214:217], v[190:193], v[68:71]
	s_mov_b32 m0, s56
	s_barrier
	ds_read_b128 v[162:165], v144 offset:49152
	ds_read_b128 v[166:169], v144 offset:50176
	ds_read_b128 v[170:173], v144 offset:51200
	ds_read_b128 v[174:177], v144 offset:52224
	ds_read_b128 v[178:181], v144 offset:53248
	ds_read_b128 v[182:185], v144 offset:54272
	ds_read_b128 v[186:189], v144 offset:55296
	s_add_u32 s98, s48, 0x80
	s_addc_u32 s99, s49, 0
	global_load_lds_dwordx4 v0, s[98:99]
	s_mov_b32 m0, s57
	ds_read_b128 v[190:193], v144 offset:56320
	global_load_lds_dwordx4 v134, s[98:99]
	s_barrier
	s_waitcnt lgkmcnt(0)
	v_mfma_f32_16x16x32_bf16 v[64:67], v[146:149], v[162:165], v[64:67]
	v_mfma_f32_16x16x32_bf16 v[60:63], v[154:157], v[162:165], v[60:63]
	v_mfma_f32_16x16x32_bf16 v[56:59], v[146:149], v[170:173], v[56:59]
	v_mfma_f32_16x16x32_bf16 v[52:55], v[154:157], v[170:173], v[52:55]
	v_mfma_f32_16x16x32_bf16 v[40:43], v[146:149], v[178:181], v[40:43]
	v_mfma_f32_16x16x32_bf16 v[36:39], v[154:157], v[178:181], v[36:39]
	v_mfma_f32_16x16x32_bf16 v[24:27], v[146:149], v[186:189], v[24:27]
	v_mfma_f32_16x16x32_bf16 v[16:19], v[154:157], v[186:189], v[16:19]
	v_mfma_f32_16x16x32_bf16 v[64:67], v[150:153], v[166:169], v[64:67]
	v_mfma_f32_16x16x32_bf16 v[60:63], v[158:161], v[166:169], v[60:63]
	v_mfma_f32_16x16x32_bf16 v[56:59], v[150:153], v[174:177], v[56:59]
	v_mfma_f32_16x16x32_bf16 v[52:55], v[158:161], v[174:177], v[52:55]
	v_mfma_f32_16x16x32_bf16 v[40:43], v[150:153], v[182:185], v[40:43]
	v_mfma_f32_16x16x32_bf16 v[36:39], v[158:161], v[182:185], v[36:39]
	v_mfma_f32_16x16x32_bf16 v[24:27], v[150:153], v[190:193], v[24:27]
	v_mfma_f32_16x16x32_bf16 v[16:19], v[158:161], v[190:193], v[16:19]
	s_barrier
	s_add_i32 s23, s26, s37
	s_mov_b32 m0, s23
	s_add_u32 s24, s46, 0xb0080
	s_addc_u32 s25, s47, 0
	global_load_lds_dwordx4 v132, s[24:25]
	s_add_i32 m0, s23, 0x2000
	s_waitcnt vmcnt(5)
	global_load_lds_dwordx4 v136, s[24:25]
	s_barrier
	v_mfma_f32_16x16x32_bf16 v[48:51], v[202:205], v[162:165], v[48:51]
	v_mfma_f32_16x16x32_bf16 v[44:47], v[210:213], v[162:165], v[44:47]
	v_mfma_f32_16x16x32_bf16 v[32:35], v[202:205], v[170:173], v[32:35]
	v_mfma_f32_16x16x32_bf16 v[28:31], v[210:213], v[170:173], v[28:31]
	v_mfma_f32_16x16x32_bf16 v[20:23], v[202:205], v[178:181], v[20:23]
	v_mfma_f32_16x16x32_bf16 v[12:15], v[210:213], v[178:181], v[12:15]
	v_mfma_f32_16x16x32_bf16 v[8:11], v[202:205], v[186:189], v[8:11]
	v_mfma_f32_16x16x32_bf16 v[4:7], v[210:213], v[186:189], v[4:7]
	v_mfma_f32_16x16x32_bf16 v[48:51], v[206:209], v[166:169], v[48:51]
	v_mfma_f32_16x16x32_bf16 v[44:47], v[214:217], v[166:169], v[44:47]
	v_mfma_f32_16x16x32_bf16 v[32:35], v[206:209], v[174:177], v[32:35]
	v_mfma_f32_16x16x32_bf16 v[28:31], v[214:217], v[174:177], v[28:31]
	v_mfma_f32_16x16x32_bf16 v[20:23], v[206:209], v[182:185], v[20:23]
	v_mfma_f32_16x16x32_bf16 v[12:15], v[214:217], v[182:185], v[12:15]
	v_mfma_f32_16x16x32_bf16 v[8:11], v[206:209], v[190:193], v[8:11]
	v_mfma_f32_16x16x32_bf16 v[4:7], v[214:217], v[190:193], v[4:7]
	s_add_i32 s22, s22, 2
	s_add_u32 s20, s20, 0x100
	s_addc_u32 s21, s21, 0
	s_cmp_gt_u32 s22, 41
	s_mov_b64 s[42:43], s[44:45]
	s_barrier
	s_cbranch_scc0 .LBB0_58
	v_lshl_add_u32 v146, s61, 8, v142
	v_cvt_pk_bf16_f32 v72, v72, v73
	v_cvt_pk_bf16_f32 v73, v74, v75
	v_cvt_pk_bf16_f32 v74, v68, v69
	v_add_u32_e32 v68, 0x80, v146
	s_lshl_b32 s20, s62, 8
	v_ashrrev_i32_e32 v147, 31, v146
	v_readlane_b32 s22, v252, 10
	v_cvt_pk_bf16_f32 v112, v112, v113
	v_cvt_pk_bf16_f32 v113, v114, v115
	v_cvt_pk_bf16_f32 v114, v108, v109
	v_or_b32_e32 v108, 16, v146
	v_ashrrev_i32_e32 v69, 31, v68
	v_cvt_pk_bf16_f32 v48, v48, v49
	v_cvt_pk_bf16_f32 v49, v50, v51
	v_cvt_pk_bf16_f32 v50, v44, v45
	v_add_u32_e32 v44, 0x90, v146
	s_ashr_i32 s21, s20, 31
	v_lshlrev_b64 v[148:149], 11, v[146:147]
	v_readlane_b32 s23, v252, 11
	v_ashrrev_i32_e32 v109, 31, v108
	v_cvt_pk_bf16_f32 v96, v96, v97
	v_cvt_pk_bf16_f32 v97, v98, v99
	v_cvt_pk_bf16_f32 v98, v92, v93
	v_or_b32_e32 v92, 32, v146
	v_lshlrev_b64 v[68:69], 11, v[68:69]
	v_ashrrev_i32_e32 v45, 31, v44
	v_cvt_pk_bf16_f32 v32, v32, v33
	v_cvt_pk_bf16_f32 v33, v34, v35
	v_cvt_pk_bf16_f32 v34, v28, v29
	v_add_u32_e32 v28, 0xa0, v146
	v_lshl_add_u64 v[148:149], s[22:23], 0, v[148:149]
	s_lshl_b64 s[42:43], s[20:21], 1
	v_lshlrev_b64 v[108:109], 11, v[108:109]
	v_ashrrev_i32_e32 v93, 31, v92
	v_cvt_pk_bf16_f32 v80, v80, v81
	v_cvt_pk_bf16_f32 v81, v82, v83
	v_cvt_pk_bf16_f32 v82, v76, v77
	v_or_b32_e32 v76, 48, v146
	v_lshl_add_u64 v[68:69], s[22:23], 0, v[68:69]
	v_lshlrev_b64 v[44:45], 11, v[44:45]
	v_ashrrev_i32_e32 v29, 31, v28
	v_cvt_pk_bf16_f32 v20, v20, v21
	v_cvt_pk_bf16_f32 v21, v22, v23
	v_cvt_pk_bf16_f32 v22, v12, v13
	v_add_u32_e32 v12, 0xb0, v146
	v_lshl_add_u64 v[148:149], v[148:149], 0, s[42:43]
	v_lshl_add_u64 v[108:109], s[22:23], 0, v[108:109]
	v_lshlrev_b64 v[92:93], 11, v[92:93]
	v_ashrrev_i32_e32 v77, 31, v76
	v_lshl_add_u64 v[68:69], v[68:69], 0, s[42:43]
	v_lshl_add_u64 v[44:45], s[22:23], 0, v[44:45]
	v_lshlrev_b64 v[28:29], 11, v[28:29]
	v_ashrrev_i32_e32 v13, 31, v12
	v_lshl_add_u64 v[148:149], v[148:149], 0, s[72:73]
	v_lshl_add_u64 v[108:109], v[108:109], 0, s[42:43]
	v_lshl_add_u64 v[92:93], s[22:23], 0, v[92:93]
	v_lshlrev_b64 v[76:77], 11, v[76:77]
	v_lshl_add_u64 v[68:69], v[68:69], 0, s[72:73]
	v_lshl_add_u64 v[44:45], v[44:45], 0, s[42:43]
	v_lshl_add_u64 v[28:29], s[22:23], 0, v[28:29]
	v_lshlrev_b64 v[12:13], 11, v[12:13]
	v_lshl_add_u64 v[148:149], v[148:149], 0, v[2:3]
	v_cvt_pk_bf16_f32 v115, v110, v111
	v_lshl_add_u64 v[108:109], v[108:109], 0, s[72:73]
	v_lshl_add_u64 v[92:93], v[92:93], 0, s[42:43]
	v_lshl_add_u64 v[76:77], s[22:23], 0, v[76:77]
	v_lshl_add_u64 v[68:69], v[68:69], 0, v[2:3]
	v_cvt_pk_bf16_f32 v51, v46, v47
	v_lshl_add_u64 v[44:45], v[44:45], 0, s[72:73]
	v_lshl_add_u64 v[28:29], v[28:29], 0, s[42:43]
	v_lshl_add_u64 v[12:13], s[22:23], 0, v[12:13]
	global_store_dwordx4 v[148:149], v[112:115], off offset:256
	v_cvt_pk_bf16_f32 v99, v94, v95
	v_lshl_add_u64 v[92:93], v[92:93], 0, s[72:73]
	v_lshl_add_u64 v[112:113], v[108:109], 0, v[2:3]
	v_lshl_add_u64 v[76:77], v[76:77], 0, s[42:43]
	global_store_dwordx4 v[68:69], v[48:51], off offset:256
	v_cvt_pk_bf16_f32 v35, v30, v31
	v_lshl_add_u64 v[28:29], v[28:29], 0, s[72:73]
	v_lshl_add_u64 v[48:49], v[44:45], 0, v[2:3]
	v_lshl_add_u64 v[12:13], v[12:13], 0, s[42:43]
	global_store_dwordx4 v[112:113], v[96:99], off offset:256
	v_cvt_pk_bf16_f32 v83, v78, v79
	v_lshl_add_u64 v[76:77], v[76:77], 0, s[72:73]
	v_lshl_add_u64 v[96:97], v[92:93], 0, v[2:3]
	global_store_dwordx4 v[48:49], v[32:35], off offset:256
	v_cvt_pk_bf16_f32 v23, v14, v15
	v_lshl_add_u64 v[12:13], v[12:13], 0, s[72:73]
	v_lshl_add_u64 v[32:33], v[28:29], 0, v[2:3]
	v_cvt_pk_bf16_f32 v128, v128, v129
	v_cvt_pk_bf16_f32 v129, v130, v131
	v_cvt_pk_bf16_f32 v130, v124, v125
	v_cvt_pk_bf16_f32 v131, v126, v127
	v_cvt_pk_bf16_f32 v108, v120, v121
	v_cvt_pk_bf16_f32 v109, v122, v123
	v_cvt_pk_bf16_f32 v110, v116, v117
	v_cvt_pk_bf16_f32 v111, v118, v119
	v_cvt_pk_bf16_f32 v92, v104, v105
	v_cvt_pk_bf16_f32 v93, v106, v107
	v_cvt_pk_bf16_f32 v94, v100, v101
	v_cvt_pk_bf16_f32 v95, v102, v103
	global_store_dwordx4 v[96:97], v[80:83], off offset:256
	v_cvt_pk_bf16_f32 v78, v84, v85
	v_cvt_pk_bf16_f32 v79, v86, v87
	v_lshl_add_u64 v[80:81], v[76:77], 0, v[2:3]
	v_cvt_pk_bf16_f32 v76, v88, v89
	v_cvt_pk_bf16_f32 v77, v90, v91
	v_cvt_pk_bf16_f32 v75, v70, v71
	v_cvt_pk_bf16_f32 v64, v64, v65
	v_cvt_pk_bf16_f32 v65, v66, v67
	v_cvt_pk_bf16_f32 v66, v60, v61
	v_cvt_pk_bf16_f32 v67, v62, v63
	v_cvt_pk_bf16_f32 v44, v56, v57
	v_cvt_pk_bf16_f32 v45, v58, v59
	v_cvt_pk_bf16_f32 v46, v52, v53
	v_cvt_pk_bf16_f32 v47, v54, v55
	v_cvt_pk_bf16_f32 v28, v40, v41
	v_cvt_pk_bf16_f32 v29, v42, v43
	v_cvt_pk_bf16_f32 v30, v36, v37
	v_cvt_pk_bf16_f32 v31, v38, v39
	global_store_dwordx4 v[32:33], v[20:23], off offset:256
	v_cvt_pk_bf16_f32 v14, v16, v17
	v_cvt_pk_bf16_f32 v15, v18, v19
	v_lshl_add_u64 v[20:21], v[12:13], 0, v[2:3]
	v_cvt_pk_bf16_f32 v12, v24, v25
	v_cvt_pk_bf16_f32 v13, v26, v27
	v_cvt_pk_bf16_f32 v8, v8, v9
	v_cvt_pk_bf16_f32 v9, v10, v11
	v_cvt_pk_bf16_f32 v10, v4, v5
	v_cvt_pk_bf16_f32 v11, v6, v7
	s_and_b64 vcc, exec, s[38:39]
	s_mov_b32 s62, s59
	s_mov_b32 s61, s60
	s_mov_b64 s[44:45], s[40:41]
	s_mov_b64 s[42:43], s[0:1]
	global_store_dwordx4 v[148:149], v[128:131], off
	global_store_dwordx4 v[112:113], v[108:111], off
	global_store_dwordx4 v[96:97], v[92:95], off
	global_store_dwordx4 v[80:81], v[76:79], off
	global_store_dwordx4 v[80:81], v[72:75], off offset:256
	global_store_dwordx4 v[68:69], v[64:67], off
	global_store_dwordx4 v[48:49], v[44:47], off
	global_store_dwordx4 v[32:33], v[28:31], off
	global_store_dwordx4 v[20:21], v[12:15], off
	global_store_dwordx4 v[20:21], v[8:11], off offset:256
	s_cbranch_vccz .LBB0_51
	s_waitcnt vmcnt(0)
	s_cmpk_gt_u32 s36, 0xff
	s_cbranch_scc1 .LBB0_62
	s_barrier

.LBB0_79:
	s_add_u32 s52, s52, 0x40080
	s_addc_u32 s53, s53, 0
	s_add_u32 s1, s54, 0x100
	v_mov_b32_e32 v4, 0
	s_addc_u32 s20, s55, 0
	s_mov_b32 s21, -2
	v_mov_b32_e32 v5, v4
	v_mov_b32_e32 v6, v4
	v_mov_b32_e32 v7, v4
	v_mov_b32_e32 v8, v4
	v_mov_b32_e32 v9, v4
	v_mov_b32_e32 v10, v4
	v_mov_b32_e32 v11, v4
	v_mov_b32_e32 v20, v4
	v_mov_b32_e32 v21, v4
	v_mov_b32_e32 v22, v4
	v_mov_b32_e32 v23, v4
	v_mov_b32_e32 v28, v4
	v_mov_b32_e32 v29, v4
	v_mov_b32_e32 v30, v4
	v_mov_b32_e32 v31, v4
	v_mov_b32_e32 v36, v4
	v_mov_b32_e32 v37, v4
	v_mov_b32_e32 v38, v4
	v_mov_b32_e32 v39, v4
	v_mov_b32_e32 v44, v4
	v_mov_b32_e32 v45, v4
	v_mov_b32_e32 v46, v4
	v_mov_b32_e32 v47, v4
	v_mov_b32_e32 v68, v4
	v_mov_b32_e32 v69, v4
	v_mov_b32_e32 v70, v4
	v_mov_b32_e32 v71, v4
	v_mov_b32_e32 v108, v4
	v_mov_b32_e32 v109, v4
	v_mov_b32_e32 v110, v4
	v_mov_b32_e32 v111, v4
	v_mov_b32_e32 v12, v4
	v_mov_b32_e32 v13, v4
	v_mov_b32_e32 v14, v4
	v_mov_b32_e32 v15, v4
	v_mov_b32_e32 v16, v4
	v_mov_b32_e32 v17, v4
	v_mov_b32_e32 v18, v4
	v_mov_b32_e32 v19, v4
	v_mov_b32_e32 v24, v4
	v_mov_b32_e32 v25, v4
	v_mov_b32_e32 v26, v4
	v_mov_b32_e32 v27, v4
	v_mov_b32_e32 v32, v4
	v_mov_b32_e32 v33, v4
	v_mov_b32_e32 v34, v4
	v_mov_b32_e32 v35, v4
	v_mov_b32_e32 v40, v4
	v_mov_b32_e32 v41, v4
	v_mov_b32_e32 v42, v4
	v_mov_b32_e32 v43, v4
	v_mov_b32_e32 v48, v4
	v_mov_b32_e32 v49, v4
	v_mov_b32_e32 v50, v4
	v_mov_b32_e32 v51, v4
	v_mov_b32_e32 v72, v4
	v_mov_b32_e32 v73, v4
	v_mov_b32_e32 v74, v4
	v_mov_b32_e32 v75, v4
	v_mov_b32_e32 v112, v4
	v_mov_b32_e32 v113, v4
	v_mov_b32_e32 v114, v4
	v_mov_b32_e32 v115, v4
	v_mov_b32_e32 v132, v4
	v_mov_b32_e32 v133, v4
	v_mov_b32_e32 v134, v4
	v_mov_b32_e32 v135, v4
	v_mov_b32_e32 v136, v4
	v_mov_b32_e32 v137, v4
	v_mov_b32_e32 v138, v4
	v_mov_b32_e32 v139, v4
	v_mov_b32_e32 v148, v4
	v_mov_b32_e32 v149, v4
	v_mov_b32_e32 v150, v4
	v_mov_b32_e32 v151, v4
	v_mov_b32_e32 v156, v4
	v_mov_b32_e32 v157, v4
	v_mov_b32_e32 v158, v4
	v_mov_b32_e32 v159, v4
	v_mov_b32_e32 v164, v4
	v_mov_b32_e32 v165, v4
	v_mov_b32_e32 v166, v4
	v_mov_b32_e32 v167, v4
	v_mov_b32_e32 v172, v4
	v_mov_b32_e32 v173, v4
	v_mov_b32_e32 v174, v4
	v_mov_b32_e32 v175, v4
	v_mov_b32_e32 v180, v4
	v_mov_b32_e32 v181, v4
	v_mov_b32_e32 v182, v4
	v_mov_b32_e32 v183, v4
	v_mov_b32_e32 v188, v4
	v_mov_b32_e32 v189, v4
	v_mov_b32_e32 v190, v4
	v_mov_b32_e32 v191, v4
	v_mov_b32_e32 v140, v4
	v_mov_b32_e32 v141, v4
	v_mov_b32_e32 v142, v4
	v_mov_b32_e32 v143, v4
	v_mov_b32_e32 v144, v4
	v_mov_b32_e32 v145, v4
	v_mov_b32_e32 v146, v4
	v_mov_b32_e32 v147, v4
	v_mov_b32_e32 v152, v4
	v_mov_b32_e32 v153, v4
	v_mov_b32_e32 v154, v4
	v_mov_b32_e32 v155, v4
	v_mov_b32_e32 v160, v4
	v_mov_b32_e32 v161, v4
	v_mov_b32_e32 v162, v4
	v_mov_b32_e32 v163, v4
	v_mov_b32_e32 v168, v4
	v_mov_b32_e32 v169, v4
	v_mov_b32_e32 v170, v4
	v_mov_b32_e32 v171, v4
	v_mov_b32_e32 v176, v4
	v_mov_b32_e32 v177, v4
	v_mov_b32_e32 v178, v4
	v_mov_b32_e32 v179, v4
	v_mov_b32_e32 v184, v4
	v_mov_b32_e32 v185, v4
	v_mov_b32_e32 v186, v4
	v_mov_b32_e32 v187, v4
	v_mov_b32_e32 v192, v4
	v_mov_b32_e32 v193, v4
	v_mov_b32_e32 v194, v4
	v_mov_b32_e32 v195, v4
	v_add_u32_e32 v198, 0x10000, v235
.LBB0_80:
	s_add_u32 s22, s52, 0xfffc0080
	s_addc_u32 s23, s53, -1
	s_add_i32 s24, 0, 0x10000
	ds_read_b128 v[52:55], v198
	ds_read_b128 v[56:59], v198 offset:1024
	ds_read_b128 v[60:63], v198 offset:2048
	ds_read_b128 v[64:67], v198 offset:3072
	s_cmp_eq_u32 s21, 12
	s_cselect_b32 s57, s47, s23
	s_cselect_b32 s56, s46, s22
	s_cselect_b32 s55, s49, s20
	s_cselect_b32 s54, s48, s1
	s_add_i32 m0, s62, 0xc000
	ds_read_b128 v[76:79], v239
	ds_read_b128 v[80:83], v239 offset:1024
	ds_read_b128 v[84:87], v239 offset:2048
	ds_read_b128 v[88:91], v239 offset:3072
	ds_read_b128 v[92:95], v239 offset:4096
	ds_read_b128 v[96:99], v239 offset:5120
	ds_read_b128 v[100:103], v239 offset:6144
	global_load_lds_dwordx4 v206, s[52:53]
	s_add_i32 m0, s62, 0xe000
	ds_read_b128 v[104:107], v239 offset:7168
	global_load_lds_dwordx4 v208, s[52:53]
	s_waitcnt lgkmcnt(8)
	s_barrier
	s_waitcnt lgkmcnt(0)
	v_mfma_f32_16x16x32_bf16 v[160:163], v[52:55], v[92:95], v[160:163]
	v_mfma_f32_16x16x32_bf16 v[152:155], v[60:63], v[92:95], v[152:155]
	v_mfma_f32_16x16x32_bf16 v[144:147], v[52:55], v[100:103], v[144:147]
	v_mfma_f32_16x16x32_bf16 v[140:143], v[60:63], v[100:103], v[140:143]
	v_mfma_f32_16x16x32_bf16 v[116:119], v[52:55], v[76:79], v[192:195]
	v_mfma_f32_16x16x32_bf16 v[120:123], v[60:63], v[76:79], v[184:187]
	v_mfma_f32_16x16x32_bf16 v[124:127], v[52:55], v[84:87], v[176:179]
	v_mfma_f32_16x16x32_bf16 v[128:131], v[60:63], v[84:87], v[168:171]
	v_mfma_f32_16x16x32_bf16 v[160:163], v[56:59], v[96:99], v[160:163]
	v_mfma_f32_16x16x32_bf16 v[152:155], v[64:67], v[96:99], v[152:155]
	v_mfma_f32_16x16x32_bf16 v[144:147], v[56:59], v[104:107], v[144:147]
	v_mfma_f32_16x16x32_bf16 v[140:143], v[64:67], v[104:107], v[140:143]
	v_mfma_f32_16x16x32_bf16 v[116:119], v[56:59], v[80:83], v[116:119]
	v_mfma_f32_16x16x32_bf16 v[120:123], v[64:67], v[80:83], v[120:123]
	v_mfma_f32_16x16x32_bf16 v[124:127], v[56:59], v[88:91], v[124:127]
	v_mfma_f32_16x16x32_bf16 v[128:131], v[64:67], v[88:91], v[128:131]
	s_barrier
	s_add_i32 s25, 0, 0x14000
	s_add_i32 s22, s24, s60
	s_mov_b32 m0, s22
	ds_read_b128 v[168:171], v198 offset:16384
	ds_read_b128 v[176:179], v198 offset:17408
	ds_read_b128 v[184:187], v198 offset:18432
	global_load_lds_dwordx4 v2, s[54:55]
	s_add_i32 m0, s22, 0x2000
	ds_read_b128 v[192:195], v198 offset:19456
	global_load_lds_dwordx4 v0, s[54:55]
	s_barrier
	s_waitcnt lgkmcnt(0)
	v_mfma_f32_16x16x32_bf16 v[188:191], v[168:171], v[76:79], v[188:191]
	v_mfma_f32_16x16x32_bf16 v[76:79], v[184:187], v[76:79], v[180:183]
	v_mfma_f32_16x16x32_bf16 v[188:191], v[176:179], v[80:83], v[188:191]
	v_mfma_f32_16x16x32_bf16 v[76:79], v[192:195], v[80:83], v[76:79]
	v_mfma_f32_16x16x32_bf16 v[80:83], v[168:171], v[84:87], v[172:175]
	v_mfma_f32_16x16x32_bf16 v[84:87], v[184:187], v[84:87], v[164:167]
	v_mfma_f32_16x16x32_bf16 v[80:83], v[176:179], v[88:91], v[80:83]
	v_mfma_f32_16x16x32_bf16 v[84:87], v[192:195], v[88:91], v[84:87]
	v_mfma_f32_16x16x32_bf16 v[88:91], v[168:171], v[92:95], v[156:159]
	v_mfma_f32_16x16x32_bf16 v[92:95], v[184:187], v[92:95], v[148:151]
	v_mfma_f32_16x16x32_bf16 v[88:91], v[176:179], v[96:99], v[88:91]
	v_mfma_f32_16x16x32_bf16 v[92:95], v[192:195], v[96:99], v[92:95]
	v_mfma_f32_16x16x32_bf16 v[96:99], v[168:171], v[100:103], v[136:139]
	v_mfma_f32_16x16x32_bf16 v[100:103], v[184:187], v[100:103], v[132:135]
	v_mfma_f32_16x16x32_bf16 v[96:99], v[176:179], v[104:107], v[96:99]
	v_mfma_f32_16x16x32_bf16 v[100:103], v[192:195], v[104:107], v[100:103]
	s_mov_b32 m0, s62
	s_barrier
	ds_read_b128 v[104:107], v239 offset:16384
	ds_read_b128 v[132:135], v239 offset:17408
	ds_read_b128 v[136:139], v239 offset:18432
	ds_read_b128 v[148:151], v239 offset:19456
	ds_read_b128 v[156:159], v239 offset:20480
	ds_read_b128 v[164:167], v239 offset:21504
	ds_read_b128 v[172:175], v239 offset:22528
	global_load_lds_dwordx4 v204, s[56:57]
	s_mov_b32 m0, s63
	ds_read_b128 v[180:183], v239 offset:23552
	global_load_lds_dwordx4 v202, s[56:57]
	s_barrier
	s_waitcnt lgkmcnt(0)
	v_mfma_f32_16x16x32_bf16 v[112:115], v[52:55], v[104:107], v[112:115]
	v_mfma_f32_16x16x32_bf16 v[72:75], v[60:63], v[104:107], v[72:75]
	v_mfma_f32_16x16x32_bf16 v[48:51], v[52:55], v[136:139], v[48:51]
	v_mfma_f32_16x16x32_bf16 v[40:43], v[60:63], v[136:139], v[40:43]
	v_mfma_f32_16x16x32_bf16 v[32:35], v[52:55], v[156:159], v[32:35]
	v_mfma_f32_16x16x32_bf16 v[24:27], v[60:63], v[156:159], v[24:27]
	v_mfma_f32_16x16x32_bf16 v[16:19], v[52:55], v[172:175], v[16:19]
	v_mfma_f32_16x16x32_bf16 v[12:15], v[60:63], v[172:175], v[12:15]
	v_mfma_f32_16x16x32_bf16 v[112:115], v[56:59], v[132:135], v[112:115]
	v_mfma_f32_16x16x32_bf16 v[72:75], v[64:67], v[132:135], v[72:75]
	v_mfma_f32_16x16x32_bf16 v[48:51], v[56:59], v[148:151], v[48:51]
	v_mfma_f32_16x16x32_bf16 v[40:43], v[64:67], v[148:151], v[40:43]
	v_mfma_f32_16x16x32_bf16 v[32:35], v[56:59], v[164:167], v[32:35]
	v_mfma_f32_16x16x32_bf16 v[24:27], v[64:67], v[164:167], v[24:27]
	v_mfma_f32_16x16x32_bf16 v[16:19], v[56:59], v[180:183], v[16:19]
	v_mfma_f32_16x16x32_bf16 v[12:15], v[64:67], v[180:183], v[12:15]
	s_barrier
	s_add_i32 s24, s25, s60
	s_mov_b32 m0, s24
	s_add_u32 s22, s54, 0x40000
	s_addc_u32 s23, s55, 0
	global_load_lds_dwordx4 v2, s[22:23]
	s_add_i32 m0, s24, 0x2000
	s_waitcnt vmcnt(5)
	global_load_lds_dwordx4 v0, s[22:23]
	s_barrier
	v_mfma_f32_16x16x32_bf16 v[44:47], v[168:171], v[136:139], v[44:47]
	v_mfma_f32_16x16x32_bf16 v[36:39], v[184:187], v[136:139], v[36:39]
	v_mfma_f32_16x16x32_bf16 v[28:31], v[168:171], v[156:159], v[28:31]
	v_mfma_f32_16x16x32_bf16 v[20:23], v[184:187], v[156:159], v[20:23]
	v_mfma_f32_16x16x32_bf16 v[8:11], v[168:171], v[172:175], v[8:11]
	v_mfma_f32_16x16x32_bf16 v[4:7], v[184:187], v[172:175], v[4:7]
	v_mfma_f32_16x16x32_bf16 v[52:55], v[168:171], v[104:107], v[108:111]
	v_mfma_f32_16x16x32_bf16 v[56:59], v[184:187], v[104:107], v[68:71]
	v_mfma_f32_16x16x32_bf16 v[44:47], v[176:179], v[148:151], v[44:47]
	v_mfma_f32_16x16x32_bf16 v[36:39], v[192:195], v[148:151], v[36:39]
	v_mfma_f32_16x16x32_bf16 v[28:31], v[176:179], v[164:167], v[28:31]
	v_mfma_f32_16x16x32_bf16 v[20:23], v[192:195], v[164:167], v[20:23]
	v_mfma_f32_16x16x32_bf16 v[8:11], v[176:179], v[180:183], v[8:11]
	v_mfma_f32_16x16x32_bf16 v[4:7], v[192:195], v[180:183], v[4:7]
	v_mfma_f32_16x16x32_bf16 v[52:55], v[176:179], v[132:135], v[52:55]
	v_mfma_f32_16x16x32_bf16 v[56:59], v[192:195], v[132:135], v[56:59]
	s_add_i32 s24, 0, 0x18000
	s_barrier
	ds_read_b128 v[60:63], v198 offset:32768
	ds_read_b128 v[64:67], v198 offset:33792
	ds_read_b128 v[68:71], v198 offset:34816
	ds_read_b128 v[104:107], v198 offset:35840
	s_add_u32 s22, s56, 0x40000
	s_addc_u32 s23, s57, 0
	s_mov_b32 m0, s64
	ds_read_b128 v[108:111], v239 offset:32768
	ds_read_b128 v[132:135], v239 offset:33792
	ds_read_b128 v[136:139], v239 offset:34816
	ds_read_b128 v[148:151], v239 offset:35840
	ds_read_b128 v[210:213], v239 offset:36864
	ds_read_b128 v[214:217], v239 offset:37888
	ds_read_b128 v[240:243], v239 offset:38912
	global_load_lds_dwordx4 v204, s[22:23]
	s_mov_b32 m0, s65
	ds_read_b128 v[244:247], v239 offset:39936
	global_load_lds_dwordx4 v202, s[22:23]
	s_waitcnt lgkmcnt(8)
	s_barrier
	s_waitcnt lgkmcnt(0)
	v_mfma_f32_16x16x32_bf16 v[116:119], v[60:63], v[108:111], v[116:119]
	v_mfma_f32_16x16x32_bf16 v[192:195], v[64:67], v[132:135], v[116:119]
	v_mfma_f32_16x16x32_bf16 v[116:119], v[68:71], v[108:111], v[120:123]
	v_mfma_f32_16x16x32_bf16 v[184:187], v[104:107], v[132:135], v[116:119]
	v_mfma_f32_16x16x32_bf16 v[116:119], v[60:63], v[136:139], v[124:127]
	v_mfma_f32_16x16x32_bf16 v[176:179], v[64:67], v[148:151], v[116:119]
	v_mfma_f32_16x16x32_bf16 v[116:119], v[68:71], v[136:139], v[128:131]
	v_mfma_f32_16x16x32_bf16 v[168:171], v[104:107], v[148:151], v[116:119]
	v_mfma_f32_16x16x32_bf16 v[116:119], v[60:63], v[210:213], v[160:163]
	v_mfma_f32_16x16x32_bf16 v[160:163], v[64:67], v[214:217], v[116:119]
	v_mfma_f32_16x16x32_bf16 v[116:119], v[68:71], v[210:213], v[152:155]
	v_mfma_f32_16x16x32_bf16 v[152:155], v[104:107], v[214:217], v[116:119]
	v_mfma_f32_16x16x32_bf16 v[116:119], v[60:63], v[240:243], v[144:147]
	v_mfma_f32_16x16x32_bf16 v[144:147], v[64:67], v[244:247], v[116:119]
	v_mfma_f32_16x16x32_bf16 v[116:119], v[68:71], v[240:243], v[140:143]
	v_mfma_f32_16x16x32_bf16 v[140:143], v[104:107], v[244:247], v[116:119]
	s_barrier
	s_add_i32 s25, 0, 0x1c000
	s_add_i32 s22, s24, s60
	s_mov_b32 m0, s22
	ds_read_b128 v[116:119], v198 offset:49152
	ds_read_b128 v[120:123], v198 offset:50176
	ds_read_b128 v[124:127], v198 offset:51200
	s_add_u32 s98, s54, 0x80
	s_addc_u32 s99, s55, 0
	global_load_lds_dwordx4 v2, s[98:99]
	s_add_i32 m0, s22, 0x2000
	ds_read_b128 v[128:131], v198 offset:52224
	global_load_lds_dwordx4 v0, s[98:99]
	s_barrier
	s_waitcnt lgkmcnt(0)
	v_mfma_f32_16x16x32_bf16 v[76:79], v[124:127], v[108:111], v[76:79]
	v_mfma_f32_16x16x32_bf16 v[180:183], v[128:131], v[132:135], v[76:79]
	v_mfma_f32_16x16x32_bf16 v[76:79], v[116:119], v[136:139], v[80:83]
	v_mfma_f32_16x16x32_bf16 v[172:175], v[120:123], v[148:151], v[76:79]
	v_mfma_f32_16x16x32_bf16 v[76:79], v[124:127], v[136:139], v[84:87]
	v_mfma_f32_16x16x32_bf16 v[156:159], v[116:119], v[108:111], v[188:191]
	v_mfma_f32_16x16x32_bf16 v[164:167], v[128:131], v[148:151], v[76:79]
	v_mfma_f32_16x16x32_bf16 v[76:79], v[116:119], v[210:213], v[88:91]
	v_mfma_f32_16x16x32_bf16 v[188:191], v[120:123], v[132:135], v[156:159]
	v_mfma_f32_16x16x32_bf16 v[156:159], v[120:123], v[214:217], v[76:79]
	v_mfma_f32_16x16x32_bf16 v[76:79], v[124:127], v[210:213], v[92:95]
	v_mfma_f32_16x16x32_bf16 v[148:151], v[128:131], v[214:217], v[76:79]
	v_mfma_f32_16x16x32_bf16 v[76:79], v[116:119], v[240:243], v[96:99]
	v_mfma_f32_16x16x32_bf16 v[136:139], v[120:123], v[244:247], v[76:79]
	v_mfma_f32_16x16x32_bf16 v[76:79], v[124:127], v[240:243], v[100:103]
	v_mfma_f32_16x16x32_bf16 v[132:135], v[128:131], v[244:247], v[76:79]
	s_mov_b32 m0, s72
	s_barrier
	s_nop 2
	ds_read_b128 v[76:79], v239 offset:49152
	ds_read_b128 v[80:83], v239 offset:50176
	ds_read_b128 v[84:87], v239 offset:51200
	ds_read_b128 v[88:91], v239 offset:52224
	ds_read_b128 v[92:95], v239 offset:53248
	ds_read_b128 v[96:99], v239 offset:54272
	ds_read_b128 v[100:103], v239 offset:55296
	s_add_u32 s98, s56, 0x80
	s_addc_u32 s99, s57, 0
	global_load_lds_dwordx4 v204, s[98:99]
	s_mov_b32 m0, s74
	ds_read_b128 v[210:213], v239 offset:56320
	global_load_lds_dwordx4 v202, s[98:99]
	s_barrier
	s_waitcnt lgkmcnt(0)
	v_mfma_f32_16x16x32_bf16 v[108:111], v[60:63], v[76:79], v[112:115]
	v_mfma_f32_16x16x32_bf16 v[72:75], v[68:71], v[76:79], v[72:75]
	v_mfma_f32_16x16x32_bf16 v[48:51], v[60:63], v[84:87], v[48:51]
	v_mfma_f32_16x16x32_bf16 v[40:43], v[68:71], v[84:87], v[40:43]
	v_mfma_f32_16x16x32_bf16 v[32:35], v[60:63], v[92:95], v[32:35]
	v_mfma_f32_16x16x32_bf16 v[24:27], v[68:71], v[92:95], v[24:27]
	v_mfma_f32_16x16x32_bf16 v[16:19], v[60:63], v[100:103], v[16:19]
	v_mfma_f32_16x16x32_bf16 v[12:15], v[68:71], v[100:103], v[12:15]
	v_mfma_f32_16x16x32_bf16 v[112:115], v[64:67], v[80:83], v[108:111]
	v_mfma_f32_16x16x32_bf16 v[72:75], v[104:107], v[80:83], v[72:75]
	v_mfma_f32_16x16x32_bf16 v[48:51], v[64:67], v[88:91], v[48:51]
	v_mfma_f32_16x16x32_bf16 v[40:43], v[104:107], v[88:91], v[40:43]
	v_mfma_f32_16x16x32_bf16 v[32:35], v[64:67], v[96:99], v[32:35]
	v_mfma_f32_16x16x32_bf16 v[24:27], v[104:107], v[96:99], v[24:27]
	v_mfma_f32_16x16x32_bf16 v[16:19], v[64:67], v[210:213], v[16:19]
	v_mfma_f32_16x16x32_bf16 v[12:15], v[104:107], v[210:213], v[12:15]
	s_barrier
	s_add_i32 s24, s25, s60
	s_mov_b32 m0, s24
	s_add_u32 s22, s54, 0x40080
	s_addc_u32 s23, s55, 0
	global_load_lds_dwordx4 v2, s[22:23]
	s_add_i32 m0, s24, 0x2000
	s_waitcnt vmcnt(5)
	global_load_lds_dwordx4 v0, s[22:23]
	s_barrier
	v_mfma_f32_16x16x32_bf16 v[52:55], v[116:119], v[76:79], v[52:55]
	v_mfma_f32_16x16x32_bf16 v[108:111], v[120:123], v[80:83], v[52:55]
	v_mfma_f32_16x16x32_bf16 v[52:55], v[124:127], v[76:79], v[56:59]
	v_mfma_f32_16x16x32_bf16 v[44:47], v[116:119], v[84:87], v[44:47]
	v_mfma_f32_16x16x32_bf16 v[36:39], v[124:127], v[84:87], v[36:39]
	v_mfma_f32_16x16x32_bf16 v[28:31], v[116:119], v[92:95], v[28:31]
	v_mfma_f32_16x16x32_bf16 v[20:23], v[124:127], v[92:95], v[20:23]
	v_mfma_f32_16x16x32_bf16 v[8:11], v[116:119], v[100:103], v[8:11]
	v_mfma_f32_16x16x32_bf16 v[4:7], v[124:127], v[100:103], v[4:7]
	v_mfma_f32_16x16x32_bf16 v[68:71], v[128:131], v[80:83], v[52:55]
	v_mfma_f32_16x16x32_bf16 v[44:47], v[120:123], v[88:91], v[44:47]
	v_mfma_f32_16x16x32_bf16 v[36:39], v[128:131], v[88:91], v[36:39]
	v_mfma_f32_16x16x32_bf16 v[28:31], v[120:123], v[96:99], v[28:31]
	v_mfma_f32_16x16x32_bf16 v[20:23], v[128:131], v[96:99], v[20:23]
	v_mfma_f32_16x16x32_bf16 v[8:11], v[120:123], v[210:213], v[8:11]
	v_mfma_f32_16x16x32_bf16 v[4:7], v[128:131], v[210:213], v[4:7]
	s_add_i32 s21, s21, 2
	s_add_u32 s52, s52, 0x100
	s_addc_u32 s53, s53, 0
	s_add_u32 s1, s1, 0x100
	s_addc_u32 s20, s20, 0
	s_cmp_gt_u32 s21, 13
	s_barrier
	s_cbranch_scc0 .LBB0_80
	v_lshl_or_b32 v210, s30, 7, v238
	s_lshl_b32 s1, s50, 8
	s_add_i32 s1, s1, s67
	v_lshlrev_b32_e32 v211, 2, v210
	v_lshlrev_b32_e32 v219, 1, v210
	v_readlane_b32 s2, v252, 4
	v_readlane_b32 s3, v252, 5
	v_readlane_b32 s20, v252, 20
	v_readlane_b32 s21, v252, 21
	v_readlane_b32 s22, v252, 2
	v_readlane_b32 s23, v252, 3
	v_readlane_b32 s24, v252, 22
	v_readlane_b32 s25, v252, 23
	v_readlane_b32 s26, v252, 24
	v_readlane_b32 s27, v252, 25
	v_readlane_b32 s50, v252, 26
	v_readlane_b32 s51, v252, 27
	v_readlane_b32 s56, v252, 28
	v_readlane_b32 s57, v252, 29
	v_readlane_b32 s98, v252, 30
	v_readlane_b32 s99, v252, 31
	v_lshl_add_u32 v240, v201, 2, s1
	v_mul_u32_u24_e32 v240, 0x1600, v240
	v_add_u32_e32 v240, v240, v219
	global_load_dwordx4 v[120:123], v211, s[2:3]
	global_load_dwordx4 v[80:83], v211, s[2:3] offset:16
	global_load_dwordx4 v[116:119], v211, s[20:21]
	global_load_dwordx4 v[76:79], v211, s[20:21] offset:16
	global_load_dwordx4 v[96:99], v211, s[22:23]
	global_load_dwordx4 v[56:59], v211, s[22:23] offset:16
	global_load_dwordx4 v[92:95], v211, s[24:25]
	global_load_dwordx4 v[52:55], v211, s[24:25] offset:16
	global_load_dwordx4 v[104:107], v211, s[26:27]
	global_load_dwordx4 v[64:67], v211, s[26:27] offset:16
	global_load_dwordx4 v[100:103], v211, s[50:51]
	global_load_dwordx4 v[60:63], v211, s[50:51] offset:16
	global_load_dwordx4 v[124:127], v211, s[56:57]
	global_load_dwordx4 v[84:87], v211, s[56:57] offset:16
	global_load_dwordx4 v[128:131], v211, s[98:99]
	global_load_dwordx4 v[88:91], v211, s[98:99] offset:16
	v_readlane_b32 s56, v254, 63
	v_readlane_b32 s57, v255, 0
	v_cmp_eq_u32_e64 s[2:3], 0, v201
	v_cmp_eq_u32_e64 s[26:27], 15, v201
	s_lshr_b32 s24, s1, 4
	s_mov_b64 exec, s[2:3]
	v_cvt_pk_bf16_f32 v212, v192, v193
	v_cvt_pk_bf16_f32 v213, v194, v195
	v_cvt_pk_bf16_f32 v214, v184, v185
	v_cvt_pk_bf16_f32 v215, v186, v187
	s_add_i32 s20, s24, 2
	s_mulk_i32 s20, 0x2c00
	s_add_u32 s22, s56, s20
	s_addc_u32 s23, s57, 0
	global_store_dwordx4 v219, v[212:215], s[22:23]
	v_cvt_pk_bf16_f32 v242, v188, v189
	v_cvt_pk_bf16_f32 v243, v190, v191
	v_cvt_pk_bf16_f32 v244, v180, v181
	v_cvt_pk_bf16_f32 v245, v182, v183
	s_add_u32 s22, s22, 0x1600
	s_addc_u32 s23, s23, 0
	global_store_dwordx4 v219, v[242:245], s[22:23]
	v_cvt_pk_bf16_f32 v246, v176, v177
	v_cvt_pk_bf16_f32 v247, v178, v179
	v_cvt_pk_bf16_f32 v248, v168, v169
	v_cvt_pk_bf16_f32 v249, v170, v171
	s_add_i32 s20, s24, 3
	s_mulk_i32 s20, 0x2c00
	s_add_u32 s22, s56, s20
	s_addc_u32 s23, s57, 0
	global_store_dwordx4 v219, v[246:249], s[22:23]
	v_cvt_pk_bf16_f32 v212, v172, v173
	v_cvt_pk_bf16_f32 v213, v174, v175
	v_cvt_pk_bf16_f32 v214, v164, v165
	v_cvt_pk_bf16_f32 v215, v166, v167
	s_add_u32 s22, s22, 0x1600
	s_addc_u32 s23, s23, 0
	global_store_dwordx4 v219, v[212:215], s[22:23]
	s_mov_b64 exec, s[26:27]
	v_cvt_pk_bf16_f32 v242, v160, v161
	v_cvt_pk_bf16_f32 v243, v162, v163
	v_cvt_pk_bf16_f32 v244, v152, v153
	v_cvt_pk_bf16_f32 v245, v154, v155
	s_add_i32 s20, s24, 0
	s_mulk_i32 s20, 0x2c00
	s_add_u32 s22, s56, s20
	s_addc_u32 s23, s57, 0
	global_store_dwordx4 v219, v[242:245], s[22:23]
	v_cvt_pk_bf16_f32 v246, v156, v157
	v_cvt_pk_bf16_f32 v247, v158, v159
	v_cvt_pk_bf16_f32 v248, v148, v149
	v_cvt_pk_bf16_f32 v249, v150, v151
	s_add_u32 s22, s22, 0x1600
	s_addc_u32 s23, s23, 0
	global_store_dwordx4 v219, v[246:249], s[22:23]
	v_cvt_pk_bf16_f32 v212, v144, v145
	v_cvt_pk_bf16_f32 v213, v146, v147
	v_cvt_pk_bf16_f32 v214, v140, v141
	v_cvt_pk_bf16_f32 v215, v142, v143
	s_add_i32 s20, s24, 1
	s_mulk_i32 s20, 0x2c00
	s_add_u32 s22, s56, s20
	s_addc_u32 s23, s57, 0
	global_store_dwordx4 v219, v[212:215], s[22:23]
	v_cvt_pk_bf16_f32 v242, v136, v137
	v_cvt_pk_bf16_f32 v243, v138, v139
	v_cvt_pk_bf16_f32 v244, v132, v133
	v_cvt_pk_bf16_f32 v245, v134, v135
	s_add_u32 s22, s22, 0x1600
	s_addc_u32 s23, s23, 0
	global_store_dwordx4 v219, v[242:245], s[22:23]
	s_mov_b64 exec, s[2:3]
	v_cvt_pk_bf16_f32 v246, v112, v113
	v_cvt_pk_bf16_f32 v247, v114, v115
	v_cvt_pk_bf16_f32 v248, v72, v73
	v_cvt_pk_bf16_f32 v249, v74, v75
	s_add_i32 s20, s24, 10
	s_mulk_i32 s20, 0x2c00
	s_add_u32 s22, s56, s20
	s_addc_u32 s23, s57, 0
	global_store_dwordx4 v219, v[246:249], s[22:23]
	v_cvt_pk_bf16_f32 v212, v108, v109
	v_cvt_pk_bf16_f32 v213, v110, v111
	v_cvt_pk_bf16_f32 v214, v68, v69
	v_cvt_pk_bf16_f32 v215, v70, v71
	s_add_u32 s22, s22, 0x1600
	s_addc_u32 s23, s23, 0
	global_store_dwordx4 v219, v[212:215], s[22:23]
	v_cvt_pk_bf16_f32 v242, v48, v49
	v_cvt_pk_bf16_f32 v243, v50, v51
	v_cvt_pk_bf16_f32 v244, v40, v41
	v_cvt_pk_bf16_f32 v245, v42, v43
	s_add_i32 s20, s24, 11
	s_mulk_i32 s20, 0x2c00
	s_add_u32 s22, s56, s20
	s_addc_u32 s23, s57, 0
	global_store_dwordx4 v219, v[242:245], s[22:23]
	v_cvt_pk_bf16_f32 v246, v44, v45
	v_cvt_pk_bf16_f32 v247, v46, v47
	v_cvt_pk_bf16_f32 v248, v36, v37
	v_cvt_pk_bf16_f32 v249, v38, v39
	s_add_u32 s22, s22, 0x1600
	s_addc_u32 s23, s23, 0
	global_store_dwordx4 v219, v[246:249], s[22:23]
	s_mov_b64 exec, s[26:27]
	v_cvt_pk_bf16_f32 v212, v32, v33
	v_cvt_pk_bf16_f32 v213, v34, v35
	v_cvt_pk_bf16_f32 v214, v24, v25
	v_cvt_pk_bf16_f32 v215, v26, v27
	s_add_i32 s20, s24, 8
	s_mulk_i32 s20, 0x2c00
	s_add_u32 s22, s56, s20
	s_addc_u32 s23, s57, 0
	global_store_dwordx4 v219, v[212:215], s[22:23]
	v_cvt_pk_bf16_f32 v242, v28, v29
	v_cvt_pk_bf16_f32 v243, v30, v31
	v_cvt_pk_bf16_f32 v244, v20, v21
	v_cvt_pk_bf16_f32 v245, v22, v23
	s_add_u32 s22, s22, 0x1600
	s_addc_u32 s23, s23, 0
	global_store_dwordx4 v219, v[242:245], s[22:23]
	v_cvt_pk_bf16_f32 v246, v16, v17
	v_cvt_pk_bf16_f32 v247, v18, v19
	v_cvt_pk_bf16_f32 v248, v12, v13
	v_cvt_pk_bf16_f32 v249, v14, v15
	s_add_i32 s20, s24, 9
	s_mulk_i32 s20, 0x2c00
	s_add_u32 s22, s56, s20
	s_addc_u32 s23, s57, 0
	global_store_dwordx4 v219, v[246:249], s[22:23]
	v_cvt_pk_bf16_f32 v212, v8, v9
	v_cvt_pk_bf16_f32 v213, v10, v11
	v_cvt_pk_bf16_f32 v214, v4, v5
	v_cvt_pk_bf16_f32 v215, v6, v7
	s_add_u32 s22, s22, 0x1600
	s_addc_u32 s23, s23, 0
	global_store_dwordx4 v219, v[212:215], s[22:23]
	s_mov_b64 exec, -1
	s_mov_b32 s50, 0xbfb8aa3b
	s_mov_b32 s51, 0xbfb8aa3b
	s_waitcnt vmcnt(16)
	v_mov_b32_dpp v198, v144 row_shr:1 row_mask:0xf bank_mask:0xf bound_ctrl:1
	v_mov_b32_dpp v199, v145 row_shr:1 row_mask:0xf bank_mask:0xf bound_ctrl:1
	v_mov_b32_dpp v214, v136 row_shr:1 row_mask:0xf bank_mask:0xf bound_ctrl:1
	v_mov_b32_dpp v215, v137 row_shr:1 row_mask:0xf bank_mask:0xf bound_ctrl:1
	v_mov_b32_dpp v212, v160 row_shr:1 row_mask:0xf bank_mask:0xf bound_ctrl:1
	v_mov_b32_dpp v213, v161 row_shr:1 row_mask:0xf bank_mask:0xf bound_ctrl:1
	v_mov_b32_dpp v216, v156 row_shr:1 row_mask:0xf bank_mask:0xf bound_ctrl:1
	v_mov_b32_dpp v217, v157 row_shr:1 row_mask:0xf bank_mask:0xf bound_ctrl:1
	v_pk_fma_f32 v[144:145], v[144:145], v[124:125], v[120:121]
	v_pk_fma_f32 v[136:137], v[136:137], v[128:129], v[116:117]
	v_pk_fma_f32 v[144:145], v[160:161], v[104:105], v[144:145]
	v_pk_fma_f32 v[136:137], v[156:157], v[100:101], v[136:137]
	v_pk_fma_f32 v[144:145], v[176:177], v[96:97], v[144:145]
	v_pk_fma_f32 v[136:137], v[172:173], v[92:93], v[136:137]
	v_pk_fma_f32 v[160:161], v[160:161], v[124:125], v[120:121]
	v_pk_fma_f32 v[156:157], v[156:157], v[128:129], v[116:117]
	v_pk_fma_f32 v[160:161], v[176:177], v[104:105], v[160:161]
	v_pk_fma_f32 v[156:157], v[172:173], v[100:101], v[156:157]
	v_pk_fma_f32 v[160:161], v[192:193], v[96:97], v[160:161]
	v_pk_fma_f32 v[156:157], v[188:189], v[92:93], v[156:157]
	v_pk_fma_f32 v[176:177], v[176:177], v[124:125], v[120:121]
	v_pk_fma_f32 v[172:173], v[172:173], v[128:129], v[116:117]
	v_pk_fma_f32 v[176:177], v[192:193], v[104:105], v[176:177]
	v_pk_fma_f32 v[172:173], v[188:189], v[100:101], v[172:173]
	v_pk_fma_f32 v[176:177], v[198:199], v[96:97], v[176:177]
	v_pk_fma_f32 v[172:173], v[214:215], v[92:93], v[172:173]
	v_pk_fma_f32 v[192:193], v[192:193], v[124:125], v[120:121]
	v_pk_fma_f32 v[188:189], v[188:189], v[128:129], v[116:117]
	v_pk_fma_f32 v[192:193], v[198:199], v[104:105], v[192:193]
	v_pk_fma_f32 v[188:189], v[214:215], v[100:101], v[188:189]
	v_pk_fma_f32 v[192:193], v[212:213], v[96:97], v[192:193]
	v_pk_fma_f32 v[188:189], v[216:217], v[92:93], v[188:189]
	v_pk_mul_f32 v[222:223], v[192:193], s[50:51]
	v_pk_mul_f32 v[242:243], v[176:177], s[50:51]
	v_pk_mul_f32 v[244:245], v[160:161], s[50:51]
	v_pk_mul_f32 v[246:247], v[144:145], s[50:51]
	v_exp_f32_e32 v222, v222
	v_exp_f32_e32 v223, v223
	v_exp_f32_e32 v242, v242
	v_exp_f32_e32 v243, v243
	v_exp_f32_e32 v244, v244
	v_exp_f32_e32 v245, v245
	v_exp_f32_e32 v246, v246
	v_exp_f32_e32 v247, v247
	v_pk_add_f32 v[222:223], v[222:223], 1.0 op_sel_hi:[1,0]
	v_pk_add_f32 v[242:243], v[242:243], 1.0 op_sel_hi:[1,0]
	v_pk_add_f32 v[244:245], v[244:245], 1.0 op_sel_hi:[1,0]
	v_pk_add_f32 v[246:247], v[246:247], 1.0 op_sel_hi:[1,0]
	v_rcp_f32_e32 v222, v222
	v_rcp_f32_e32 v223, v223
	v_rcp_f32_e32 v242, v242
	v_rcp_f32_e32 v243, v243
	v_rcp_f32_e32 v244, v244
	v_rcp_f32_e32 v245, v245
	v_rcp_f32_e32 v246, v246
	v_rcp_f32_e32 v247, v247
	v_pk_mul_f32 v[192:193], v[192:193], v[222:223]
	v_pk_mul_f32 v[176:177], v[176:177], v[242:243]
	v_pk_mul_f32 v[160:161], v[160:161], v[244:245]
	v_pk_mul_f32 v[144:145], v[144:145], v[246:247]
	v_pk_mul_f32 v[192:193], v[192:193], v[188:189]
	v_pk_mul_f32 v[176:177], v[176:177], v[172:173]
	v_pk_mul_f32 v[160:161], v[160:161], v[156:157]
	v_pk_mul_f32 v[144:145], v[144:145], v[136:137]
	v_cvt_pk_bf16_f32 v192, v192, v193
	v_cvt_pk_bf16_f32 v176, v176, v177
	v_cvt_pk_bf16_f32 v160, v160, v161
	v_cvt_pk_bf16_f32 v144, v144, v145
	v_mov_b32_dpp v198, v146 row_shr:1 row_mask:0xf bank_mask:0xf bound_ctrl:1
	v_mov_b32_dpp v199, v147 row_shr:1 row_mask:0xf bank_mask:0xf bound_ctrl:1
	v_mov_b32_dpp v214, v138 row_shr:1 row_mask:0xf bank_mask:0xf bound_ctrl:1
	v_mov_b32_dpp v215, v139 row_shr:1 row_mask:0xf bank_mask:0xf bound_ctrl:1
	v_mov_b32_dpp v212, v162 row_shr:1 row_mask:0xf bank_mask:0xf bound_ctrl:1
	v_mov_b32_dpp v213, v163 row_shr:1 row_mask:0xf bank_mask:0xf bound_ctrl:1
	v_mov_b32_dpp v216, v158 row_shr:1 row_mask:0xf bank_mask:0xf bound_ctrl:1
	v_mov_b32_dpp v217, v159 row_shr:1 row_mask:0xf bank_mask:0xf bound_ctrl:1
	v_pk_fma_f32 v[146:147], v[146:147], v[126:127], v[122:123]
	v_pk_fma_f32 v[138:139], v[138:139], v[130:131], v[118:119]
	v_pk_fma_f32 v[146:147], v[162:163], v[106:107], v[146:147]
	v_pk_fma_f32 v[138:139], v[158:159], v[102:103], v[138:139]
	v_pk_fma_f32 v[146:147], v[178:179], v[98:99], v[146:147]
	v_pk_fma_f32 v[138:139], v[174:175], v[94:95], v[138:139]
	v_pk_fma_f32 v[162:163], v[162:163], v[126:127], v[122:123]
	v_pk_fma_f32 v[158:159], v[158:159], v[130:131], v[118:119]
	v_pk_fma_f32 v[162:163], v[178:179], v[106:107], v[162:163]
	v_pk_fma_f32 v[158:159], v[174:175], v[102:103], v[158:159]
	v_pk_fma_f32 v[162:163], v[194:195], v[98:99], v[162:163]
	v_pk_fma_f32 v[158:159], v[190:191], v[94:95], v[158:159]
	v_pk_fma_f32 v[178:179], v[178:179], v[126:127], v[122:123]
	v_pk_fma_f32 v[174:175], v[174:175], v[130:131], v[118:119]
	v_pk_fma_f32 v[178:179], v[194:195], v[106:107], v[178:179]
	v_pk_fma_f32 v[174:175], v[190:191], v[102:103], v[174:175]
	v_pk_fma_f32 v[178:179], v[198:199], v[98:99], v[178:179]
	v_pk_fma_f32 v[174:175], v[214:215], v[94:95], v[174:175]
	v_pk_fma_f32 v[194:195], v[194:195], v[126:127], v[122:123]
	v_pk_fma_f32 v[190:191], v[190:191], v[130:131], v[118:119]
	v_pk_fma_f32 v[194:195], v[198:199], v[106:107], v[194:195]
	v_pk_fma_f32 v[190:191], v[214:215], v[102:103], v[190:191]
	v_pk_fma_f32 v[194:195], v[212:213], v[98:99], v[194:195]
	v_pk_fma_f32 v[190:191], v[216:217], v[94:95], v[190:191]
	v_pk_mul_f32 v[222:223], v[194:195], s[50:51]
	v_pk_mul_f32 v[242:243], v[178:179], s[50:51]
	v_pk_mul_f32 v[244:245], v[162:163], s[50:51]
	v_pk_mul_f32 v[246:247], v[146:147], s[50:51]
	v_exp_f32_e32 v222, v222
	v_exp_f32_e32 v223, v223
	v_exp_f32_e32 v242, v242
	v_exp_f32_e32 v243, v243
	v_exp_f32_e32 v244, v244
	v_exp_f32_e32 v245, v245
	v_exp_f32_e32 v246, v246
	v_exp_f32_e32 v247, v247
	v_pk_add_f32 v[222:223], v[222:223], 1.0 op_sel_hi:[1,0]
	v_pk_add_f32 v[242:243], v[242:243], 1.0 op_sel_hi:[1,0]
	v_pk_add_f32 v[244:245], v[244:245], 1.0 op_sel_hi:[1,0]
	v_pk_add_f32 v[246:247], v[246:247], 1.0 op_sel_hi:[1,0]
	v_rcp_f32_e32 v222, v222
	v_rcp_f32_e32 v223, v223
	v_rcp_f32_e32 v242, v242
	v_rcp_f32_e32 v243, v243
	v_rcp_f32_e32 v244, v244
	v_rcp_f32_e32 v245, v245
	v_rcp_f32_e32 v246, v246
	v_rcp_f32_e32 v247, v247
	v_pk_mul_f32 v[194:195], v[194:195], v[222:223]
	v_pk_mul_f32 v[178:179], v[178:179], v[242:243]
	v_pk_mul_f32 v[162:163], v[162:163], v[244:245]
	v_pk_mul_f32 v[146:147], v[146:147], v[246:247]
	v_pk_mul_f32 v[194:195], v[194:195], v[190:191]
	v_pk_mul_f32 v[178:179], v[178:179], v[174:175]
	v_pk_mul_f32 v[162:163], v[162:163], v[158:159]
	v_pk_mul_f32 v[146:147], v[146:147], v[138:139]
	v_cvt_pk_bf16_f32 v193, v194, v195
	v_cvt_pk_bf16_f32 v177, v178, v179
	v_cvt_pk_bf16_f32 v161, v162, v163
	v_cvt_pk_bf16_f32 v145, v146, v147
	v_mov_b32_dpp v198, v140 row_shr:1 row_mask:0xf bank_mask:0xf bound_ctrl:1
	v_mov_b32_dpp v199, v141 row_shr:1 row_mask:0xf bank_mask:0xf bound_ctrl:1
	v_mov_b32_dpp v214, v132 row_shr:1 row_mask:0xf bank_mask:0xf bound_ctrl:1
	v_mov_b32_dpp v215, v133 row_shr:1 row_mask:0xf bank_mask:0xf bound_ctrl:1
	v_mov_b32_dpp v212, v152 row_shr:1 row_mask:0xf bank_mask:0xf bound_ctrl:1
	v_mov_b32_dpp v213, v153 row_shr:1 row_mask:0xf bank_mask:0xf bound_ctrl:1
	v_mov_b32_dpp v216, v148 row_shr:1 row_mask:0xf bank_mask:0xf bound_ctrl:1
	v_mov_b32_dpp v217, v149 row_shr:1 row_mask:0xf bank_mask:0xf bound_ctrl:1
	v_pk_fma_f32 v[140:141], v[140:141], v[84:85], v[80:81]
	v_pk_fma_f32 v[132:133], v[132:133], v[88:89], v[76:77]
	v_pk_fma_f32 v[140:141], v[152:153], v[64:65], v[140:141]
	v_pk_fma_f32 v[132:133], v[148:149], v[60:61], v[132:133]
	v_pk_fma_f32 v[140:141], v[168:169], v[56:57], v[140:141]
	v_pk_fma_f32 v[132:133], v[164:165], v[52:53], v[132:133]
	v_pk_fma_f32 v[152:153], v[152:153], v[84:85], v[80:81]
	v_pk_fma_f32 v[148:149], v[148:149], v[88:89], v[76:77]
	v_pk_fma_f32 v[152:153], v[168:169], v[64:65], v[152:153]
	v_pk_fma_f32 v[148:149], v[164:165], v[60:61], v[148:149]
	v_pk_fma_f32 v[152:153], v[184:185], v[56:57], v[152:153]
	v_pk_fma_f32 v[148:149], v[180:181], v[52:53], v[148:149]
	v_pk_fma_f32 v[168:169], v[168:169], v[84:85], v[80:81]
	v_pk_fma_f32 v[164:165], v[164:165], v[88:89], v[76:77]
	v_pk_fma_f32 v[168:169], v[184:185], v[64:65], v[168:169]
	v_pk_fma_f32 v[164:165], v[180:181], v[60:61], v[164:165]
	v_pk_fma_f32 v[168:169], v[198:199], v[56:57], v[168:169]
	v_pk_fma_f32 v[164:165], v[214:215], v[52:53], v[164:165]
	v_pk_fma_f32 v[184:185], v[184:185], v[84:85], v[80:81]
	v_pk_fma_f32 v[180:181], v[180:181], v[88:89], v[76:77]
	v_pk_fma_f32 v[184:185], v[198:199], v[64:65], v[184:185]
	v_pk_fma_f32 v[180:181], v[214:215], v[60:61], v[180:181]
	v_pk_fma_f32 v[184:185], v[212:213], v[56:57], v[184:185]
	v_pk_fma_f32 v[180:181], v[216:217], v[52:53], v[180:181]
	v_pk_mul_f32 v[222:223], v[184:185], s[50:51]
	v_pk_mul_f32 v[242:243], v[168:169], s[50:51]
	v_pk_mul_f32 v[244:245], v[152:153], s[50:51]
	v_pk_mul_f32 v[246:247], v[140:141], s[50:51]
	v_exp_f32_e32 v222, v222
	v_exp_f32_e32 v223, v223
	v_exp_f32_e32 v242, v242
	v_exp_f32_e32 v243, v243
	v_exp_f32_e32 v244, v244
	v_exp_f32_e32 v245, v245
	v_exp_f32_e32 v246, v246
	v_exp_f32_e32 v247, v247
	v_pk_add_f32 v[222:223], v[222:223], 1.0 op_sel_hi:[1,0]
	v_pk_add_f32 v[242:243], v[242:243], 1.0 op_sel_hi:[1,0]
	v_pk_add_f32 v[244:245], v[244:245], 1.0 op_sel_hi:[1,0]
	v_pk_add_f32 v[246:247], v[246:247], 1.0 op_sel_hi:[1,0]
	v_rcp_f32_e32 v222, v222
	v_rcp_f32_e32 v223, v223
	v_rcp_f32_e32 v242, v242
	v_rcp_f32_e32 v243, v243
	v_rcp_f32_e32 v244, v244
	v_rcp_f32_e32 v245, v245
	v_rcp_f32_e32 v246, v246
	v_rcp_f32_e32 v247, v247
	v_pk_mul_f32 v[184:185], v[184:185], v[222:223]
	v_pk_mul_f32 v[168:169], v[168:169], v[242:243]
	v_pk_mul_f32 v[152:153], v[152:153], v[244:245]
	v_pk_mul_f32 v[140:141], v[140:141], v[246:247]
	v_pk_mul_f32 v[184:185], v[184:185], v[180:181]
	v_pk_mul_f32 v[168:169], v[168:169], v[164:165]
	v_pk_mul_f32 v[152:153], v[152:153], v[148:149]
	v_pk_mul_f32 v[140:141], v[140:141], v[132:133]
	v_cvt_pk_bf16_f32 v194, v184, v185
	v_cvt_pk_bf16_f32 v178, v168, v169
	v_cvt_pk_bf16_f32 v162, v152, v153
	v_cvt_pk_bf16_f32 v146, v140, v141
	v_mov_b32_dpp v198, v142 row_shr:1 row_mask:0xf bank_mask:0xf bound_ctrl:1
	v_mov_b32_dpp v199, v143 row_shr:1 row_mask:0xf bank_mask:0xf bound_ctrl:1
	v_mov_b32_dpp v214, v134 row_shr:1 row_mask:0xf bank_mask:0xf bound_ctrl:1
	v_mov_b32_dpp v215, v135 row_shr:1 row_mask:0xf bank_mask:0xf bound_ctrl:1
	v_mov_b32_dpp v212, v154 row_shr:1 row_mask:0xf bank_mask:0xf bound_ctrl:1
	v_mov_b32_dpp v213, v155 row_shr:1 row_mask:0xf bank_mask:0xf bound_ctrl:1
	v_mov_b32_dpp v216, v150 row_shr:1 row_mask:0xf bank_mask:0xf bound_ctrl:1
	v_mov_b32_dpp v217, v151 row_shr:1 row_mask:0xf bank_mask:0xf bound_ctrl:1
	v_pk_fma_f32 v[142:143], v[142:143], v[86:87], v[82:83]
	v_pk_fma_f32 v[134:135], v[134:135], v[90:91], v[78:79]
	v_pk_fma_f32 v[142:143], v[154:155], v[66:67], v[142:143]
	v_pk_fma_f32 v[134:135], v[150:151], v[62:63], v[134:135]
	v_pk_fma_f32 v[142:143], v[170:171], v[58:59], v[142:143]
	v_pk_fma_f32 v[134:135], v[166:167], v[54:55], v[134:135]
	v_pk_fma_f32 v[154:155], v[154:155], v[86:87], v[82:83]
	v_pk_fma_f32 v[150:151], v[150:151], v[90:91], v[78:79]
	v_pk_fma_f32 v[154:155], v[170:171], v[66:67], v[154:155]
	v_pk_fma_f32 v[150:151], v[166:167], v[62:63], v[150:151]
	v_pk_fma_f32 v[154:155], v[186:187], v[58:59], v[154:155]
	v_pk_fma_f32 v[150:151], v[182:183], v[54:55], v[150:151]
	v_pk_fma_f32 v[170:171], v[170:171], v[86:87], v[82:83]
	v_pk_fma_f32 v[166:167], v[166:167], v[90:91], v[78:79]
	v_pk_fma_f32 v[170:171], v[186:187], v[66:67], v[170:171]
	v_pk_fma_f32 v[166:167], v[182:183], v[62:63], v[166:167]
	v_pk_fma_f32 v[170:171], v[198:199], v[58:59], v[170:171]
	v_pk_fma_f32 v[166:167], v[214:215], v[54:55], v[166:167]
	v_pk_fma_f32 v[186:187], v[186:187], v[86:87], v[82:83]
	v_pk_fma_f32 v[182:183], v[182:183], v[90:91], v[78:79]
	v_pk_fma_f32 v[186:187], v[198:199], v[66:67], v[186:187]
	v_pk_fma_f32 v[182:183], v[214:215], v[62:63], v[182:183]
	v_pk_fma_f32 v[186:187], v[212:213], v[58:59], v[186:187]
	v_pk_fma_f32 v[182:183], v[216:217], v[54:55], v[182:183]
	v_pk_mul_f32 v[222:223], v[186:187], s[50:51]
	v_pk_mul_f32 v[242:243], v[170:171], s[50:51]
	v_pk_mul_f32 v[244:245], v[154:155], s[50:51]
	v_pk_mul_f32 v[246:247], v[142:143], s[50:51]
	v_exp_f32_e32 v222, v222
	v_exp_f32_e32 v223, v223
	v_exp_f32_e32 v242, v242
	v_exp_f32_e32 v243, v243
	v_exp_f32_e32 v244, v244
	v_exp_f32_e32 v245, v245
	v_exp_f32_e32 v246, v246
	v_exp_f32_e32 v247, v247
	v_pk_add_f32 v[222:223], v[222:223], 1.0 op_sel_hi:[1,0]
	v_pk_add_f32 v[242:243], v[242:243], 1.0 op_sel_hi:[1,0]
	v_pk_add_f32 v[244:245], v[244:245], 1.0 op_sel_hi:[1,0]
	v_pk_add_f32 v[246:247], v[246:247], 1.0 op_sel_hi:[1,0]
	v_rcp_f32_e32 v222, v222
	v_rcp_f32_e32 v223, v223
	v_rcp_f32_e32 v242, v242
	v_rcp_f32_e32 v243, v243
	v_rcp_f32_e32 v244, v244
	v_rcp_f32_e32 v245, v245
	v_rcp_f32_e32 v246, v246
	v_rcp_f32_e32 v247, v247
	v_pk_mul_f32 v[186:187], v[186:187], v[222:223]
	v_pk_mul_f32 v[170:171], v[170:171], v[242:243]
	v_pk_mul_f32 v[154:155], v[154:155], v[244:245]
	v_pk_mul_f32 v[142:143], v[142:143], v[246:247]
	v_pk_mul_f32 v[186:187], v[186:187], v[182:183]
	v_pk_mul_f32 v[170:171], v[170:171], v[166:167]
	v_pk_mul_f32 v[154:155], v[154:155], v[150:151]
	v_pk_mul_f32 v[142:143], v[142:143], v[134:135]
	v_cvt_pk_bf16_f32 v195, v186, v187
	v_cvt_pk_bf16_f32 v179, v170, v171
	v_cvt_pk_bf16_f32 v163, v154, v155
	v_cvt_pk_bf16_f32 v147, v142, v143
	s_mov_b64 s[20:21], s[82:83]
	global_store_dwordx4 v240, v[192:195], s[20:21]
	s_add_u32 s20, s82, 0x1600
	s_addc_u32 s21, s83, 0
	global_store_dwordx4 v240, v[176:179], s[20:21]
	s_add_u32 s20, s82, 0x2c00
	s_addc_u32 s21, s83, 0
	global_store_dwordx4 v240, v[160:163], s[20:21]
	s_add_u32 s20, s82, 0x4200
	s_addc_u32 s21, s83, 0
	global_store_dwordx4 v240, v[144:147], s[20:21]
	v_mov_b32_dpp v198, v16 row_shr:1 row_mask:0xf bank_mask:0xf bound_ctrl:1
	v_mov_b32_dpp v199, v17 row_shr:1 row_mask:0xf bank_mask:0xf bound_ctrl:1
	v_mov_b32_dpp v214, v8 row_shr:1 row_mask:0xf bank_mask:0xf bound_ctrl:1
	v_mov_b32_dpp v215, v9 row_shr:1 row_mask:0xf bank_mask:0xf bound_ctrl:1
	v_mov_b32_dpp v212, v32 row_shr:1 row_mask:0xf bank_mask:0xf bound_ctrl:1
	v_mov_b32_dpp v213, v33 row_shr:1 row_mask:0xf bank_mask:0xf bound_ctrl:1
	v_mov_b32_dpp v216, v28 row_shr:1 row_mask:0xf bank_mask:0xf bound_ctrl:1
	v_mov_b32_dpp v217, v29 row_shr:1 row_mask:0xf bank_mask:0xf bound_ctrl:1
	v_pk_fma_f32 v[16:17], v[16:17], v[124:125], v[120:121]
	v_pk_fma_f32 v[8:9], v[8:9], v[128:129], v[116:117]
	v_pk_fma_f32 v[16:17], v[32:33], v[104:105], v[16:17]
	v_pk_fma_f32 v[8:9], v[28:29], v[100:101], v[8:9]
	v_pk_fma_f32 v[16:17], v[48:49], v[96:97], v[16:17]
	v_pk_fma_f32 v[8:9], v[44:45], v[92:93], v[8:9]
	v_pk_fma_f32 v[32:33], v[32:33], v[124:125], v[120:121]
	v_pk_fma_f32 v[28:29], v[28:29], v[128:129], v[116:117]
	v_pk_fma_f32 v[32:33], v[48:49], v[104:105], v[32:33]
	v_pk_fma_f32 v[28:29], v[44:45], v[100:101], v[28:29]
	v_pk_fma_f32 v[32:33], v[112:113], v[96:97], v[32:33]
	v_pk_fma_f32 v[28:29], v[108:109], v[92:93], v[28:29]
	v_pk_fma_f32 v[48:49], v[48:49], v[124:125], v[120:121]
	v_pk_fma_f32 v[44:45], v[44:45], v[128:129], v[116:117]
	v_pk_fma_f32 v[48:49], v[112:113], v[104:105], v[48:49]
	v_pk_fma_f32 v[44:45], v[108:109], v[100:101], v[44:45]
	v_pk_fma_f32 v[48:49], v[198:199], v[96:97], v[48:49]
	v_pk_fma_f32 v[44:45], v[214:215], v[92:93], v[44:45]
	v_pk_fma_f32 v[112:113], v[112:113], v[124:125], v[120:121]
	v_pk_fma_f32 v[108:109], v[108:109], v[128:129], v[116:117]
	v_pk_fma_f32 v[112:113], v[198:199], v[104:105], v[112:113]
	v_pk_fma_f32 v[108:109], v[214:215], v[100:101], v[108:109]
	v_pk_fma_f32 v[112:113], v[212:213], v[96:97], v[112:113]
	v_pk_fma_f32 v[108:109], v[216:217], v[92:93], v[108:109]
	v_pk_mul_f32 v[222:223], v[112:113], s[50:51]
	v_pk_mul_f32 v[242:243], v[48:49], s[50:51]
	v_pk_mul_f32 v[244:245], v[32:33], s[50:51]
	v_pk_mul_f32 v[246:247], v[16:17], s[50:51]
	v_exp_f32_e32 v222, v222
	v_exp_f32_e32 v223, v223
	v_exp_f32_e32 v242, v242
	v_exp_f32_e32 v243, v243
	v_exp_f32_e32 v244, v244
	v_exp_f32_e32 v245, v245
	v_exp_f32_e32 v246, v246
	v_exp_f32_e32 v247, v247
	v_pk_add_f32 v[222:223], v[222:223], 1.0 op_sel_hi:[1,0]
	v_pk_add_f32 v[242:243], v[242:243], 1.0 op_sel_hi:[1,0]
	v_pk_add_f32 v[244:245], v[244:245], 1.0 op_sel_hi:[1,0]
	v_pk_add_f32 v[246:247], v[246:247], 1.0 op_sel_hi:[1,0]
	v_rcp_f32_e32 v222, v222
	v_rcp_f32_e32 v223, v223
	v_rcp_f32_e32 v242, v242
	v_rcp_f32_e32 v243, v243
	v_rcp_f32_e32 v244, v244
	v_rcp_f32_e32 v245, v245
	v_rcp_f32_e32 v246, v246
	v_rcp_f32_e32 v247, v247
	v_pk_mul_f32 v[112:113], v[112:113], v[222:223]
	v_pk_mul_f32 v[48:49], v[48:49], v[242:243]
	v_pk_mul_f32 v[32:33], v[32:33], v[244:245]
	v_pk_mul_f32 v[16:17], v[16:17], v[246:247]
	v_pk_mul_f32 v[112:113], v[112:113], v[108:109]
	v_pk_mul_f32 v[48:49], v[48:49], v[44:45]
	v_pk_mul_f32 v[32:33], v[32:33], v[28:29]
	v_pk_mul_f32 v[16:17], v[16:17], v[8:9]
	v_cvt_pk_bf16_f32 v112, v112, v113
	v_cvt_pk_bf16_f32 v48, v48, v49
	v_cvt_pk_bf16_f32 v32, v32, v33
	v_cvt_pk_bf16_f32 v16, v16, v17
	v_mov_b32_dpp v198, v18 row_shr:1 row_mask:0xf bank_mask:0xf bound_ctrl:1
	v_mov_b32_dpp v199, v19 row_shr:1 row_mask:0xf bank_mask:0xf bound_ctrl:1
	v_mov_b32_dpp v214, v10 row_shr:1 row_mask:0xf bank_mask:0xf bound_ctrl:1
	v_mov_b32_dpp v215, v11 row_shr:1 row_mask:0xf bank_mask:0xf bound_ctrl:1
	v_mov_b32_dpp v212, v34 row_shr:1 row_mask:0xf bank_mask:0xf bound_ctrl:1
	v_mov_b32_dpp v213, v35 row_shr:1 row_mask:0xf bank_mask:0xf bound_ctrl:1
	v_mov_b32_dpp v216, v30 row_shr:1 row_mask:0xf bank_mask:0xf bound_ctrl:1
	v_mov_b32_dpp v217, v31 row_shr:1 row_mask:0xf bank_mask:0xf bound_ctrl:1
	v_pk_fma_f32 v[18:19], v[18:19], v[126:127], v[122:123]
	v_pk_fma_f32 v[10:11], v[10:11], v[130:131], v[118:119]
	v_pk_fma_f32 v[18:19], v[34:35], v[106:107], v[18:19]
	v_pk_fma_f32 v[10:11], v[30:31], v[102:103], v[10:11]
	v_pk_fma_f32 v[18:19], v[50:51], v[98:99], v[18:19]
	v_pk_fma_f32 v[10:11], v[46:47], v[94:95], v[10:11]
	v_pk_fma_f32 v[34:35], v[34:35], v[126:127], v[122:123]
	v_pk_fma_f32 v[30:31], v[30:31], v[130:131], v[118:119]
	v_pk_fma_f32 v[34:35], v[50:51], v[106:107], v[34:35]
	v_pk_fma_f32 v[30:31], v[46:47], v[102:103], v[30:31]
	v_pk_fma_f32 v[34:35], v[114:115], v[98:99], v[34:35]
	v_pk_fma_f32 v[30:31], v[110:111], v[94:95], v[30:31]
	v_pk_fma_f32 v[50:51], v[50:51], v[126:127], v[122:123]
	v_pk_fma_f32 v[46:47], v[46:47], v[130:131], v[118:119]
	v_pk_fma_f32 v[50:51], v[114:115], v[106:107], v[50:51]
	v_pk_fma_f32 v[46:47], v[110:111], v[102:103], v[46:47]
	v_pk_fma_f32 v[50:51], v[198:199], v[98:99], v[50:51]
	v_pk_fma_f32 v[46:47], v[214:215], v[94:95], v[46:47]
	v_pk_fma_f32 v[114:115], v[114:115], v[126:127], v[122:123]
	v_pk_fma_f32 v[110:111], v[110:111], v[130:131], v[118:119]
	v_pk_fma_f32 v[114:115], v[198:199], v[106:107], v[114:115]
	v_pk_fma_f32 v[110:111], v[214:215], v[102:103], v[110:111]
	v_pk_fma_f32 v[114:115], v[212:213], v[98:99], v[114:115]
	v_pk_fma_f32 v[110:111], v[216:217], v[94:95], v[110:111]
	v_pk_mul_f32 v[222:223], v[114:115], s[50:51]
	v_pk_mul_f32 v[242:243], v[50:51], s[50:51]
	v_pk_mul_f32 v[244:245], v[34:35], s[50:51]
	v_pk_mul_f32 v[246:247], v[18:19], s[50:51]
	v_exp_f32_e32 v222, v222
	v_exp_f32_e32 v223, v223
	v_exp_f32_e32 v242, v242
	v_exp_f32_e32 v243, v243
	v_exp_f32_e32 v244, v244
	v_exp_f32_e32 v245, v245
	v_exp_f32_e32 v246, v246
	v_exp_f32_e32 v247, v247
	v_pk_add_f32 v[222:223], v[222:223], 1.0 op_sel_hi:[1,0]
	v_pk_add_f32 v[242:243], v[242:243], 1.0 op_sel_hi:[1,0]
	v_pk_add_f32 v[244:245], v[244:245], 1.0 op_sel_hi:[1,0]
	v_pk_add_f32 v[246:247], v[246:247], 1.0 op_sel_hi:[1,0]
	v_rcp_f32_e32 v222, v222
	v_rcp_f32_e32 v223, v223
	v_rcp_f32_e32 v242, v242
	v_rcp_f32_e32 v243, v243
	v_rcp_f32_e32 v244, v244
	v_rcp_f32_e32 v245, v245
	v_rcp_f32_e32 v246, v246
	v_rcp_f32_e32 v247, v247
	v_pk_mul_f32 v[114:115], v[114:115], v[222:223]
	v_pk_mul_f32 v[50:51], v[50:51], v[242:243]
	v_pk_mul_f32 v[34:35], v[34:35], v[244:245]
	v_pk_mul_f32 v[18:19], v[18:19], v[246:247]
	v_pk_mul_f32 v[114:115], v[114:115], v[110:111]
	v_pk_mul_f32 v[50:51], v[50:51], v[46:47]
	v_pk_mul_f32 v[34:35], v[34:35], v[30:31]
	v_pk_mul_f32 v[18:19], v[18:19], v[10:11]
	v_cvt_pk_bf16_f32 v113, v114, v115
	v_cvt_pk_bf16_f32 v49, v50, v51
	v_cvt_pk_bf16_f32 v33, v34, v35
	v_cvt_pk_bf16_f32 v17, v18, v19
	v_mov_b32_dpp v198, v12 row_shr:1 row_mask:0xf bank_mask:0xf bound_ctrl:1
	v_mov_b32_dpp v199, v13 row_shr:1 row_mask:0xf bank_mask:0xf bound_ctrl:1
	v_mov_b32_dpp v214, v4 row_shr:1 row_mask:0xf bank_mask:0xf bound_ctrl:1
	v_mov_b32_dpp v215, v5 row_shr:1 row_mask:0xf bank_mask:0xf bound_ctrl:1
	v_mov_b32_dpp v212, v24 row_shr:1 row_mask:0xf bank_mask:0xf bound_ctrl:1
	v_mov_b32_dpp v213, v25 row_shr:1 row_mask:0xf bank_mask:0xf bound_ctrl:1
	v_mov_b32_dpp v216, v20 row_shr:1 row_mask:0xf bank_mask:0xf bound_ctrl:1
	v_mov_b32_dpp v217, v21 row_shr:1 row_mask:0xf bank_mask:0xf bound_ctrl:1
	v_pk_fma_f32 v[12:13], v[12:13], v[84:85], v[80:81]
	v_pk_fma_f32 v[4:5], v[4:5], v[88:89], v[76:77]
	v_pk_fma_f32 v[12:13], v[24:25], v[64:65], v[12:13]
	v_pk_fma_f32 v[4:5], v[20:21], v[60:61], v[4:5]
	v_pk_fma_f32 v[12:13], v[40:41], v[56:57], v[12:13]
	v_pk_fma_f32 v[4:5], v[36:37], v[52:53], v[4:5]
	v_pk_fma_f32 v[24:25], v[24:25], v[84:85], v[80:81]
	v_pk_fma_f32 v[20:21], v[20:21], v[88:89], v[76:77]
	v_pk_fma_f32 v[24:25], v[40:41], v[64:65], v[24:25]
	v_pk_fma_f32 v[20:21], v[36:37], v[60:61], v[20:21]
	v_pk_fma_f32 v[24:25], v[72:73], v[56:57], v[24:25]
	v_pk_fma_f32 v[20:21], v[68:69], v[52:53], v[20:21]
	v_pk_fma_f32 v[40:41], v[40:41], v[84:85], v[80:81]
	v_pk_fma_f32 v[36:37], v[36:37], v[88:89], v[76:77]
	v_pk_fma_f32 v[40:41], v[72:73], v[64:65], v[40:41]
	v_pk_fma_f32 v[36:37], v[68:69], v[60:61], v[36:37]
	v_pk_fma_f32 v[40:41], v[198:199], v[56:57], v[40:41]
	v_pk_fma_f32 v[36:37], v[214:215], v[52:53], v[36:37]
	v_pk_fma_f32 v[72:73], v[72:73], v[84:85], v[80:81]
	v_pk_fma_f32 v[68:69], v[68:69], v[88:89], v[76:77]
	v_pk_fma_f32 v[72:73], v[198:199], v[64:65], v[72:73]
	v_pk_fma_f32 v[68:69], v[214:215], v[60:61], v[68:69]
	v_pk_fma_f32 v[72:73], v[212:213], v[56:57], v[72:73]
	v_pk_fma_f32 v[68:69], v[216:217], v[52:53], v[68:69]
	v_pk_mul_f32 v[222:223], v[72:73], s[50:51]
	v_pk_mul_f32 v[242:243], v[40:41], s[50:51]
	v_pk_mul_f32 v[244:245], v[24:25], s[50:51]
	v_pk_mul_f32 v[246:247], v[12:13], s[50:51]
	v_exp_f32_e32 v222, v222
	v_exp_f32_e32 v223, v223
	v_exp_f32_e32 v242, v242
	v_exp_f32_e32 v243, v243
	v_exp_f32_e32 v244, v244
	v_exp_f32_e32 v245, v245
	v_exp_f32_e32 v246, v246
	v_exp_f32_e32 v247, v247
	v_pk_add_f32 v[222:223], v[222:223], 1.0 op_sel_hi:[1,0]
	v_pk_add_f32 v[242:243], v[242:243], 1.0 op_sel_hi:[1,0]
	v_pk_add_f32 v[244:245], v[244:245], 1.0 op_sel_hi:[1,0]
	v_pk_add_f32 v[246:247], v[246:247], 1.0 op_sel_hi:[1,0]
	v_rcp_f32_e32 v222, v222
	v_rcp_f32_e32 v223, v223
	v_rcp_f32_e32 v242, v242
	v_rcp_f32_e32 v243, v243
	v_rcp_f32_e32 v244, v244
	v_rcp_f32_e32 v245, v245
	v_rcp_f32_e32 v246, v246
	v_rcp_f32_e32 v247, v247
	v_pk_mul_f32 v[72:73], v[72:73], v[222:223]
	v_pk_mul_f32 v[40:41], v[40:41], v[242:243]
	v_pk_mul_f32 v[24:25], v[24:25], v[244:245]
	v_pk_mul_f32 v[12:13], v[12:13], v[246:247]
	v_pk_mul_f32 v[72:73], v[72:73], v[68:69]
	v_pk_mul_f32 v[40:41], v[40:41], v[36:37]
	v_pk_mul_f32 v[24:25], v[24:25], v[20:21]
	v_pk_mul_f32 v[12:13], v[12:13], v[4:5]
	v_cvt_pk_bf16_f32 v114, v72, v73
	v_cvt_pk_bf16_f32 v50, v40, v41
	v_cvt_pk_bf16_f32 v34, v24, v25
	v_cvt_pk_bf16_f32 v18, v12, v13
	v_mov_b32_dpp v198, v14 row_shr:1 row_mask:0xf bank_mask:0xf bound_ctrl:1
	v_mov_b32_dpp v199, v15 row_shr:1 row_mask:0xf bank_mask:0xf bound_ctrl:1
	v_mov_b32_dpp v214, v6 row_shr:1 row_mask:0xf bank_mask:0xf bound_ctrl:1
	v_mov_b32_dpp v215, v7 row_shr:1 row_mask:0xf bank_mask:0xf bound_ctrl:1
	v_mov_b32_dpp v212, v26 row_shr:1 row_mask:0xf bank_mask:0xf bound_ctrl:1
	v_mov_b32_dpp v213, v27 row_shr:1 row_mask:0xf bank_mask:0xf bound_ctrl:1
	v_mov_b32_dpp v216, v22 row_shr:1 row_mask:0xf bank_mask:0xf bound_ctrl:1
	v_mov_b32_dpp v217, v23 row_shr:1 row_mask:0xf bank_mask:0xf bound_ctrl:1
	v_pk_fma_f32 v[14:15], v[14:15], v[86:87], v[82:83]
	v_pk_fma_f32 v[6:7], v[6:7], v[90:91], v[78:79]
	v_pk_fma_f32 v[14:15], v[26:27], v[66:67], v[14:15]
	v_pk_fma_f32 v[6:7], v[22:23], v[62:63], v[6:7]
	v_pk_fma_f32 v[14:15], v[42:43], v[58:59], v[14:15]
	v_pk_fma_f32 v[6:7], v[38:39], v[54:55], v[6:7]
	v_pk_fma_f32 v[26:27], v[26:27], v[86:87], v[82:83]
	v_pk_fma_f32 v[22:23], v[22:23], v[90:91], v[78:79]
	v_pk_fma_f32 v[26:27], v[42:43], v[66:67], v[26:27]
	v_pk_fma_f32 v[22:23], v[38:39], v[62:63], v[22:23]
	v_pk_fma_f32 v[26:27], v[74:75], v[58:59], v[26:27]
	v_pk_fma_f32 v[22:23], v[70:71], v[54:55], v[22:23]
	v_pk_fma_f32 v[42:43], v[42:43], v[86:87], v[82:83]
	v_pk_fma_f32 v[38:39], v[38:39], v[90:91], v[78:79]
	v_pk_fma_f32 v[42:43], v[74:75], v[66:67], v[42:43]
	v_pk_fma_f32 v[38:39], v[70:71], v[62:63], v[38:39]
	v_pk_fma_f32 v[42:43], v[198:199], v[58:59], v[42:43]
	v_pk_fma_f32 v[38:39], v[214:215], v[54:55], v[38:39]
	v_pk_fma_f32 v[74:75], v[74:75], v[86:87], v[82:83]
	v_pk_fma_f32 v[70:71], v[70:71], v[90:91], v[78:79]
	v_pk_fma_f32 v[74:75], v[198:199], v[66:67], v[74:75]
	v_pk_fma_f32 v[70:71], v[214:215], v[62:63], v[70:71]
	v_pk_fma_f32 v[74:75], v[212:213], v[58:59], v[74:75]
	v_pk_fma_f32 v[70:71], v[216:217], v[54:55], v[70:71]
	v_pk_mul_f32 v[222:223], v[74:75], s[50:51]
	v_pk_mul_f32 v[242:243], v[42:43], s[50:51]
	v_pk_mul_f32 v[244:245], v[26:27], s[50:51]
	v_pk_mul_f32 v[246:247], v[14:15], s[50:51]
	v_exp_f32_e32 v222, v222
	v_exp_f32_e32 v223, v223
	v_exp_f32_e32 v242, v242
	v_exp_f32_e32 v243, v243
	v_exp_f32_e32 v244, v244
	v_exp_f32_e32 v245, v245
	v_exp_f32_e32 v246, v246
	v_exp_f32_e32 v247, v247
	v_pk_add_f32 v[222:223], v[222:223], 1.0 op_sel_hi:[1,0]
	v_pk_add_f32 v[242:243], v[242:243], 1.0 op_sel_hi:[1,0]
	v_pk_add_f32 v[244:245], v[244:245], 1.0 op_sel_hi:[1,0]
	v_pk_add_f32 v[246:247], v[246:247], 1.0 op_sel_hi:[1,0]
	v_rcp_f32_e32 v222, v222
	v_rcp_f32_e32 v223, v223
	v_rcp_f32_e32 v242, v242
	v_rcp_f32_e32 v243, v243
	v_rcp_f32_e32 v244, v244
	v_rcp_f32_e32 v245, v245
	v_rcp_f32_e32 v246, v246
	v_rcp_f32_e32 v247, v247
	v_pk_mul_f32 v[74:75], v[74:75], v[222:223]
	v_pk_mul_f32 v[42:43], v[42:43], v[242:243]
	v_pk_mul_f32 v[26:27], v[26:27], v[244:245]
	v_pk_mul_f32 v[14:15], v[14:15], v[246:247]
	v_pk_mul_f32 v[74:75], v[74:75], v[70:71]
	v_pk_mul_f32 v[42:43], v[42:43], v[38:39]
	v_pk_mul_f32 v[26:27], v[26:27], v[22:23]
	v_pk_mul_f32 v[14:15], v[14:15], v[6:7]
	v_cvt_pk_bf16_f32 v115, v74, v75
	v_cvt_pk_bf16_f32 v51, v42, v43
	v_cvt_pk_bf16_f32 v35, v26, v27
	v_cvt_pk_bf16_f32 v19, v14, v15
	s_add_u32 s20, s82, 0xb0000
	s_addc_u32 s21, s83, 0
	global_store_dwordx4 v240, v[112:115], s[20:21]
	s_add_u32 s20, s82, 0xb1600
	s_addc_u32 s21, s83, 0
	global_store_dwordx4 v240, v[48:51], s[20:21]
	s_add_u32 s20, s82, 0xb2c00
	s_addc_u32 s21, s83, 0
	global_store_dwordx4 v240, v[32:35], s[20:21]
	s_add_u32 s20, s82, 0xb4200
	s_addc_u32 s21, s83, 0
	global_store_dwordx4 v240, v[16:19], s[20:21]
	s_mov_b64 s[50:51], -1
	s_branch .LBB0_76

.LBB0_135:
	s_add_u32 s48, s48, 0x40080
	s_addc_u32 s49, s49, 0
	s_add_u32 s20, s50, 0x100
	v_mov_b32_e32 v4, 0
	s_addc_u32 s21, s51, 0
	s_mov_b32 s22, -2
	v_mov_b32_e32 v5, v4
	v_mov_b32_e32 v6, v4
	v_mov_b32_e32 v7, v4
	v_mov_b32_e32 v8, v4
	v_mov_b32_e32 v9, v4
	v_mov_b32_e32 v10, v4
	v_mov_b32_e32 v11, v4
	v_mov_b32_e32 v12, v4
	v_mov_b32_e32 v13, v4
	v_mov_b32_e32 v14, v4
	v_mov_b32_e32 v15, v4
	v_mov_b32_e32 v20, v4
	v_mov_b32_e32 v21, v4
	v_mov_b32_e32 v22, v4
	v_mov_b32_e32 v23, v4
	v_mov_b32_e32 v28, v4
	v_mov_b32_e32 v29, v4
	v_mov_b32_e32 v30, v4
	v_mov_b32_e32 v31, v4
	v_mov_b32_e32 v32, v4
	v_mov_b32_e32 v33, v4
	v_mov_b32_e32 v34, v4
	v_mov_b32_e32 v35, v4
	v_mov_b32_e32 v44, v4
	v_mov_b32_e32 v45, v4
	v_mov_b32_e32 v46, v4
	v_mov_b32_e32 v47, v4
	v_mov_b32_e32 v48, v4
	v_mov_b32_e32 v49, v4
	v_mov_b32_e32 v50, v4
	v_mov_b32_e32 v51, v4
	v_mov_b32_e32 v16, v4
	v_mov_b32_e32 v17, v4
	v_mov_b32_e32 v18, v4
	v_mov_b32_e32 v19, v4
	v_mov_b32_e32 v24, v4
	v_mov_b32_e32 v25, v4
	v_mov_b32_e32 v26, v4
	v_mov_b32_e32 v27, v4
	v_mov_b32_e32 v36, v4
	v_mov_b32_e32 v37, v4
	v_mov_b32_e32 v38, v4
	v_mov_b32_e32 v39, v4
	v_mov_b32_e32 v40, v4
	v_mov_b32_e32 v41, v4
	v_mov_b32_e32 v42, v4
	v_mov_b32_e32 v43, v4
	v_mov_b32_e32 v52, v4
	v_mov_b32_e32 v53, v4
	v_mov_b32_e32 v54, v4
	v_mov_b32_e32 v55, v4
	v_mov_b32_e32 v56, v4
	v_mov_b32_e32 v57, v4
	v_mov_b32_e32 v58, v4
	v_mov_b32_e32 v59, v4
	v_mov_b32_e32 v60, v4
	v_mov_b32_e32 v61, v4
	v_mov_b32_e32 v62, v4
	v_mov_b32_e32 v63, v4
	v_mov_b32_e32 v64, v4
	v_mov_b32_e32 v65, v4
	v_mov_b32_e32 v66, v4
	v_mov_b32_e32 v67, v4
	v_mov_b32_e32 v68, v4
	v_mov_b32_e32 v69, v4
	v_mov_b32_e32 v70, v4
	v_mov_b32_e32 v71, v4
	v_mov_b32_e32 v72, v4
	v_mov_b32_e32 v73, v4
	v_mov_b32_e32 v74, v4
	v_mov_b32_e32 v75, v4
	v_mov_b32_e32 v76, v4
	v_mov_b32_e32 v77, v4
	v_mov_b32_e32 v78, v4
	v_mov_b32_e32 v79, v4
	v_mov_b32_e32 v80, v4
	v_mov_b32_e32 v81, v4
	v_mov_b32_e32 v82, v4
	v_mov_b32_e32 v83, v4
	v_mov_b32_e32 v92, v4
	v_mov_b32_e32 v93, v4
	v_mov_b32_e32 v94, v4
	v_mov_b32_e32 v95, v4
	v_mov_b32_e32 v96, v4
	v_mov_b32_e32 v97, v4
	v_mov_b32_e32 v98, v4
	v_mov_b32_e32 v99, v4
	v_mov_b32_e32 v108, v4
	v_mov_b32_e32 v109, v4
	v_mov_b32_e32 v110, v4
	v_mov_b32_e32 v111, v4
	v_mov_b32_e32 v112, v4
	v_mov_b32_e32 v113, v4
	v_mov_b32_e32 v114, v4
	v_mov_b32_e32 v115, v4
	v_mov_b32_e32 v84, v4
	v_mov_b32_e32 v85, v4
	v_mov_b32_e32 v86, v4
	v_mov_b32_e32 v87, v4
	v_mov_b32_e32 v88, v4
	v_mov_b32_e32 v89, v4
	v_mov_b32_e32 v90, v4
	v_mov_b32_e32 v91, v4
	v_mov_b32_e32 v100, v4
	v_mov_b32_e32 v101, v4
	v_mov_b32_e32 v102, v4
	v_mov_b32_e32 v103, v4
	v_mov_b32_e32 v104, v4
	v_mov_b32_e32 v105, v4
	v_mov_b32_e32 v106, v4
	v_mov_b32_e32 v107, v4
	v_mov_b32_e32 v116, v4
	v_mov_b32_e32 v117, v4
	v_mov_b32_e32 v118, v4
	v_mov_b32_e32 v119, v4
	v_mov_b32_e32 v120, v4
	v_mov_b32_e32 v121, v4
	v_mov_b32_e32 v122, v4
	v_mov_b32_e32 v123, v4
	v_mov_b32_e32 v124, v4
	v_mov_b32_e32 v125, v4
	v_mov_b32_e32 v126, v4
	v_mov_b32_e32 v127, v4
	v_mov_b32_e32 v128, v4
	v_mov_b32_e32 v129, v4
	v_mov_b32_e32 v130, v4
	v_mov_b32_e32 v131, v4
	v_add_u32_e32 v194, 0x10000, v143
.LBB0_136:
	s_add_u32 s23, s48, 0xfffc0080
	s_addc_u32 s24, s49, -1
	s_add_i32 s25, 0, 0x10000
	ds_read_b128 v[146:149], v194
	ds_read_b128 v[150:153], v194 offset:1024
	ds_read_b128 v[154:157], v194 offset:2048
	ds_read_b128 v[158:161], v194 offset:3072
	s_cmp_eq_u32 s22, 12
	s_cselect_b32 s53, s45, s24
	s_cselect_b32 s52, s44, s23
	s_cselect_b32 s51, s47, s21
	s_cselect_b32 s50, s46, s20
	s_add_i32 m0, s54, 0xc000
	ds_read_b128 v[162:165], v144
	ds_read_b128 v[166:169], v144 offset:1024
	ds_read_b128 v[170:173], v144 offset:2048
	ds_read_b128 v[174:177], v144 offset:3072
	ds_read_b128 v[178:181], v144 offset:4096
	ds_read_b128 v[182:185], v144 offset:5120
	ds_read_b128 v[186:189], v144 offset:6144
	global_load_lds_dwordx4 v138, s[48:49]
	s_add_i32 m0, s54, 0xe000
	ds_read_b128 v[190:193], v144 offset:7168
	global_load_lds_dwordx4 v140, s[48:49]
	s_waitcnt lgkmcnt(8)
	s_barrier
	s_waitcnt lgkmcnt(0)
	v_mfma_f32_16x16x32_bf16 v[128:131], v[146:149], v[162:165], v[128:131]
	v_mfma_f32_16x16x32_bf16 v[124:127], v[154:157], v[162:165], v[124:127]
	v_mfma_f32_16x16x32_bf16 v[120:123], v[146:149], v[170:173], v[120:123]
	v_mfma_f32_16x16x32_bf16 v[116:119], v[154:157], v[170:173], v[116:119]
	v_mfma_f32_16x16x32_bf16 v[104:107], v[146:149], v[178:181], v[104:107]
	v_mfma_f32_16x16x32_bf16 v[100:103], v[154:157], v[178:181], v[100:103]
	v_mfma_f32_16x16x32_bf16 v[88:91], v[146:149], v[186:189], v[88:91]
	v_mfma_f32_16x16x32_bf16 v[84:87], v[154:157], v[186:189], v[84:87]
	v_mfma_f32_16x16x32_bf16 v[128:131], v[150:153], v[166:169], v[128:131]
	v_mfma_f32_16x16x32_bf16 v[124:127], v[158:161], v[166:169], v[124:127]
	v_mfma_f32_16x16x32_bf16 v[120:123], v[150:153], v[174:177], v[120:123]
	v_mfma_f32_16x16x32_bf16 v[116:119], v[158:161], v[174:177], v[116:119]
	v_mfma_f32_16x16x32_bf16 v[104:107], v[150:153], v[182:185], v[104:107]
	v_mfma_f32_16x16x32_bf16 v[100:103], v[158:161], v[182:185], v[100:103]
	v_mfma_f32_16x16x32_bf16 v[88:91], v[150:153], v[190:193], v[88:91]
	v_mfma_f32_16x16x32_bf16 v[84:87], v[158:161], v[190:193], v[84:87]
	s_barrier
	s_add_i32 s23, 0, 0x14000
	s_add_i32 s24, s25, s37
	s_mov_b32 m0, s24
	ds_read_b128 v[202:205], v194 offset:16384
	ds_read_b128 v[206:209], v194 offset:17408
	ds_read_b128 v[210:213], v194 offset:18432
	global_load_lds_dwordx4 v132, s[50:51]
	s_add_i32 m0, s24, 0x2000
	ds_read_b128 v[214:217], v194 offset:19456
	global_load_lds_dwordx4 v136, s[50:51]
	s_barrier
	s_waitcnt lgkmcnt(0)
	v_mfma_f32_16x16x32_bf16 v[112:115], v[202:205], v[162:165], v[112:115]
	v_mfma_f32_16x16x32_bf16 v[108:111], v[210:213], v[162:165], v[108:111]
	v_mfma_f32_16x16x32_bf16 v[96:99], v[202:205], v[170:173], v[96:99]
	v_mfma_f32_16x16x32_bf16 v[92:95], v[210:213], v[170:173], v[92:95]
	v_mfma_f32_16x16x32_bf16 v[80:83], v[202:205], v[178:181], v[80:83]
	v_mfma_f32_16x16x32_bf16 v[76:79], v[210:213], v[178:181], v[76:79]
	v_mfma_f32_16x16x32_bf16 v[72:75], v[202:205], v[186:189], v[72:75]
	v_mfma_f32_16x16x32_bf16 v[68:71], v[210:213], v[186:189], v[68:71]
	v_mfma_f32_16x16x32_bf16 v[112:115], v[206:209], v[166:169], v[112:115]
	v_mfma_f32_16x16x32_bf16 v[108:111], v[214:217], v[166:169], v[108:111]
	v_mfma_f32_16x16x32_bf16 v[96:99], v[206:209], v[174:177], v[96:99]
	v_mfma_f32_16x16x32_bf16 v[92:95], v[214:217], v[174:177], v[92:95]
	v_mfma_f32_16x16x32_bf16 v[80:83], v[206:209], v[182:185], v[80:83]
	v_mfma_f32_16x16x32_bf16 v[76:79], v[214:217], v[182:185], v[76:79]
	v_mfma_f32_16x16x32_bf16 v[72:75], v[206:209], v[190:193], v[72:75]
	v_mfma_f32_16x16x32_bf16 v[68:71], v[214:217], v[190:193], v[68:71]
	s_mov_b32 m0, s54
	s_barrier
	ds_read_b128 v[162:165], v144 offset:16384
	ds_read_b128 v[166:169], v144 offset:17408
	ds_read_b128 v[170:173], v144 offset:18432
	ds_read_b128 v[174:177], v144 offset:19456
	ds_read_b128 v[178:181], v144 offset:20480
	ds_read_b128 v[182:185], v144 offset:21504
	ds_read_b128 v[186:189], v144 offset:22528
	global_load_lds_dwordx4 v0, s[52:53]
	s_mov_b32 m0, s55
	ds_read_b128 v[190:193], v144 offset:23552
	global_load_lds_dwordx4 v134, s[52:53]
	s_barrier
	s_waitcnt lgkmcnt(0)
	v_mfma_f32_16x16x32_bf16 v[64:67], v[146:149], v[162:165], v[64:67]
	v_mfma_f32_16x16x32_bf16 v[60:63], v[154:157], v[162:165], v[60:63]
	v_mfma_f32_16x16x32_bf16 v[56:59], v[146:149], v[170:173], v[56:59]
	v_mfma_f32_16x16x32_bf16 v[52:55], v[154:157], v[170:173], v[52:55]
	v_mfma_f32_16x16x32_bf16 v[40:43], v[146:149], v[178:181], v[40:43]
	v_mfma_f32_16x16x32_bf16 v[36:39], v[154:157], v[178:181], v[36:39]
	v_mfma_f32_16x16x32_bf16 v[24:27], v[146:149], v[186:189], v[24:27]
	v_mfma_f32_16x16x32_bf16 v[16:19], v[154:157], v[186:189], v[16:19]
	v_mfma_f32_16x16x32_bf16 v[64:67], v[150:153], v[166:169], v[64:67]
	v_mfma_f32_16x16x32_bf16 v[60:63], v[158:161], v[166:169], v[60:63]
	v_mfma_f32_16x16x32_bf16 v[56:59], v[150:153], v[174:177], v[56:59]
	v_mfma_f32_16x16x32_bf16 v[52:55], v[158:161], v[174:177], v[52:55]
	v_mfma_f32_16x16x32_bf16 v[40:43], v[150:153], v[182:185], v[40:43]
	v_mfma_f32_16x16x32_bf16 v[36:39], v[158:161], v[182:185], v[36:39]
	v_mfma_f32_16x16x32_bf16 v[24:27], v[150:153], v[190:193], v[24:27]
	v_mfma_f32_16x16x32_bf16 v[16:19], v[158:161], v[190:193], v[16:19]
	s_barrier
	s_add_i32 s23, s23, s37
	s_mov_b32 m0, s23
	s_add_u32 s24, s50, 0x40000
	s_addc_u32 s25, s51, 0
	global_load_lds_dwordx4 v132, s[24:25]
	s_add_i32 m0, s23, 0x2000
	s_waitcnt vmcnt(5)
	global_load_lds_dwordx4 v136, s[24:25]
	s_barrier
	v_mfma_f32_16x16x32_bf16 v[48:51], v[202:205], v[162:165], v[48:51]
	v_mfma_f32_16x16x32_bf16 v[44:47], v[210:213], v[162:165], v[44:47]
	v_mfma_f32_16x16x32_bf16 v[32:35], v[202:205], v[170:173], v[32:35]
	v_mfma_f32_16x16x32_bf16 v[28:31], v[210:213], v[170:173], v[28:31]
	v_mfma_f32_16x16x32_bf16 v[20:23], v[202:205], v[178:181], v[20:23]
	v_mfma_f32_16x16x32_bf16 v[12:15], v[210:213], v[178:181], v[12:15]
	v_mfma_f32_16x16x32_bf16 v[8:11], v[202:205], v[186:189], v[8:11]
	v_mfma_f32_16x16x32_bf16 v[4:7], v[210:213], v[186:189], v[4:7]
	v_mfma_f32_16x16x32_bf16 v[48:51], v[206:209], v[166:169], v[48:51]
	v_mfma_f32_16x16x32_bf16 v[44:47], v[214:217], v[166:169], v[44:47]
	v_mfma_f32_16x16x32_bf16 v[32:35], v[206:209], v[174:177], v[32:35]
	v_mfma_f32_16x16x32_bf16 v[28:31], v[214:217], v[174:177], v[28:31]
	v_mfma_f32_16x16x32_bf16 v[20:23], v[206:209], v[182:185], v[20:23]
	v_mfma_f32_16x16x32_bf16 v[12:15], v[214:217], v[182:185], v[12:15]
	v_mfma_f32_16x16x32_bf16 v[8:11], v[206:209], v[190:193], v[8:11]
	v_mfma_f32_16x16x32_bf16 v[4:7], v[214:217], v[190:193], v[4:7]
	s_add_i32 s23, 0, 0x18000
	s_barrier
	ds_read_b128 v[146:149], v194 offset:32768
	ds_read_b128 v[150:153], v194 offset:33792
	ds_read_b128 v[154:157], v194 offset:34816
	ds_read_b128 v[158:161], v194 offset:35840
	s_add_u32 s24, s52, 0x40000
	s_addc_u32 s25, s53, 0
	s_mov_b32 m0, s56
	ds_read_b128 v[162:165], v144 offset:32768
	ds_read_b128 v[166:169], v144 offset:33792
	ds_read_b128 v[170:173], v144 offset:34816
	ds_read_b128 v[174:177], v144 offset:35840
	ds_read_b128 v[178:181], v144 offset:36864
	ds_read_b128 v[182:185], v144 offset:37888
	ds_read_b128 v[186:189], v144 offset:38912
	global_load_lds_dwordx4 v0, s[24:25]
	s_mov_b32 m0, s57
	ds_read_b128 v[190:193], v144 offset:39936
	global_load_lds_dwordx4 v134, s[24:25]
	s_waitcnt lgkmcnt(8)
	s_barrier
	s_waitcnt lgkmcnt(0)
	v_mfma_f32_16x16x32_bf16 v[128:131], v[146:149], v[162:165], v[128:131]
	v_mfma_f32_16x16x32_bf16 v[124:127], v[154:157], v[162:165], v[124:127]
	v_mfma_f32_16x16x32_bf16 v[120:123], v[146:149], v[170:173], v[120:123]
	v_mfma_f32_16x16x32_bf16 v[116:119], v[154:157], v[170:173], v[116:119]
	v_mfma_f32_16x16x32_bf16 v[104:107], v[146:149], v[178:181], v[104:107]
	v_mfma_f32_16x16x32_bf16 v[100:103], v[154:157], v[178:181], v[100:103]
	v_mfma_f32_16x16x32_bf16 v[88:91], v[146:149], v[186:189], v[88:91]
	v_mfma_f32_16x16x32_bf16 v[84:87], v[154:157], v[186:189], v[84:87]
	v_mfma_f32_16x16x32_bf16 v[128:131], v[150:153], v[166:169], v[128:131]
	v_mfma_f32_16x16x32_bf16 v[124:127], v[158:161], v[166:169], v[124:127]
	v_mfma_f32_16x16x32_bf16 v[120:123], v[150:153], v[174:177], v[120:123]
	v_mfma_f32_16x16x32_bf16 v[116:119], v[158:161], v[174:177], v[116:119]
	v_mfma_f32_16x16x32_bf16 v[104:107], v[150:153], v[182:185], v[104:107]
	v_mfma_f32_16x16x32_bf16 v[100:103], v[158:161], v[182:185], v[100:103]
	v_mfma_f32_16x16x32_bf16 v[88:91], v[150:153], v[190:193], v[88:91]
	v_mfma_f32_16x16x32_bf16 v[84:87], v[158:161], v[190:193], v[84:87]
	s_barrier
	s_add_i32 s26, 0, 0x1c000
	s_add_i32 s23, s23, s37
	s_mov_b32 m0, s23
	ds_read_b128 v[202:205], v194 offset:49152
	ds_read_b128 v[206:209], v194 offset:50176
	ds_read_b128 v[210:213], v194 offset:51200
	s_add_u32 s98, s50, 0x80
	s_addc_u32 s99, s51, 0
	global_load_lds_dwordx4 v132, s[98:99]
	s_add_i32 m0, s23, 0x2000
	ds_read_b128 v[214:217], v194 offset:52224
	global_load_lds_dwordx4 v136, s[98:99]
	s_barrier
	s_waitcnt lgkmcnt(0)
	v_mfma_f32_16x16x32_bf16 v[112:115], v[202:205], v[162:165], v[112:115]
	v_mfma_f32_16x16x32_bf16 v[108:111], v[210:213], v[162:165], v[108:111]
	v_mfma_f32_16x16x32_bf16 v[96:99], v[202:205], v[170:173], v[96:99]
	v_mfma_f32_16x16x32_bf16 v[92:95], v[210:213], v[170:173], v[92:95]
	v_mfma_f32_16x16x32_bf16 v[80:83], v[202:205], v[178:181], v[80:83]
	v_mfma_f32_16x16x32_bf16 v[76:79], v[210:213], v[178:181], v[76:79]
	v_mfma_f32_16x16x32_bf16 v[72:75], v[202:205], v[186:189], v[72:75]
	v_mfma_f32_16x16x32_bf16 v[68:71], v[210:213], v[186:189], v[68:71]
	v_mfma_f32_16x16x32_bf16 v[112:115], v[206:209], v[166:169], v[112:115]
	v_mfma_f32_16x16x32_bf16 v[108:111], v[214:217], v[166:169], v[108:111]
	v_mfma_f32_16x16x32_bf16 v[96:99], v[206:209], v[174:177], v[96:99]
	v_mfma_f32_16x16x32_bf16 v[92:95], v[214:217], v[174:177], v[92:95]
	v_mfma_f32_16x16x32_bf16 v[80:83], v[206:209], v[182:185], v[80:83]
	v_mfma_f32_16x16x32_bf16 v[76:79], v[214:217], v[182:185], v[76:79]
	v_mfma_f32_16x16x32_bf16 v[72:75], v[206:209], v[190:193], v[72:75]
	v_mfma_f32_16x16x32_bf16 v[68:71], v[214:217], v[190:193], v[68:71]
	s_mov_b32 m0, s59
	s_barrier
	ds_read_b128 v[162:165], v144 offset:49152
	ds_read_b128 v[166:169], v144 offset:50176
	ds_read_b128 v[170:173], v144 offset:51200
	ds_read_b128 v[174:177], v144 offset:52224
	ds_read_b128 v[178:181], v144 offset:53248
	ds_read_b128 v[182:185], v144 offset:54272
	ds_read_b128 v[186:189], v144 offset:55296
	s_add_u32 s98, s52, 0x80
	s_addc_u32 s99, s53, 0
	global_load_lds_dwordx4 v0, s[98:99]
	s_mov_b32 m0, s60
	ds_read_b128 v[190:193], v144 offset:56320
	global_load_lds_dwordx4 v134, s[98:99]
	s_barrier
	s_waitcnt lgkmcnt(0)
	v_mfma_f32_16x16x32_bf16 v[64:67], v[146:149], v[162:165], v[64:67]
	v_mfma_f32_16x16x32_bf16 v[60:63], v[154:157], v[162:165], v[60:63]
	v_mfma_f32_16x16x32_bf16 v[56:59], v[146:149], v[170:173], v[56:59]
	v_mfma_f32_16x16x32_bf16 v[52:55], v[154:157], v[170:173], v[52:55]
	v_mfma_f32_16x16x32_bf16 v[40:43], v[146:149], v[178:181], v[40:43]
	v_mfma_f32_16x16x32_bf16 v[36:39], v[154:157], v[178:181], v[36:39]
	v_mfma_f32_16x16x32_bf16 v[24:27], v[146:149], v[186:189], v[24:27]
	v_mfma_f32_16x16x32_bf16 v[16:19], v[154:157], v[186:189], v[16:19]
	v_mfma_f32_16x16x32_bf16 v[64:67], v[150:153], v[166:169], v[64:67]
	v_mfma_f32_16x16x32_bf16 v[60:63], v[158:161], v[166:169], v[60:63]
	v_mfma_f32_16x16x32_bf16 v[56:59], v[150:153], v[174:177], v[56:59]
	v_mfma_f32_16x16x32_bf16 v[52:55], v[158:161], v[174:177], v[52:55]
	v_mfma_f32_16x16x32_bf16 v[40:43], v[150:153], v[182:185], v[40:43]
	v_mfma_f32_16x16x32_bf16 v[36:39], v[158:161], v[182:185], v[36:39]
	v_mfma_f32_16x16x32_bf16 v[24:27], v[150:153], v[190:193], v[24:27]
	v_mfma_f32_16x16x32_bf16 v[16:19], v[158:161], v[190:193], v[16:19]
	s_barrier
	s_add_i32 s23, s26, s37
	s_mov_b32 m0, s23
	s_add_u32 s24, s50, 0x40080
	s_addc_u32 s25, s51, 0
	global_load_lds_dwordx4 v132, s[24:25]
	s_add_i32 m0, s23, 0x2000
	s_waitcnt vmcnt(5)
	global_load_lds_dwordx4 v136, s[24:25]
	s_barrier
	v_mfma_f32_16x16x32_bf16 v[48:51], v[202:205], v[162:165], v[48:51]
	v_mfma_f32_16x16x32_bf16 v[44:47], v[210:213], v[162:165], v[44:47]
	v_mfma_f32_16x16x32_bf16 v[32:35], v[202:205], v[170:173], v[32:35]
	v_mfma_f32_16x16x32_bf16 v[28:31], v[210:213], v[170:173], v[28:31]
	v_mfma_f32_16x16x32_bf16 v[20:23], v[202:205], v[178:181], v[20:23]
	v_mfma_f32_16x16x32_bf16 v[12:15], v[210:213], v[178:181], v[12:15]
	v_mfma_f32_16x16x32_bf16 v[8:11], v[202:205], v[186:189], v[8:11]
	v_mfma_f32_16x16x32_bf16 v[4:7], v[210:213], v[186:189], v[4:7]
	v_mfma_f32_16x16x32_bf16 v[48:51], v[206:209], v[166:169], v[48:51]
	v_mfma_f32_16x16x32_bf16 v[44:47], v[214:217], v[166:169], v[44:47]
	v_mfma_f32_16x16x32_bf16 v[32:35], v[206:209], v[174:177], v[32:35]
	v_mfma_f32_16x16x32_bf16 v[28:31], v[214:217], v[174:177], v[28:31]
	v_mfma_f32_16x16x32_bf16 v[20:23], v[206:209], v[182:185], v[20:23]
	v_mfma_f32_16x16x32_bf16 v[12:15], v[214:217], v[182:185], v[12:15]
	v_mfma_f32_16x16x32_bf16 v[8:11], v[206:209], v[190:193], v[8:11]
	v_mfma_f32_16x16x32_bf16 v[4:7], v[214:217], v[190:193], v[4:7]
	s_add_i32 s22, s22, 2
	s_add_u32 s48, s48, 0x100
	s_addc_u32 s49, s49, 0
	s_add_u32 s20, s20, 0x100
	s_addc_u32 s21, s21, 0
	s_cmp_gt_u32 s22, 13
	s_barrier
	s_cbranch_scc0 .LBB0_136
	v_lshl_add_u32 v146, s0, 8, v142
	v_cvt_pk_bf16_f32 v72, v72, v73
	v_cvt_pk_bf16_f32 v73, v74, v75
	v_cvt_pk_bf16_f32 v74, v68, v69
	v_add_u32_e32 v68, 0x80, v146
	s_lshl_b32 s0, s1, 8
	v_ashrrev_i32_e32 v147, 31, v146
	v_readlane_b32 s20, v252, 12
	v_cvt_pk_bf16_f32 v112, v112, v113
	v_cvt_pk_bf16_f32 v113, v114, v115
	v_cvt_pk_bf16_f32 v114, v108, v109
	v_or_b32_e32 v108, 16, v146
	v_ashrrev_i32_e32 v69, 31, v68
	v_cvt_pk_bf16_f32 v48, v48, v49
	v_cvt_pk_bf16_f32 v49, v50, v51
	v_cvt_pk_bf16_f32 v50, v44, v45
	v_add_u32_e32 v44, 0x90, v146
	s_ashr_i32 s1, s0, 31
	v_lshlrev_b64 v[148:149], 11, v[146:147]
	v_readlane_b32 s21, v252, 13
	v_ashrrev_i32_e32 v109, 31, v108
	v_cvt_pk_bf16_f32 v96, v96, v97
	v_cvt_pk_bf16_f32 v97, v98, v99
	v_cvt_pk_bf16_f32 v98, v92, v93
	v_or_b32_e32 v92, 32, v146
	v_lshlrev_b64 v[68:69], 11, v[68:69]
	v_ashrrev_i32_e32 v45, 31, v44
	v_cvt_pk_bf16_f32 v32, v32, v33
	v_cvt_pk_bf16_f32 v33, v34, v35
	v_cvt_pk_bf16_f32 v34, v28, v29
	v_add_u32_e32 v28, 0xa0, v146
	v_lshl_add_u64 v[148:149], s[20:21], 0, v[148:149]
	s_lshl_b64 s[0:1], s[0:1], 1
	v_lshlrev_b64 v[108:109], 11, v[108:109]
	v_ashrrev_i32_e32 v93, 31, v92
	v_cvt_pk_bf16_f32 v80, v80, v81
	v_cvt_pk_bf16_f32 v81, v82, v83
	v_cvt_pk_bf16_f32 v82, v76, v77
	v_or_b32_e32 v76, 48, v146
	v_lshl_add_u64 v[68:69], s[20:21], 0, v[68:69]
	v_lshlrev_b64 v[44:45], 11, v[44:45]
	v_ashrrev_i32_e32 v29, 31, v28
	v_cvt_pk_bf16_f32 v20, v20, v21
	v_cvt_pk_bf16_f32 v21, v22, v23
	v_cvt_pk_bf16_f32 v22, v12, v13
	v_add_u32_e32 v12, 0xb0, v146
	v_lshl_add_u64 v[148:149], v[148:149], 0, s[0:1]
	v_lshl_add_u64 v[108:109], s[20:21], 0, v[108:109]
	v_lshlrev_b64 v[92:93], 11, v[92:93]
	v_ashrrev_i32_e32 v77, 31, v76
	v_lshl_add_u64 v[68:69], v[68:69], 0, s[0:1]
	v_lshl_add_u64 v[44:45], s[20:21], 0, v[44:45]
	v_lshlrev_b64 v[28:29], 11, v[28:29]
	v_ashrrev_i32_e32 v13, 31, v12
	v_lshl_add_u64 v[148:149], v[148:149], 0, s[72:73]
	v_lshl_add_u64 v[108:109], v[108:109], 0, s[0:1]
	v_lshl_add_u64 v[92:93], s[20:21], 0, v[92:93]
	v_lshlrev_b64 v[76:77], 11, v[76:77]
	v_lshl_add_u64 v[68:69], v[68:69], 0, s[72:73]
	v_lshl_add_u64 v[44:45], v[44:45], 0, s[0:1]
	v_lshl_add_u64 v[28:29], s[20:21], 0, v[28:29]
	v_lshlrev_b64 v[12:13], 11, v[12:13]
	v_lshl_add_u64 v[148:149], v[148:149], 0, v[2:3]
	v_cvt_pk_bf16_f32 v115, v110, v111
	v_lshl_add_u64 v[108:109], v[108:109], 0, s[72:73]
	v_lshl_add_u64 v[92:93], v[92:93], 0, s[0:1]
	v_lshl_add_u64 v[76:77], s[20:21], 0, v[76:77]
	v_lshl_add_u64 v[68:69], v[68:69], 0, v[2:3]
	v_cvt_pk_bf16_f32 v51, v46, v47
	v_lshl_add_u64 v[44:45], v[44:45], 0, s[72:73]
	v_lshl_add_u64 v[28:29], v[28:29], 0, s[0:1]
	v_lshl_add_u64 v[12:13], s[20:21], 0, v[12:13]
	global_store_dwordx4 v[148:149], v[112:115], off offset:256
	v_cvt_pk_bf16_f32 v99, v94, v95
	v_lshl_add_u64 v[92:93], v[92:93], 0, s[72:73]
	v_lshl_add_u64 v[112:113], v[108:109], 0, v[2:3]
	v_lshl_add_u64 v[76:77], v[76:77], 0, s[0:1]
	global_store_dwordx4 v[68:69], v[48:51], off offset:256
	v_cvt_pk_bf16_f32 v35, v30, v31
	v_lshl_add_u64 v[28:29], v[28:29], 0, s[72:73]
	v_lshl_add_u64 v[48:49], v[44:45], 0, v[2:3]
	v_lshl_add_u64 v[12:13], v[12:13], 0, s[0:1]
	global_store_dwordx4 v[112:113], v[96:99], off offset:256
	v_cvt_pk_bf16_f32 v83, v78, v79
	v_lshl_add_u64 v[76:77], v[76:77], 0, s[72:73]
	v_lshl_add_u64 v[96:97], v[92:93], 0, v[2:3]
	global_store_dwordx4 v[48:49], v[32:35], off offset:256
	v_cvt_pk_bf16_f32 v23, v14, v15
	v_lshl_add_u64 v[12:13], v[12:13], 0, s[72:73]
	v_lshl_add_u64 v[32:33], v[28:29], 0, v[2:3]
	v_cvt_pk_bf16_f32 v128, v128, v129
	v_cvt_pk_bf16_f32 v129, v130, v131
	v_cvt_pk_bf16_f32 v130, v124, v125
	v_cvt_pk_bf16_f32 v131, v126, v127
	v_cvt_pk_bf16_f32 v108, v120, v121
	v_cvt_pk_bf16_f32 v109, v122, v123
	v_cvt_pk_bf16_f32 v110, v116, v117
	v_cvt_pk_bf16_f32 v111, v118, v119
	v_cvt_pk_bf16_f32 v92, v104, v105
	v_cvt_pk_bf16_f32 v93, v106, v107
	v_cvt_pk_bf16_f32 v94, v100, v101
	v_cvt_pk_bf16_f32 v95, v102, v103
	global_store_dwordx4 v[96:97], v[80:83], off offset:256
	v_cvt_pk_bf16_f32 v78, v84, v85
	v_cvt_pk_bf16_f32 v79, v86, v87
	v_lshl_add_u64 v[80:81], v[76:77], 0, v[2:3]
	v_cvt_pk_bf16_f32 v76, v88, v89
	v_cvt_pk_bf16_f32 v77, v90, v91
	v_cvt_pk_bf16_f32 v75, v70, v71
	v_cvt_pk_bf16_f32 v64, v64, v65
	v_cvt_pk_bf16_f32 v65, v66, v67
	v_cvt_pk_bf16_f32 v66, v60, v61
	v_cvt_pk_bf16_f32 v67, v62, v63
	v_cvt_pk_bf16_f32 v44, v56, v57
	v_cvt_pk_bf16_f32 v45, v58, v59
	v_cvt_pk_bf16_f32 v46, v52, v53
	v_cvt_pk_bf16_f32 v47, v54, v55
	v_cvt_pk_bf16_f32 v28, v40, v41
	v_cvt_pk_bf16_f32 v29, v42, v43
	v_cvt_pk_bf16_f32 v30, v36, v37
	v_cvt_pk_bf16_f32 v31, v38, v39
	global_store_dwordx4 v[32:33], v[20:23], off offset:256
	v_cvt_pk_bf16_f32 v14, v16, v17
	v_cvt_pk_bf16_f32 v15, v18, v19
	v_lshl_add_u64 v[20:21], v[12:13], 0, v[2:3]
	v_cvt_pk_bf16_f32 v12, v24, v25
	v_cvt_pk_bf16_f32 v13, v26, v27
	v_cvt_pk_bf16_f32 v8, v8, v9
	v_cvt_pk_bf16_f32 v9, v10, v11
	v_cvt_pk_bf16_f32 v10, v4, v5
	v_cvt_pk_bf16_f32 v11, v6, v7
	s_and_b64 vcc, exec, s[38:39]
	s_mov_b32 s1, s40
	s_mov_b32 s0, s42
	s_mov_b64 s[50:51], s[46:47]
	s_mov_b64 s[48:49], s[44:45]
	global_store_dwordx4 v[148:149], v[128:131], off
	global_store_dwordx4 v[112:113], v[108:111], off
	global_store_dwordx4 v[96:97], v[92:95], off
	global_store_dwordx4 v[80:81], v[76:79], off
	global_store_dwordx4 v[80:81], v[72:75], off offset:256
	global_store_dwordx4 v[68:69], v[64:67], off
	global_store_dwordx4 v[48:49], v[44:47], off
	global_store_dwordx4 v[32:33], v[28:31], off
	global_store_dwordx4 v[20:21], v[12:15], off
	global_store_dwordx4 v[20:21], v[8:11], off offset:256
	s_cbranch_vccz .LBB0_129
	s_waitcnt vmcnt(0)
	s_cmpk_gt_u32 s31, 0xff
	s_cbranch_scc1 .LBB0_140
	s_barrier

.LBB0_174:
	s_add_i32 s23, s22, -2
	v_mov_b64_e32 v[0:1], 0x200
	s_add_u32 s24, s44, 0x100
	v_cmp_lt_i64_e64 s[38:39], s[38:39], v[0:1]
	s_addc_u32 s25, s45, 0
	s_mov_b32 s27, 0
	v_add_u32_e32 v1, 0x10000, v157
.LBB0_175:
	s_add_i32 s26, s27, 2
	s_add_u32 s44, s40, 0x100
	s_addc_u32 s45, s41, 0
	s_add_i32 s30, 0, 0x10000
	ds_read_b128 v[132:135], v1
	ds_read_b128 v[164:167], v1 offset:1024
	ds_read_b128 v[168:171], v1 offset:2048
	ds_read_b128 v[174:177], v1 offset:3072
	s_cmp_eq_u32 s23, s27
	s_cselect_b32 s49, s1, s45
	s_cselect_b32 s48, s0, s44
	s_cselect_b32 s47, s43, s25
	s_cselect_b32 s46, s42, s24
	s_add_i32 m0, s53, 0xc000
	ds_read_b128 v[178:181], v172
	ds_read_b128 v[182:185], v172 offset:1024
	ds_read_b128 v[186:189], v172 offset:2048
	ds_read_b128 v[190:193], v172 offset:3072
	ds_read_b128 v[202:205], v172 offset:4096
	ds_read_b128 v[206:209], v172 offset:5120
	ds_read_b128 v[210:213], v172 offset:6144
	global_load_lds_dwordx4 v160, s[40:41]
	s_add_i32 m0, s53, 0xe000
	ds_read_b128 v[214:217], v172 offset:7168
	global_load_lds_dwordx4 v162, s[40:41]
	s_waitcnt lgkmcnt(8)
	s_barrier
	s_waitcnt lgkmcnt(0)
	v_mfma_f32_16x16x32_bf16 v[4:7], v[132:135], v[178:181], v[4:7]
	v_mfma_f32_16x16x32_bf16 v[8:11], v[168:171], v[178:181], v[8:11]
	v_mfma_f32_16x16x32_bf16 v[128:131], v[132:135], v[186:189], v[128:131]
	v_mfma_f32_16x16x32_bf16 v[124:127], v[168:171], v[186:189], v[124:127]
	v_mfma_f32_16x16x32_bf16 v[120:123], v[132:135], v[202:205], v[120:123]
	v_mfma_f32_16x16x32_bf16 v[116:119], v[168:171], v[202:205], v[116:119]
	v_mfma_f32_16x16x32_bf16 v[112:115], v[132:135], v[210:213], v[112:115]
	v_mfma_f32_16x16x32_bf16 v[108:111], v[168:171], v[210:213], v[108:111]
	v_mfma_f32_16x16x32_bf16 v[4:7], v[164:167], v[182:185], v[4:7]
	v_mfma_f32_16x16x32_bf16 v[8:11], v[174:177], v[182:185], v[8:11]
	v_mfma_f32_16x16x32_bf16 v[128:131], v[164:167], v[190:193], v[128:131]
	v_mfma_f32_16x16x32_bf16 v[124:127], v[174:177], v[190:193], v[124:127]
	v_mfma_f32_16x16x32_bf16 v[120:123], v[164:167], v[206:209], v[120:123]
	v_mfma_f32_16x16x32_bf16 v[116:119], v[174:177], v[206:209], v[116:119]
	v_mfma_f32_16x16x32_bf16 v[112:115], v[164:167], v[214:217], v[112:115]
	v_mfma_f32_16x16x32_bf16 v[108:111], v[174:177], v[214:217], v[108:111]
	s_barrier
	s_add_i32 s27, 0, 0x14000
	s_add_i32 s30, s30, s52
	ds_read_b128 v[236:239], v1 offset:16384
	ds_read_b128 v[240:243], v1 offset:17408
	s_mov_b32 m0, s30
	ds_read_b128 v[244:247], v1 offset:18432
	global_load_lds_dwordx4 v138, s[46:47]
	s_add_i32 m0, s30, 0x2000
	ds_read_b128 v[248:251], v1 offset:19456
	global_load_lds_dwordx4 v142, s[46:47]
	s_barrier
	s_waitcnt lgkmcnt(0)
	v_mfma_f32_16x16x32_bf16 v[12:15], v[236:239], v[178:181], v[12:15]
	v_mfma_f32_16x16x32_bf16 v[16:19], v[244:247], v[178:181], v[16:19]
	v_mfma_f32_16x16x32_bf16 v[104:107], v[236:239], v[186:189], v[104:107]
	v_mfma_f32_16x16x32_bf16 v[100:103], v[244:247], v[186:189], v[100:103]
	v_mfma_f32_16x16x32_bf16 v[96:99], v[236:239], v[202:205], v[96:99]
	v_mfma_f32_16x16x32_bf16 v[92:95], v[244:247], v[202:205], v[92:95]
	v_mfma_f32_16x16x32_bf16 v[88:91], v[236:239], v[210:213], v[88:91]
	v_mfma_f32_16x16x32_bf16 v[84:87], v[244:247], v[210:213], v[84:87]
	v_mfma_f32_16x16x32_bf16 v[12:15], v[240:243], v[182:185], v[12:15]
	v_mfma_f32_16x16x32_bf16 v[16:19], v[248:251], v[182:185], v[16:19]
	v_mfma_f32_16x16x32_bf16 v[104:107], v[240:243], v[190:193], v[104:107]
	v_mfma_f32_16x16x32_bf16 v[100:103], v[248:251], v[190:193], v[100:103]
	v_mfma_f32_16x16x32_bf16 v[96:99], v[240:243], v[206:209], v[96:99]
	v_mfma_f32_16x16x32_bf16 v[92:95], v[248:251], v[206:209], v[92:95]
	v_mfma_f32_16x16x32_bf16 v[88:91], v[240:243], v[214:217], v[88:91]
	v_mfma_f32_16x16x32_bf16 v[84:87], v[248:251], v[214:217], v[84:87]
	s_mov_b32 m0, s53
	s_barrier
	ds_read_b128 v[178:181], v172 offset:16384
	ds_read_b128 v[182:185], v172 offset:17408
	ds_read_b128 v[186:189], v172 offset:18432
	ds_read_b128 v[190:193], v172 offset:19456
	ds_read_b128 v[202:205], v172 offset:20480
	ds_read_b128 v[206:209], v172 offset:21504
	ds_read_b128 v[210:213], v172 offset:22528
	global_load_lds_dwordx4 v136, s[48:49]
	s_mov_b32 m0, s54
	ds_read_b128 v[214:217], v172 offset:23552
	global_load_lds_dwordx4 v140, s[48:49]
	s_barrier
	s_waitcnt lgkmcnt(0)
	v_mfma_f32_16x16x32_bf16 v[80:83], v[132:135], v[178:181], v[80:83]
	v_mfma_f32_16x16x32_bf16 v[76:79], v[168:171], v[178:181], v[76:79]
	v_mfma_f32_16x16x32_bf16 v[72:75], v[132:135], v[186:189], v[72:75]
	v_mfma_f32_16x16x32_bf16 v[68:71], v[168:171], v[186:189], v[68:71]
	v_mfma_f32_16x16x32_bf16 v[64:67], v[132:135], v[202:205], v[64:67]
	v_mfma_f32_16x16x32_bf16 v[60:63], v[168:171], v[202:205], v[60:63]
	v_mfma_f32_16x16x32_bf16 v[56:59], v[132:135], v[210:213], v[56:59]
	v_mfma_f32_16x16x32_bf16 v[52:55], v[168:171], v[210:213], v[52:55]
	v_mfma_f32_16x16x32_bf16 v[80:83], v[164:167], v[182:185], v[80:83]
	v_mfma_f32_16x16x32_bf16 v[76:79], v[174:177], v[182:185], v[76:79]
	v_mfma_f32_16x16x32_bf16 v[72:75], v[164:167], v[190:193], v[72:75]
	v_mfma_f32_16x16x32_bf16 v[68:71], v[174:177], v[190:193], v[68:71]
	v_mfma_f32_16x16x32_bf16 v[64:67], v[164:167], v[206:209], v[64:67]
	v_mfma_f32_16x16x32_bf16 v[60:63], v[174:177], v[206:209], v[60:63]
	v_mfma_f32_16x16x32_bf16 v[56:59], v[164:167], v[214:217], v[56:59]
	v_mfma_f32_16x16x32_bf16 v[52:55], v[174:177], v[214:217], v[52:55]
	s_barrier
	s_add_i32 s27, s27, s52
	s_mov_b32 m0, s27
	s_add_u32 s30, s46, 0xc0000
	s_addc_u32 s31, s47, 0
	global_load_lds_dwordx4 v138, s[30:31]
	s_add_i32 m0, s27, 0x2000
	s_waitcnt vmcnt(5)
	global_load_lds_dwordx4 v142, s[30:31]
	s_barrier
	v_mfma_f32_16x16x32_bf16 v[48:51], v[236:239], v[178:181], v[48:51]
	v_mfma_f32_16x16x32_bf16 v[44:47], v[244:247], v[178:181], v[44:47]
	v_mfma_f32_16x16x32_bf16 v[40:43], v[236:239], v[186:189], v[40:43]
	v_mfma_f32_16x16x32_bf16 v[36:39], v[244:247], v[186:189], v[36:39]
	v_mfma_f32_16x16x32_bf16 v[32:35], v[236:239], v[202:205], v[32:35]
	v_mfma_f32_16x16x32_bf16 v[28:31], v[244:247], v[202:205], v[28:31]
	v_mfma_f32_16x16x32_bf16 v[24:27], v[236:239], v[210:213], v[24:27]
	v_mfma_f32_16x16x32_bf16 v[20:23], v[244:247], v[210:213], v[20:23]
	v_mfma_f32_16x16x32_bf16 v[48:51], v[240:243], v[182:185], v[48:51]
	v_mfma_f32_16x16x32_bf16 v[44:47], v[248:251], v[182:185], v[44:47]
	v_mfma_f32_16x16x32_bf16 v[40:43], v[240:243], v[190:193], v[40:43]
	v_mfma_f32_16x16x32_bf16 v[36:39], v[248:251], v[190:193], v[36:39]
	v_mfma_f32_16x16x32_bf16 v[32:35], v[240:243], v[206:209], v[32:35]
	v_mfma_f32_16x16x32_bf16 v[28:31], v[248:251], v[206:209], v[28:31]
	v_mfma_f32_16x16x32_bf16 v[24:27], v[240:243], v[214:217], v[24:27]
	v_mfma_f32_16x16x32_bf16 v[20:23], v[248:251], v[214:217], v[20:23]
	s_add_i32 s27, 0, 0x18000
	s_barrier
	ds_read_b128 v[132:135], v1 offset:32768
	ds_read_b128 v[164:167], v1 offset:33792
	ds_read_b128 v[168:171], v1 offset:34816
	ds_read_b128 v[174:177], v1 offset:35840
	s_add_u32 s30, s48, 0x1a0000
	s_addc_u32 s31, s49, 0
	s_mov_b32 m0, s55
	ds_read_b128 v[178:181], v172 offset:32768
	ds_read_b128 v[182:185], v172 offset:33792
	ds_read_b128 v[186:189], v172 offset:34816
	ds_read_b128 v[190:193], v172 offset:35840
	ds_read_b128 v[202:205], v172 offset:36864
	ds_read_b128 v[206:209], v172 offset:37888
	ds_read_b128 v[210:213], v172 offset:38912
	global_load_lds_dwordx4 v136, s[30:31]
	s_mov_b32 m0, s56
	ds_read_b128 v[214:217], v172 offset:39936
	global_load_lds_dwordx4 v140, s[30:31]
	s_waitcnt lgkmcnt(8)
	s_barrier
	s_waitcnt lgkmcnt(0)
	v_mfma_f32_16x16x32_bf16 v[4:7], v[132:135], v[178:181], v[4:7]
	v_mfma_f32_16x16x32_bf16 v[8:11], v[168:171], v[178:181], v[8:11]
	v_mfma_f32_16x16x32_bf16 v[128:131], v[132:135], v[186:189], v[128:131]
	v_mfma_f32_16x16x32_bf16 v[124:127], v[168:171], v[186:189], v[124:127]
	v_mfma_f32_16x16x32_bf16 v[120:123], v[132:135], v[202:205], v[120:123]
	v_mfma_f32_16x16x32_bf16 v[116:119], v[168:171], v[202:205], v[116:119]
	v_mfma_f32_16x16x32_bf16 v[112:115], v[132:135], v[210:213], v[112:115]
	v_mfma_f32_16x16x32_bf16 v[108:111], v[168:171], v[210:213], v[108:111]
	v_mfma_f32_16x16x32_bf16 v[4:7], v[164:167], v[182:185], v[4:7]
	v_mfma_f32_16x16x32_bf16 v[8:11], v[174:177], v[182:185], v[8:11]
	v_mfma_f32_16x16x32_bf16 v[128:131], v[164:167], v[190:193], v[128:131]
	v_mfma_f32_16x16x32_bf16 v[124:127], v[174:177], v[190:193], v[124:127]
	v_mfma_f32_16x16x32_bf16 v[120:123], v[164:167], v[206:209], v[120:123]
	v_mfma_f32_16x16x32_bf16 v[116:119], v[174:177], v[206:209], v[116:119]
	v_mfma_f32_16x16x32_bf16 v[112:115], v[164:167], v[214:217], v[112:115]
	v_mfma_f32_16x16x32_bf16 v[108:111], v[174:177], v[214:217], v[108:111]
	s_barrier
	s_add_i32 s36, 0, 0x1c000
	s_add_i32 s27, s27, s52
	s_mov_b32 m0, s27
	ds_read_b128 v[236:239], v1 offset:49152
	ds_read_b128 v[240:243], v1 offset:50176
	ds_read_b128 v[244:247], v1 offset:51200
	s_add_u32 s98, s46, 0x80
	s_addc_u32 s99, s47, 0
	global_load_lds_dwordx4 v138, s[98:99]
	s_add_i32 m0, s27, 0x2000
	ds_read_b128 v[248:251], v1 offset:52224
	global_load_lds_dwordx4 v142, s[98:99]
	s_barrier
	s_waitcnt lgkmcnt(0)
	v_mfma_f32_16x16x32_bf16 v[12:15], v[236:239], v[178:181], v[12:15]
	v_mfma_f32_16x16x32_bf16 v[16:19], v[244:247], v[178:181], v[16:19]
	v_mfma_f32_16x16x32_bf16 v[104:107], v[236:239], v[186:189], v[104:107]
	v_mfma_f32_16x16x32_bf16 v[100:103], v[244:247], v[186:189], v[100:103]
	v_mfma_f32_16x16x32_bf16 v[96:99], v[236:239], v[202:205], v[96:99]
	v_mfma_f32_16x16x32_bf16 v[92:95], v[244:247], v[202:205], v[92:95]
	v_mfma_f32_16x16x32_bf16 v[88:91], v[236:239], v[210:213], v[88:91]
	v_mfma_f32_16x16x32_bf16 v[84:87], v[244:247], v[210:213], v[84:87]
	v_mfma_f32_16x16x32_bf16 v[12:15], v[240:243], v[182:185], v[12:15]
	v_mfma_f32_16x16x32_bf16 v[16:19], v[248:251], v[182:185], v[16:19]
	v_mfma_f32_16x16x32_bf16 v[104:107], v[240:243], v[190:193], v[104:107]
	v_mfma_f32_16x16x32_bf16 v[100:103], v[248:251], v[190:193], v[100:103]
	v_mfma_f32_16x16x32_bf16 v[96:99], v[240:243], v[206:209], v[96:99]
	v_mfma_f32_16x16x32_bf16 v[92:95], v[248:251], v[206:209], v[92:95]
	v_mfma_f32_16x16x32_bf16 v[88:91], v[240:243], v[214:217], v[88:91]
	v_mfma_f32_16x16x32_bf16 v[84:87], v[248:251], v[214:217], v[84:87]
	s_mov_b32 m0, s59
	s_barrier
	ds_read_b128 v[178:181], v172 offset:49152
	ds_read_b128 v[182:185], v172 offset:50176
	ds_read_b128 v[186:189], v172 offset:51200
	ds_read_b128 v[190:193], v172 offset:52224
	ds_read_b128 v[202:205], v172 offset:53248
	ds_read_b128 v[206:209], v172 offset:54272
	ds_read_b128 v[210:213], v172 offset:55296
	s_add_u32 s98, s48, 0x80
	s_addc_u32 s99, s49, 0
	global_load_lds_dwordx4 v136, s[98:99]
	s_mov_b32 m0, s60
	ds_read_b128 v[214:217], v172 offset:56320
	global_load_lds_dwordx4 v140, s[98:99]
	s_barrier
	s_waitcnt lgkmcnt(0)
	v_mfma_f32_16x16x32_bf16 v[80:83], v[132:135], v[178:181], v[80:83]
	v_mfma_f32_16x16x32_bf16 v[76:79], v[168:171], v[178:181], v[76:79]
	v_mfma_f32_16x16x32_bf16 v[72:75], v[132:135], v[186:189], v[72:75]
	v_mfma_f32_16x16x32_bf16 v[68:71], v[168:171], v[186:189], v[68:71]
	v_mfma_f32_16x16x32_bf16 v[64:67], v[132:135], v[202:205], v[64:67]
	v_mfma_f32_16x16x32_bf16 v[60:63], v[168:171], v[202:205], v[60:63]
	v_mfma_f32_16x16x32_bf16 v[56:59], v[132:135], v[210:213], v[56:59]
	v_mfma_f32_16x16x32_bf16 v[52:55], v[168:171], v[210:213], v[52:55]
	v_mfma_f32_16x16x32_bf16 v[80:83], v[164:167], v[182:185], v[80:83]
	v_mfma_f32_16x16x32_bf16 v[76:79], v[174:177], v[182:185], v[76:79]
	v_mfma_f32_16x16x32_bf16 v[72:75], v[164:167], v[190:193], v[72:75]
	v_mfma_f32_16x16x32_bf16 v[68:71], v[174:177], v[190:193], v[68:71]
	v_mfma_f32_16x16x32_bf16 v[64:67], v[164:167], v[206:209], v[64:67]
	v_mfma_f32_16x16x32_bf16 v[60:63], v[174:177], v[206:209], v[60:63]
	v_mfma_f32_16x16x32_bf16 v[56:59], v[164:167], v[214:217], v[56:59]
	v_mfma_f32_16x16x32_bf16 v[52:55], v[174:177], v[214:217], v[52:55]
	s_barrier
	s_add_i32 s27, s36, s52
	s_mov_b32 m0, s27
	s_add_u32 s30, s46, 0xc0080
	s_addc_u32 s31, s47, 0
	global_load_lds_dwordx4 v138, s[30:31]
	s_add_i32 m0, s27, 0x2000
	s_waitcnt vmcnt(5)
	global_load_lds_dwordx4 v142, s[30:31]
	s_barrier
	v_mfma_f32_16x16x32_bf16 v[48:51], v[236:239], v[178:181], v[48:51]
	v_mfma_f32_16x16x32_bf16 v[44:47], v[244:247], v[178:181], v[44:47]
	v_mfma_f32_16x16x32_bf16 v[40:43], v[236:239], v[186:189], v[40:43]
	v_mfma_f32_16x16x32_bf16 v[36:39], v[244:247], v[186:189], v[36:39]
	v_mfma_f32_16x16x32_bf16 v[32:35], v[236:239], v[202:205], v[32:35]
	v_mfma_f32_16x16x32_bf16 v[28:31], v[244:247], v[202:205], v[28:31]
	v_mfma_f32_16x16x32_bf16 v[24:27], v[236:239], v[210:213], v[24:27]
	v_mfma_f32_16x16x32_bf16 v[20:23], v[244:247], v[210:213], v[20:23]
	v_mfma_f32_16x16x32_bf16 v[48:51], v[240:243], v[182:185], v[48:51]
	v_mfma_f32_16x16x32_bf16 v[44:47], v[248:251], v[182:185], v[44:47]
	v_mfma_f32_16x16x32_bf16 v[40:43], v[240:243], v[190:193], v[40:43]
	v_mfma_f32_16x16x32_bf16 v[36:39], v[248:251], v[190:193], v[36:39]
	v_mfma_f32_16x16x32_bf16 v[32:35], v[240:243], v[206:209], v[32:35]
	v_mfma_f32_16x16x32_bf16 v[28:31], v[248:251], v[206:209], v[28:31]
	v_mfma_f32_16x16x32_bf16 v[24:27], v[240:243], v[214:217], v[24:27]
	v_mfma_f32_16x16x32_bf16 v[20:23], v[248:251], v[214:217], v[20:23]
	s_add_u32 s24, s24, 0x100
	s_addc_u32 s25, s25, 0
	s_cmp_ge_i32 s26, s22
	s_mov_b64 s[40:41], s[44:45]
	s_mov_b32 s27, s26
	s_barrier
	s_cbranch_scc0 .LBB0_175
	s_lshl_b32 s46, s66, 8
	v_lshl_or_b32 v0, s20, 8, v159
	s_mov_b32 s44, 0xbfb8aa3b
	s_mov_b32 s45, 0xbfb8aa3b
	v_lshlrev_b32_e32 v0, 1, v0
	v_add_u32_e32 v0, 0x1000, v0
	s_cmp_lg_u32 s21, 1
	s_cbranch_scc0 .Lg2_kind1
	v_readlane_b32 s22, v252, 34
	v_readlane_b32 s23, v252, 35
	v_add_u32_e32 v2, s46, v144
	v_mad_u32_u24 v2, v2, s29, v0
	global_load_dwordx4 v[132:135], v2, s[96:97] offset:2048
	v_add_u32_e32 v2, s46, v144
	v_mad_u32_u24 v2, v2, s29, v0
	global_load_dwordx4 v[178:181], v2, s[96:97] offset:2304
	v_add_u32_e32 v2, s46, v146
	v_mad_u32_u24 v2, v2, s29, v0
	global_load_dwordx4 v[182:185], v2, s[96:97] offset:2048
	v_add_u32_e32 v2, s46, v146
	v_mad_u32_u24 v2, v2, s29, v0
	global_load_dwordx4 v[186:189], v2, s[96:97] offset:2304
	v_add_u32_e32 v2, s46, v148
	v_mad_u32_u24 v2, v2, s29, v0
	global_load_dwordx4 v[190:193], v2, s[96:97] offset:2048
	v_add_u32_e32 v2, s46, v148
	v_mad_u32_u24 v2, v2, s29, v0
	global_load_dwordx4 v[202:205], v2, s[96:97] offset:2304
	v_add_u32_e32 v2, s46, v150
	v_mad_u32_u24 v2, v2, s29, v0
	global_load_dwordx4 v[206:209], v2, s[96:97] offset:2048
	v_add_u32_e32 v2, s46, v150
	v_mad_u32_u24 v2, v2, s29, v0
	global_load_dwordx4 v[210:213], v2, s[96:97] offset:2304
	v_add_u32_e32 v2, s46, v152
	v_mad_u32_u24 v2, v2, s29, v0
	global_load_dwordx4 v[214:217], v2, s[96:97] offset:2048
	v_add_u32_e32 v2, s46, v152
	v_mad_u32_u24 v2, v2, s29, v0
	global_load_dwordx4 v[236:239], v2, s[96:97] offset:2304
	v_add_u32_e32 v2, s46, v154
	v_mad_u32_u24 v2, v2, s29, v0
	global_load_dwordx4 v[240:243], v2, s[96:97] offset:2048
	v_add_u32_e32 v2, s46, v154
	v_mad_u32_u24 v2, v2, s29, v0
	global_load_dwordx4 v[244:247], v2, s[96:97] offset:2304
	v_add_u32_e32 v2, s46, v156
	v_mad_u32_u24 v2, v2, s29, v0
	global_load_dwordx4 v[248:251], v2, s[96:97] offset:2048
	s_waitcnt vmcnt(12)
	v_lshlrev_b32_e32 v164, 16, v132
	v_and_b32_e32 v165, 0xffff0000, v132
	v_lshlrev_b32_e32 v166, 16, v133
	v_and_b32_e32 v167, 0xffff0000, v133
	v_lshlrev_b32_e32 v168, 16, v134
	v_and_b32_e32 v169, 0xffff0000, v134
	v_lshlrev_b32_e32 v170, 16, v135
	v_and_b32_e32 v171, 0xffff0000, v135
	v_add_u32_e32 v2, s46, v156
	v_mad_u32_u24 v2, v2, s29, v0
	global_load_dwordx4 v[132:135], v2, s[96:97] offset:2304
	v_add_u32_e32 v1, s46, v144
	v_lshl_add_u32 v1, v1, 11, v0
	v_med3_f32 v164, v164, s34, v227
	v_med3_f32 v165, v165, s34, v227
	v_med3_f32 v166, v166, s34, v227
	v_med3_f32 v167, v167, s34, v227
	v_med3_f32 v168, v168, s34, v227
	v_med3_f32 v169, v169, s34, v227
	v_med3_f32 v170, v170, s34, v227
	v_med3_f32 v171, v171, s34, v227
	v_pk_mul_f32 v[164:165], v[164:165], s[44:45]
	v_pk_mul_f32 v[166:167], v[166:167], s[44:45]
	v_pk_mul_f32 v[168:169], v[168:169], s[44:45]
	v_pk_mul_f32 v[170:171], v[170:171], s[44:45]
	v_exp_f32_e32 v164, v164
	v_exp_f32_e32 v165, v165
	v_exp_f32_e32 v166, v166
	v_exp_f32_e32 v167, v167
	v_exp_f32_e32 v168, v168
	v_exp_f32_e32 v169, v169
	v_exp_f32_e32 v170, v170
	v_exp_f32_e32 v171, v171
	v_pk_add_f32 v[164:165], v[164:165], 1.0 op_sel_hi:[1,0]
	v_pk_add_f32 v[166:167], v[166:167], 1.0 op_sel_hi:[1,0]
	v_pk_add_f32 v[168:169], v[168:169], 1.0 op_sel_hi:[1,0]
	v_pk_add_f32 v[170:171], v[170:171], 1.0 op_sel_hi:[1,0]
	v_rcp_f32_e32 v164, v164
	v_rcp_f32_e32 v165, v165
	v_rcp_f32_e32 v166, v166
	v_rcp_f32_e32 v167, v167
	v_rcp_f32_e32 v168, v168
	v_rcp_f32_e32 v169, v169
	v_rcp_f32_e32 v170, v170
	v_rcp_f32_e32 v171, v171
	v_pk_mul_f32 v[164:165], v[4:5], v[164:165]
	v_pk_mul_f32 v[166:167], v[6:7], v[166:167]
	v_pk_mul_f32 v[168:169], v[8:9], v[168:169]
	v_pk_mul_f32 v[170:171], v[10:11], v[170:171]
	v_cvt_pk_bf16_f32 v174, v164, v165
	v_cvt_pk_bf16_f32 v175, v166, v167
	v_cvt_pk_bf16_f32 v176, v168, v169
	v_cvt_pk_bf16_f32 v177, v170, v171
	global_store_dwordx4 v1, v[174:177], s[22:23] offset:-4096
	s_waitcnt vmcnt(13)
	v_lshlrev_b32_e32 v164, 16, v178
	v_and_b32_e32 v165, 0xffff0000, v178
	v_lshlrev_b32_e32 v166, 16, v179
	v_and_b32_e32 v167, 0xffff0000, v179
	v_lshlrev_b32_e32 v168, 16, v180
	v_and_b32_e32 v169, 0xffff0000, v180
	v_lshlrev_b32_e32 v170, 16, v181
	v_and_b32_e32 v171, 0xffff0000, v181
	v_add_u32_e32 v2, s46, v158
	v_mad_u32_u24 v2, v2, s29, v0
	global_load_dwordx4 v[178:181], v2, s[96:97] offset:2048
	v_med3_f32 v164, v164, s34, v227
	v_med3_f32 v165, v165, s34, v227
	v_med3_f32 v166, v166, s34, v227
	v_med3_f32 v167, v167, s34, v227
	v_med3_f32 v168, v168, s34, v227
	v_med3_f32 v169, v169, s34, v227
	v_med3_f32 v170, v170, s34, v227
	v_med3_f32 v171, v171, s34, v227
	v_pk_mul_f32 v[164:165], v[164:165], s[44:45]
	v_pk_mul_f32 v[166:167], v[166:167], s[44:45]
	v_pk_mul_f32 v[168:169], v[168:169], s[44:45]
	v_pk_mul_f32 v[170:171], v[170:171], s[44:45]
	v_exp_f32_e32 v164, v164
	v_exp_f32_e32 v165, v165
	v_exp_f32_e32 v166, v166
	v_exp_f32_e32 v167, v167
	v_exp_f32_e32 v168, v168
	v_exp_f32_e32 v169, v169
	v_exp_f32_e32 v170, v170
	v_exp_f32_e32 v171, v171
	v_pk_add_f32 v[164:165], v[164:165], 1.0 op_sel_hi:[1,0]
	v_pk_add_f32 v[166:167], v[166:167], 1.0 op_sel_hi:[1,0]
	v_pk_add_f32 v[168:169], v[168:169], 1.0 op_sel_hi:[1,0]
	v_pk_add_f32 v[170:171], v[170:171], 1.0 op_sel_hi:[1,0]
	v_rcp_f32_e32 v164, v164
	v_rcp_f32_e32 v165, v165
	v_rcp_f32_e32 v166, v166
	v_rcp_f32_e32 v167, v167
	v_rcp_f32_e32 v168, v168
	v_rcp_f32_e32 v169, v169
	v_rcp_f32_e32 v170, v170
	v_rcp_f32_e32 v171, v171
	v_pk_mul_f32 v[164:165], v[12:13], v[164:165]
	v_pk_mul_f32 v[166:167], v[14:15], v[166:167]
	v_pk_mul_f32 v[168:169], v[16:17], v[168:169]
	v_pk_mul_f32 v[170:171], v[18:19], v[170:171]
	v_cvt_pk_bf16_f32 v174, v164, v165
	v_cvt_pk_bf16_f32 v175, v166, v167
	v_cvt_pk_bf16_f32 v176, v168, v169
	v_cvt_pk_bf16_f32 v177, v170, v171
	global_store_dwordx4 v1, v[174:177], s[22:23] offset:-3840
	s_waitcnt vmcnt(14)
	v_lshlrev_b32_e32 v164, 16, v182
	v_and_b32_e32 v165, 0xffff0000, v182
	v_lshlrev_b32_e32 v166, 16, v183
	v_and_b32_e32 v167, 0xffff0000, v183
	v_lshlrev_b32_e32 v168, 16, v184
	v_and_b32_e32 v169, 0xffff0000, v184
	v_lshlrev_b32_e32 v170, 16, v185
	v_and_b32_e32 v171, 0xffff0000, v185
	v_add_u32_e32 v2, s46, v158
	v_mad_u32_u24 v2, v2, s29, v0
	global_load_dwordx4 v[182:185], v2, s[96:97] offset:2304
	v_add_u32_e32 v1, s46, v146
	v_lshl_add_u32 v1, v1, 11, v0
	v_med3_f32 v164, v164, s34, v227
	v_med3_f32 v165, v165, s34, v227
	v_med3_f32 v166, v166, s34, v227
	v_med3_f32 v167, v167, s34, v227
	v_med3_f32 v168, v168, s34, v227
	v_med3_f32 v169, v169, s34, v227
	v_med3_f32 v170, v170, s34, v227
	v_med3_f32 v171, v171, s34, v227
	v_pk_mul_f32 v[164:165], v[164:165], s[44:45]
	v_pk_mul_f32 v[166:167], v[166:167], s[44:45]
	v_pk_mul_f32 v[168:169], v[168:169], s[44:45]
	v_pk_mul_f32 v[170:171], v[170:171], s[44:45]
	v_exp_f32_e32 v164, v164
	v_exp_f32_e32 v165, v165
	v_exp_f32_e32 v166, v166
	v_exp_f32_e32 v167, v167
	v_exp_f32_e32 v168, v168
	v_exp_f32_e32 v169, v169
	v_exp_f32_e32 v170, v170
	v_exp_f32_e32 v171, v171
	v_pk_add_f32 v[164:165], v[164:165], 1.0 op_sel_hi:[1,0]
	v_pk_add_f32 v[166:167], v[166:167], 1.0 op_sel_hi:[1,0]
	v_pk_add_f32 v[168:169], v[168:169], 1.0 op_sel_hi:[1,0]
	v_pk_add_f32 v[170:171], v[170:171], 1.0 op_sel_hi:[1,0]
	v_rcp_f32_e32 v164, v164
	v_rcp_f32_e32 v165, v165
	v_rcp_f32_e32 v166, v166
	v_rcp_f32_e32 v167, v167
	v_rcp_f32_e32 v168, v168
	v_rcp_f32_e32 v169, v169
	v_rcp_f32_e32 v170, v170
	v_rcp_f32_e32 v171, v171
	v_pk_mul_f32 v[164:165], v[128:129], v[164:165]
	v_pk_mul_f32 v[166:167], v[130:131], v[166:167]
	v_pk_mul_f32 v[168:169], v[124:125], v[168:169]
	v_pk_mul_f32 v[170:171], v[126:127], v[170:171]
	v_cvt_pk_bf16_f32 v174, v164, v165
	v_cvt_pk_bf16_f32 v175, v166, v167
	v_cvt_pk_bf16_f32 v176, v168, v169
	v_cvt_pk_bf16_f32 v177, v170, v171
	global_store_dwordx4 v1, v[174:177], s[22:23] offset:-4096
	s_waitcnt vmcnt(15)
	v_lshlrev_b32_e32 v164, 16, v186
	v_and_b32_e32 v165, 0xffff0000, v186
	v_lshlrev_b32_e32 v166, 16, v187
	v_and_b32_e32 v167, 0xffff0000, v187
	v_lshlrev_b32_e32 v168, 16, v188
	v_and_b32_e32 v169, 0xffff0000, v188
	v_lshlrev_b32_e32 v170, 16, v189
	v_and_b32_e32 v171, 0xffff0000, v189
	v_med3_f32 v164, v164, s34, v227
	v_med3_f32 v165, v165, s34, v227
	v_med3_f32 v166, v166, s34, v227
	v_med3_f32 v167, v167, s34, v227
	v_med3_f32 v168, v168, s34, v227
	v_med3_f32 v169, v169, s34, v227
	v_med3_f32 v170, v170, s34, v227
	v_med3_f32 v171, v171, s34, v227
	v_pk_mul_f32 v[164:165], v[164:165], s[44:45]
	v_pk_mul_f32 v[166:167], v[166:167], s[44:45]
	v_pk_mul_f32 v[168:169], v[168:169], s[44:45]
	v_pk_mul_f32 v[170:171], v[170:171], s[44:45]
	v_exp_f32_e32 v164, v164
	v_exp_f32_e32 v165, v165
	v_exp_f32_e32 v166, v166
	v_exp_f32_e32 v167, v167
	v_exp_f32_e32 v168, v168
	v_exp_f32_e32 v169, v169
	v_exp_f32_e32 v170, v170
	v_exp_f32_e32 v171, v171
	v_pk_add_f32 v[164:165], v[164:165], 1.0 op_sel_hi:[1,0]
	v_pk_add_f32 v[166:167], v[166:167], 1.0 op_sel_hi:[1,0]
	v_pk_add_f32 v[168:169], v[168:169], 1.0 op_sel_hi:[1,0]
	v_pk_add_f32 v[170:171], v[170:171], 1.0 op_sel_hi:[1,0]
	v_rcp_f32_e32 v164, v164
	v_rcp_f32_e32 v165, v165
	v_rcp_f32_e32 v166, v166
	v_rcp_f32_e32 v167, v167
	v_rcp_f32_e32 v168, v168
	v_rcp_f32_e32 v169, v169
	v_rcp_f32_e32 v170, v170
	v_rcp_f32_e32 v171, v171
	v_pk_mul_f32 v[164:165], v[104:105], v[164:165]
	v_pk_mul_f32 v[166:167], v[106:107], v[166:167]
	v_pk_mul_f32 v[168:169], v[100:101], v[168:169]
	v_pk_mul_f32 v[170:171], v[102:103], v[170:171]
	v_cvt_pk_bf16_f32 v174, v164, v165
	v_cvt_pk_bf16_f32 v175, v166, v167
	v_cvt_pk_bf16_f32 v176, v168, v169
	v_cvt_pk_bf16_f32 v177, v170, v171
	global_store_dwordx4 v1, v[174:177], s[22:23] offset:-3840
	s_waitcnt vmcnt(15)
	v_lshlrev_b32_e32 v164, 16, v190
	v_and_b32_e32 v165, 0xffff0000, v190
	v_lshlrev_b32_e32 v166, 16, v191
	v_and_b32_e32 v167, 0xffff0000, v191
	v_lshlrev_b32_e32 v168, 16, v192
	v_and_b32_e32 v169, 0xffff0000, v192
	v_lshlrev_b32_e32 v170, 16, v193
	v_and_b32_e32 v171, 0xffff0000, v193
	v_add_u32_e32 v1, s46, v148
	v_lshl_add_u32 v1, v1, 11, v0
	v_med3_f32 v164, v164, s34, v227
	v_med3_f32 v165, v165, s34, v227
	v_med3_f32 v166, v166, s34, v227
	v_med3_f32 v167, v167, s34, v227
	v_med3_f32 v168, v168, s34, v227
	v_med3_f32 v169, v169, s34, v227
	v_med3_f32 v170, v170, s34, v227
	v_med3_f32 v171, v171, s34, v227
	v_pk_mul_f32 v[164:165], v[164:165], s[44:45]
	v_pk_mul_f32 v[166:167], v[166:167], s[44:45]
	v_pk_mul_f32 v[168:169], v[168:169], s[44:45]
	v_pk_mul_f32 v[170:171], v[170:171], s[44:45]
	v_exp_f32_e32 v164, v164
	v_exp_f32_e32 v165, v165
	v_exp_f32_e32 v166, v166
	v_exp_f32_e32 v167, v167
	v_exp_f32_e32 v168, v168
	v_exp_f32_e32 v169, v169
	v_exp_f32_e32 v170, v170
	v_exp_f32_e32 v171, v171
	v_pk_add_f32 v[164:165], v[164:165], 1.0 op_sel_hi:[1,0]
	v_pk_add_f32 v[166:167], v[166:167], 1.0 op_sel_hi:[1,0]
	v_pk_add_f32 v[168:169], v[168:169], 1.0 op_sel_hi:[1,0]
	v_pk_add_f32 v[170:171], v[170:171], 1.0 op_sel_hi:[1,0]
	v_rcp_f32_e32 v164, v164
	v_rcp_f32_e32 v165, v165
	v_rcp_f32_e32 v166, v166
	v_rcp_f32_e32 v167, v167
	v_rcp_f32_e32 v168, v168
	v_rcp_f32_e32 v169, v169
	v_rcp_f32_e32 v170, v170
	v_rcp_f32_e32 v171, v171
	v_pk_mul_f32 v[164:165], v[120:121], v[164:165]
	v_pk_mul_f32 v[166:167], v[122:123], v[166:167]
	v_pk_mul_f32 v[168:169], v[116:117], v[168:169]
	v_pk_mul_f32 v[170:171], v[118:119], v[170:171]
	v_cvt_pk_bf16_f32 v174, v164, v165
	v_cvt_pk_bf16_f32 v175, v166, v167
	v_cvt_pk_bf16_f32 v176, v168, v169
	v_cvt_pk_bf16_f32 v177, v170, v171
	global_store_dwordx4 v1, v[174:177], s[22:23] offset:-4096
	s_waitcnt vmcnt(15)
	v_lshlrev_b32_e32 v164, 16, v202
	v_and_b32_e32 v165, 0xffff0000, v202
	v_lshlrev_b32_e32 v166, 16, v203
	v_and_b32_e32 v167, 0xffff0000, v203
	v_lshlrev_b32_e32 v168, 16, v204
	v_and_b32_e32 v169, 0xffff0000, v204
	v_lshlrev_b32_e32 v170, 16, v205
	v_and_b32_e32 v171, 0xffff0000, v205
	v_med3_f32 v164, v164, s34, v227
	v_med3_f32 v165, v165, s34, v227
	v_med3_f32 v166, v166, s34, v227
	v_med3_f32 v167, v167, s34, v227
	v_med3_f32 v168, v168, s34, v227
	v_med3_f32 v169, v169, s34, v227
	v_med3_f32 v170, v170, s34, v227
	v_med3_f32 v171, v171, s34, v227
	v_pk_mul_f32 v[164:165], v[164:165], s[44:45]
	v_pk_mul_f32 v[166:167], v[166:167], s[44:45]
	v_pk_mul_f32 v[168:169], v[168:169], s[44:45]
	v_pk_mul_f32 v[170:171], v[170:171], s[44:45]
	v_exp_f32_e32 v164, v164
	v_exp_f32_e32 v165, v165
	v_exp_f32_e32 v166, v166
	v_exp_f32_e32 v167, v167
	v_exp_f32_e32 v168, v168
	v_exp_f32_e32 v169, v169
	v_exp_f32_e32 v170, v170
	v_exp_f32_e32 v171, v171
	v_pk_add_f32 v[164:165], v[164:165], 1.0 op_sel_hi:[1,0]
	v_pk_add_f32 v[166:167], v[166:167], 1.0 op_sel_hi:[1,0]
	v_pk_add_f32 v[168:169], v[168:169], 1.0 op_sel_hi:[1,0]
	v_pk_add_f32 v[170:171], v[170:171], 1.0 op_sel_hi:[1,0]
	v_rcp_f32_e32 v164, v164
	v_rcp_f32_e32 v165, v165
	v_rcp_f32_e32 v166, v166
	v_rcp_f32_e32 v167, v167
	v_rcp_f32_e32 v168, v168
	v_rcp_f32_e32 v169, v169
	v_rcp_f32_e32 v170, v170
	v_rcp_f32_e32 v171, v171
	v_pk_mul_f32 v[164:165], v[96:97], v[164:165]
	v_pk_mul_f32 v[166:167], v[98:99], v[166:167]
	v_pk_mul_f32 v[168:169], v[92:93], v[168:169]
	v_pk_mul_f32 v[170:171], v[94:95], v[170:171]
	v_cvt_pk_bf16_f32 v174, v164, v165
	v_cvt_pk_bf16_f32 v175, v166, v167
	v_cvt_pk_bf16_f32 v176, v168, v169
	v_cvt_pk_bf16_f32 v177, v170, v171
	global_store_dwordx4 v1, v[174:177], s[22:23] offset:-3840
	s_waitcnt vmcnt(15)
	v_lshlrev_b32_e32 v164, 16, v206
	v_and_b32_e32 v165, 0xffff0000, v206
	v_lshlrev_b32_e32 v166, 16, v207
	v_and_b32_e32 v167, 0xffff0000, v207
	v_lshlrev_b32_e32 v168, 16, v208
	v_and_b32_e32 v169, 0xffff0000, v208
	v_lshlrev_b32_e32 v170, 16, v209
	v_and_b32_e32 v171, 0xffff0000, v209
	v_add_u32_e32 v1, s46, v150
	v_lshl_add_u32 v1, v1, 11, v0
	v_med3_f32 v164, v164, s34, v227
	v_med3_f32 v165, v165, s34, v227
	v_med3_f32 v166, v166, s34, v227
	v_med3_f32 v167, v167, s34, v227
	v_med3_f32 v168, v168, s34, v227
	v_med3_f32 v169, v169, s34, v227
	v_med3_f32 v170, v170, s34, v227
	v_med3_f32 v171, v171, s34, v227
	v_pk_mul_f32 v[164:165], v[164:165], s[44:45]
	v_pk_mul_f32 v[166:167], v[166:167], s[44:45]
	v_pk_mul_f32 v[168:169], v[168:169], s[44:45]
	v_pk_mul_f32 v[170:171], v[170:171], s[44:45]
	v_exp_f32_e32 v164, v164
	v_exp_f32_e32 v165, v165
	v_exp_f32_e32 v166, v166
	v_exp_f32_e32 v167, v167
	v_exp_f32_e32 v168, v168
	v_exp_f32_e32 v169, v169
	v_exp_f32_e32 v170, v170
	v_exp_f32_e32 v171, v171
	v_pk_add_f32 v[164:165], v[164:165], 1.0 op_sel_hi:[1,0]
	v_pk_add_f32 v[166:167], v[166:167], 1.0 op_sel_hi:[1,0]
	v_pk_add_f32 v[168:169], v[168:169], 1.0 op_sel_hi:[1,0]
	v_pk_add_f32 v[170:171], v[170:171], 1.0 op_sel_hi:[1,0]
	v_rcp_f32_e32 v164, v164
	v_rcp_f32_e32 v165, v165
	v_rcp_f32_e32 v166, v166
	v_rcp_f32_e32 v167, v167
	v_rcp_f32_e32 v168, v168
	v_rcp_f32_e32 v169, v169
	v_rcp_f32_e32 v170, v170
	v_rcp_f32_e32 v171, v171
	v_pk_mul_f32 v[164:165], v[112:113], v[164:165]
	v_pk_mul_f32 v[166:167], v[114:115], v[166:167]
	v_pk_mul_f32 v[168:169], v[108:109], v[168:169]
	v_pk_mul_f32 v[170:171], v[110:111], v[170:171]
	v_cvt_pk_bf16_f32 v174, v164, v165
	v_cvt_pk_bf16_f32 v175, v166, v167
	v_cvt_pk_bf16_f32 v176, v168, v169
	v_cvt_pk_bf16_f32 v177, v170, v171
	global_store_dwordx4 v1, v[174:177], s[22:23] offset:-4096
	s_waitcnt vmcnt(15)
	v_lshlrev_b32_e32 v164, 16, v210
	v_and_b32_e32 v165, 0xffff0000, v210
	v_lshlrev_b32_e32 v166, 16, v211
	v_and_b32_e32 v167, 0xffff0000, v211
	v_lshlrev_b32_e32 v168, 16, v212
	v_and_b32_e32 v169, 0xffff0000, v212
	v_lshlrev_b32_e32 v170, 16, v213
	v_and_b32_e32 v171, 0xffff0000, v213
	v_med3_f32 v164, v164, s34, v227
	v_med3_f32 v165, v165, s34, v227
	v_med3_f32 v166, v166, s34, v227
	v_med3_f32 v167, v167, s34, v227
	v_med3_f32 v168, v168, s34, v227
	v_med3_f32 v169, v169, s34, v227
	v_med3_f32 v170, v170, s34, v227
	v_med3_f32 v171, v171, s34, v227
	v_pk_mul_f32 v[164:165], v[164:165], s[44:45]
	v_pk_mul_f32 v[166:167], v[166:167], s[44:45]
	v_pk_mul_f32 v[168:169], v[168:169], s[44:45]
	v_pk_mul_f32 v[170:171], v[170:171], s[44:45]
	v_exp_f32_e32 v164, v164
	v_exp_f32_e32 v165, v165
	v_exp_f32_e32 v166, v166
	v_exp_f32_e32 v167, v167
	v_exp_f32_e32 v168, v168
	v_exp_f32_e32 v169, v169
	v_exp_f32_e32 v170, v170
	v_exp_f32_e32 v171, v171
	v_pk_add_f32 v[164:165], v[164:165], 1.0 op_sel_hi:[1,0]
	v_pk_add_f32 v[166:167], v[166:167], 1.0 op_sel_hi:[1,0]
	v_pk_add_f32 v[168:169], v[168:169], 1.0 op_sel_hi:[1,0]
	v_pk_add_f32 v[170:171], v[170:171], 1.0 op_sel_hi:[1,0]
	v_rcp_f32_e32 v164, v164
	v_rcp_f32_e32 v165, v165
	v_rcp_f32_e32 v166, v166
	v_rcp_f32_e32 v167, v167
	v_rcp_f32_e32 v168, v168
	v_rcp_f32_e32 v169, v169
	v_rcp_f32_e32 v170, v170
	v_rcp_f32_e32 v171, v171
	v_pk_mul_f32 v[164:165], v[88:89], v[164:165]
	v_pk_mul_f32 v[166:167], v[90:91], v[166:167]
	v_pk_mul_f32 v[168:169], v[84:85], v[168:169]
	v_pk_mul_f32 v[170:171], v[86:87], v[170:171]
	v_cvt_pk_bf16_f32 v174, v164, v165
	v_cvt_pk_bf16_f32 v175, v166, v167
	v_cvt_pk_bf16_f32 v176, v168, v169
	v_cvt_pk_bf16_f32 v177, v170, v171
	global_store_dwordx4 v1, v[174:177], s[22:23] offset:-3840
	s_waitcnt vmcnt(15)
	v_lshlrev_b32_e32 v164, 16, v214
	v_and_b32_e32 v165, 0xffff0000, v214
	v_lshlrev_b32_e32 v166, 16, v215
	v_and_b32_e32 v167, 0xffff0000, v215
	v_lshlrev_b32_e32 v168, 16, v216
	v_and_b32_e32 v169, 0xffff0000, v216
	v_lshlrev_b32_e32 v170, 16, v217
	v_and_b32_e32 v171, 0xffff0000, v217
	v_add_u32_e32 v1, s46, v152
	v_lshl_add_u32 v1, v1, 11, v0
	v_med3_f32 v164, v164, s34, v227
	v_med3_f32 v165, v165, s34, v227
	v_med3_f32 v166, v166, s34, v227
	v_med3_f32 v167, v167, s34, v227
	v_med3_f32 v168, v168, s34, v227
	v_med3_f32 v169, v169, s34, v227
	v_med3_f32 v170, v170, s34, v227
	v_med3_f32 v171, v171, s34, v227
	v_pk_mul_f32 v[164:165], v[164:165], s[44:45]
	v_pk_mul_f32 v[166:167], v[166:167], s[44:45]
	v_pk_mul_f32 v[168:169], v[168:169], s[44:45]
	v_pk_mul_f32 v[170:171], v[170:171], s[44:45]
	v_exp_f32_e32 v164, v164
	v_exp_f32_e32 v165, v165
	v_exp_f32_e32 v166, v166
	v_exp_f32_e32 v167, v167
	v_exp_f32_e32 v168, v168
	v_exp_f32_e32 v169, v169
	v_exp_f32_e32 v170, v170
	v_exp_f32_e32 v171, v171
	v_pk_add_f32 v[164:165], v[164:165], 1.0 op_sel_hi:[1,0]
	v_pk_add_f32 v[166:167], v[166:167], 1.0 op_sel_hi:[1,0]
	v_pk_add_f32 v[168:169], v[168:169], 1.0 op_sel_hi:[1,0]
	v_pk_add_f32 v[170:171], v[170:171], 1.0 op_sel_hi:[1,0]
	v_rcp_f32_e32 v164, v164
	v_rcp_f32_e32 v165, v165
	v_rcp_f32_e32 v166, v166
	v_rcp_f32_e32 v167, v167
	v_rcp_f32_e32 v168, v168
	v_rcp_f32_e32 v169, v169
	v_rcp_f32_e32 v170, v170
	v_rcp_f32_e32 v171, v171
	v_pk_mul_f32 v[164:165], v[80:81], v[164:165]
	v_pk_mul_f32 v[166:167], v[82:83], v[166:167]
	v_pk_mul_f32 v[168:169], v[76:77], v[168:169]
	v_pk_mul_f32 v[170:171], v[78:79], v[170:171]
	v_cvt_pk_bf16_f32 v174, v164, v165
	v_cvt_pk_bf16_f32 v175, v166, v167
	v_cvt_pk_bf16_f32 v176, v168, v169
	v_cvt_pk_bf16_f32 v177, v170, v171
	global_store_dwordx4 v1, v[174:177], s[22:23] offset:-4096
	s_waitcnt vmcnt(15)
	v_lshlrev_b32_e32 v164, 16, v236
	v_and_b32_e32 v165, 0xffff0000, v236
	v_lshlrev_b32_e32 v166, 16, v237
	v_and_b32_e32 v167, 0xffff0000, v237
	v_lshlrev_b32_e32 v168, 16, v238
	v_and_b32_e32 v169, 0xffff0000, v238
	v_lshlrev_b32_e32 v170, 16, v239
	v_and_b32_e32 v171, 0xffff0000, v239
	v_med3_f32 v164, v164, s34, v227
	v_med3_f32 v165, v165, s34, v227
	v_med3_f32 v166, v166, s34, v227
	v_med3_f32 v167, v167, s34, v227
	v_med3_f32 v168, v168, s34, v227
	v_med3_f32 v169, v169, s34, v227
	v_med3_f32 v170, v170, s34, v227
	v_med3_f32 v171, v171, s34, v227
	v_pk_mul_f32 v[164:165], v[164:165], s[44:45]
	v_pk_mul_f32 v[166:167], v[166:167], s[44:45]
	v_pk_mul_f32 v[168:169], v[168:169], s[44:45]
	v_pk_mul_f32 v[170:171], v[170:171], s[44:45]
	v_exp_f32_e32 v164, v164
	v_exp_f32_e32 v165, v165
	v_exp_f32_e32 v166, v166
	v_exp_f32_e32 v167, v167
	v_exp_f32_e32 v168, v168
	v_exp_f32_e32 v169, v169
	v_exp_f32_e32 v170, v170
	v_exp_f32_e32 v171, v171
	v_pk_add_f32 v[164:165], v[164:165], 1.0 op_sel_hi:[1,0]
	v_pk_add_f32 v[166:167], v[166:167], 1.0 op_sel_hi:[1,0]
	v_pk_add_f32 v[168:169], v[168:169], 1.0 op_sel_hi:[1,0]
	v_pk_add_f32 v[170:171], v[170:171], 1.0 op_sel_hi:[1,0]
	v_rcp_f32_e32 v164, v164
	v_rcp_f32_e32 v165, v165
	v_rcp_f32_e32 v166, v166
	v_rcp_f32_e32 v167, v167
	v_rcp_f32_e32 v168, v168
	v_rcp_f32_e32 v169, v169
	v_rcp_f32_e32 v170, v170
	v_rcp_f32_e32 v171, v171
	v_pk_mul_f32 v[164:165], v[48:49], v[164:165]
	v_pk_mul_f32 v[166:167], v[50:51], v[166:167]
	v_pk_mul_f32 v[168:169], v[44:45], v[168:169]
	v_pk_mul_f32 v[170:171], v[46:47], v[170:171]
	v_cvt_pk_bf16_f32 v174, v164, v165
	v_cvt_pk_bf16_f32 v175, v166, v167
	v_cvt_pk_bf16_f32 v176, v168, v169
	v_cvt_pk_bf16_f32 v177, v170, v171
	global_store_dwordx4 v1, v[174:177], s[22:23] offset:-3840
	s_waitcnt vmcnt(15)
	v_lshlrev_b32_e32 v164, 16, v240
	v_and_b32_e32 v165, 0xffff0000, v240
	v_lshlrev_b32_e32 v166, 16, v241
	v_and_b32_e32 v167, 0xffff0000, v241
	v_lshlrev_b32_e32 v168, 16, v242
	v_and_b32_e32 v169, 0xffff0000, v242
	v_lshlrev_b32_e32 v170, 16, v243
	v_and_b32_e32 v171, 0xffff0000, v243
	v_add_u32_e32 v1, s46, v154
	v_lshl_add_u32 v1, v1, 11, v0
	v_med3_f32 v164, v164, s34, v227
	v_med3_f32 v165, v165, s34, v227
	v_med3_f32 v166, v166, s34, v227
	v_med3_f32 v167, v167, s34, v227
	v_med3_f32 v168, v168, s34, v227
	v_med3_f32 v169, v169, s34, v227
	v_med3_f32 v170, v170, s34, v227
	v_med3_f32 v171, v171, s34, v227
	v_pk_mul_f32 v[164:165], v[164:165], s[44:45]
	v_pk_mul_f32 v[166:167], v[166:167], s[44:45]
	v_pk_mul_f32 v[168:169], v[168:169], s[44:45]
	v_pk_mul_f32 v[170:171], v[170:171], s[44:45]
	v_exp_f32_e32 v164, v164
	v_exp_f32_e32 v165, v165
	v_exp_f32_e32 v166, v166
	v_exp_f32_e32 v167, v167
	v_exp_f32_e32 v168, v168
	v_exp_f32_e32 v169, v169
	v_exp_f32_e32 v170, v170
	v_exp_f32_e32 v171, v171
	v_pk_add_f32 v[164:165], v[164:165], 1.0 op_sel_hi:[1,0]
	v_pk_add_f32 v[166:167], v[166:167], 1.0 op_sel_hi:[1,0]
	v_pk_add_f32 v[168:169], v[168:169], 1.0 op_sel_hi:[1,0]
	v_pk_add_f32 v[170:171], v[170:171], 1.0 op_sel_hi:[1,0]
	v_rcp_f32_e32 v164, v164
	v_rcp_f32_e32 v165, v165
	v_rcp_f32_e32 v166, v166
	v_rcp_f32_e32 v167, v167
	v_rcp_f32_e32 v168, v168
	v_rcp_f32_e32 v169, v169
	v_rcp_f32_e32 v170, v170
	v_rcp_f32_e32 v171, v171
	v_pk_mul_f32 v[164:165], v[72:73], v[164:165]
	v_pk_mul_f32 v[166:167], v[74:75], v[166:167]
	v_pk_mul_f32 v[168:169], v[68:69], v[168:169]
	v_pk_mul_f32 v[170:171], v[70:71], v[170:171]
	v_cvt_pk_bf16_f32 v174, v164, v165
	v_cvt_pk_bf16_f32 v175, v166, v167
	v_cvt_pk_bf16_f32 v176, v168, v169
	v_cvt_pk_bf16_f32 v177, v170, v171
	global_store_dwordx4 v1, v[174:177], s[22:23] offset:-4096
	s_waitcnt vmcnt(15)
	v_lshlrev_b32_e32 v164, 16, v244
	v_and_b32_e32 v165, 0xffff0000, v244
	v_lshlrev_b32_e32 v166, 16, v245
	v_and_b32_e32 v167, 0xffff0000, v245
	v_lshlrev_b32_e32 v168, 16, v246
	v_and_b32_e32 v169, 0xffff0000, v246
	v_lshlrev_b32_e32 v170, 16, v247
	v_and_b32_e32 v171, 0xffff0000, v247
	v_med3_f32 v164, v164, s34, v227
	v_med3_f32 v165, v165, s34, v227
	v_med3_f32 v166, v166, s34, v227
	v_med3_f32 v167, v167, s34, v227
	v_med3_f32 v168, v168, s34, v227
	v_med3_f32 v169, v169, s34, v227
	v_med3_f32 v170, v170, s34, v227
	v_med3_f32 v171, v171, s34, v227
	v_pk_mul_f32 v[164:165], v[164:165], s[44:45]
	v_pk_mul_f32 v[166:167], v[166:167], s[44:45]
	v_pk_mul_f32 v[168:169], v[168:169], s[44:45]
	v_pk_mul_f32 v[170:171], v[170:171], s[44:45]
	v_exp_f32_e32 v164, v164
	v_exp_f32_e32 v165, v165
	v_exp_f32_e32 v166, v166
	v_exp_f32_e32 v167, v167
	v_exp_f32_e32 v168, v168
	v_exp_f32_e32 v169, v169
	v_exp_f32_e32 v170, v170
	v_exp_f32_e32 v171, v171
	v_pk_add_f32 v[164:165], v[164:165], 1.0 op_sel_hi:[1,0]
	v_pk_add_f32 v[166:167], v[166:167], 1.0 op_sel_hi:[1,0]
	v_pk_add_f32 v[168:169], v[168:169], 1.0 op_sel_hi:[1,0]
	v_pk_add_f32 v[170:171], v[170:171], 1.0 op_sel_hi:[1,0]
	v_rcp_f32_e32 v164, v164
	v_rcp_f32_e32 v165, v165
	v_rcp_f32_e32 v166, v166
	v_rcp_f32_e32 v167, v167
	v_rcp_f32_e32 v168, v168
	v_rcp_f32_e32 v169, v169
	v_rcp_f32_e32 v170, v170
	v_rcp_f32_e32 v171, v171
	v_pk_mul_f32 v[164:165], v[40:41], v[164:165]
	v_pk_mul_f32 v[166:167], v[42:43], v[166:167]
	v_pk_mul_f32 v[168:169], v[36:37], v[168:169]
	v_pk_mul_f32 v[170:171], v[38:39], v[170:171]
	v_cvt_pk_bf16_f32 v174, v164, v165
	v_cvt_pk_bf16_f32 v175, v166, v167
	v_cvt_pk_bf16_f32 v176, v168, v169
	v_cvt_pk_bf16_f32 v177, v170, v171
	global_store_dwordx4 v1, v[174:177], s[22:23] offset:-3840
	s_waitcnt vmcnt(15)
	v_lshlrev_b32_e32 v164, 16, v248
	v_and_b32_e32 v165, 0xffff0000, v248
	v_lshlrev_b32_e32 v166, 16, v249
	v_and_b32_e32 v167, 0xffff0000, v249
	v_lshlrev_b32_e32 v168, 16, v250
	v_and_b32_e32 v169, 0xffff0000, v250
	v_lshlrev_b32_e32 v170, 16, v251
	v_and_b32_e32 v171, 0xffff0000, v251
	v_add_u32_e32 v1, s46, v156
	v_lshl_add_u32 v1, v1, 11, v0
	v_med3_f32 v164, v164, s34, v227
	v_med3_f32 v165, v165, s34, v227
	v_med3_f32 v166, v166, s34, v227
	v_med3_f32 v167, v167, s34, v227
	v_med3_f32 v168, v168, s34, v227
	v_med3_f32 v169, v169, s34, v227
	v_med3_f32 v170, v170, s34, v227
	v_med3_f32 v171, v171, s34, v227
	v_pk_mul_f32 v[164:165], v[164:165], s[44:45]
	v_pk_mul_f32 v[166:167], v[166:167], s[44:45]
	v_pk_mul_f32 v[168:169], v[168:169], s[44:45]
	v_pk_mul_f32 v[170:171], v[170:171], s[44:45]
	v_exp_f32_e32 v164, v164
	v_exp_f32_e32 v165, v165
	v_exp_f32_e32 v166, v166
	v_exp_f32_e32 v167, v167
	v_exp_f32_e32 v168, v168
	v_exp_f32_e32 v169, v169
	v_exp_f32_e32 v170, v170
	v_exp_f32_e32 v171, v171
	v_pk_add_f32 v[164:165], v[164:165], 1.0 op_sel_hi:[1,0]
	v_pk_add_f32 v[166:167], v[166:167], 1.0 op_sel_hi:[1,0]
	v_pk_add_f32 v[168:169], v[168:169], 1.0 op_sel_hi:[1,0]
	v_pk_add_f32 v[170:171], v[170:171], 1.0 op_sel_hi:[1,0]
	v_rcp_f32_e32 v164, v164
	v_rcp_f32_e32 v165, v165
	v_rcp_f32_e32 v166, v166
	v_rcp_f32_e32 v167, v167
	v_rcp_f32_e32 v168, v168
	v_rcp_f32_e32 v169, v169
	v_rcp_f32_e32 v170, v170
	v_rcp_f32_e32 v171, v171
	v_pk_mul_f32 v[164:165], v[64:65], v[164:165]
	v_pk_mul_f32 v[166:167], v[66:67], v[166:167]
	v_pk_mul_f32 v[168:169], v[60:61], v[168:169]
	v_pk_mul_f32 v[170:171], v[62:63], v[170:171]
	v_cvt_pk_bf16_f32 v174, v164, v165
	v_cvt_pk_bf16_f32 v175, v166, v167
	v_cvt_pk_bf16_f32 v176, v168, v169
	v_cvt_pk_bf16_f32 v177, v170, v171
	global_store_dwordx4 v1, v[174:177], s[22:23] offset:-4096
	s_waitcnt vmcnt(15)
	v_lshlrev_b32_e32 v164, 16, v132
	v_and_b32_e32 v165, 0xffff0000, v132
	v_lshlrev_b32_e32 v166, 16, v133
	v_and_b32_e32 v167, 0xffff0000, v133
	v_lshlrev_b32_e32 v168, 16, v134
	v_and_b32_e32 v169, 0xffff0000, v134
	v_lshlrev_b32_e32 v170, 16, v135
	v_and_b32_e32 v171, 0xffff0000, v135
	v_med3_f32 v164, v164, s34, v227
	v_med3_f32 v165, v165, s34, v227
	v_med3_f32 v166, v166, s34, v227
	v_med3_f32 v167, v167, s34, v227
	v_med3_f32 v168, v168, s34, v227
	v_med3_f32 v169, v169, s34, v227
	v_med3_f32 v170, v170, s34, v227
	v_med3_f32 v171, v171, s34, v227
	v_pk_mul_f32 v[164:165], v[164:165], s[44:45]
	v_pk_mul_f32 v[166:167], v[166:167], s[44:45]
	v_pk_mul_f32 v[168:169], v[168:169], s[44:45]
	v_pk_mul_f32 v[170:171], v[170:171], s[44:45]
	v_exp_f32_e32 v164, v164
	v_exp_f32_e32 v165, v165
	v_exp_f32_e32 v166, v166
	v_exp_f32_e32 v167, v167
	v_exp_f32_e32 v168, v168
	v_exp_f32_e32 v169, v169
	v_exp_f32_e32 v170, v170
	v_exp_f32_e32 v171, v171
	v_pk_add_f32 v[164:165], v[164:165], 1.0 op_sel_hi:[1,0]
	v_pk_add_f32 v[166:167], v[166:167], 1.0 op_sel_hi:[1,0]
	v_pk_add_f32 v[168:169], v[168:169], 1.0 op_sel_hi:[1,0]
	v_pk_add_f32 v[170:171], v[170:171], 1.0 op_sel_hi:[1,0]
	v_rcp_f32_e32 v164, v164
	v_rcp_f32_e32 v165, v165
	v_rcp_f32_e32 v166, v166
	v_rcp_f32_e32 v167, v167
	v_rcp_f32_e32 v168, v168
	v_rcp_f32_e32 v169, v169
	v_rcp_f32_e32 v170, v170
	v_rcp_f32_e32 v171, v171
	v_pk_mul_f32 v[164:165], v[32:33], v[164:165]
	v_pk_mul_f32 v[166:167], v[34:35], v[166:167]
	v_pk_mul_f32 v[168:169], v[28:29], v[168:169]
	v_pk_mul_f32 v[170:171], v[30:31], v[170:171]
	v_cvt_pk_bf16_f32 v174, v164, v165
	v_cvt_pk_bf16_f32 v175, v166, v167
	v_cvt_pk_bf16_f32 v176, v168, v169
	v_cvt_pk_bf16_f32 v177, v170, v171
	global_store_dwordx4 v1, v[174:177], s[22:23] offset:-3840
	s_waitcnt vmcnt(14)
	v_lshlrev_b32_e32 v164, 16, v178
	v_and_b32_e32 v165, 0xffff0000, v178
	v_lshlrev_b32_e32 v166, 16, v179
	v_and_b32_e32 v167, 0xffff0000, v179
	v_lshlrev_b32_e32 v168, 16, v180
	v_and_b32_e32 v169, 0xffff0000, v180
	v_lshlrev_b32_e32 v170, 16, v181
	v_and_b32_e32 v171, 0xffff0000, v181
	v_add_u32_e32 v1, s46, v158
	v_lshl_add_u32 v1, v1, 11, v0
	v_med3_f32 v164, v164, s34, v227
	v_med3_f32 v165, v165, s34, v227
	v_med3_f32 v166, v166, s34, v227
	v_med3_f32 v167, v167, s34, v227
	v_med3_f32 v168, v168, s34, v227
	v_med3_f32 v169, v169, s34, v227
	v_med3_f32 v170, v170, s34, v227
	v_med3_f32 v171, v171, s34, v227
	v_pk_mul_f32 v[164:165], v[164:165], s[44:45]
	v_pk_mul_f32 v[166:167], v[166:167], s[44:45]
	v_pk_mul_f32 v[168:169], v[168:169], s[44:45]
	v_pk_mul_f32 v[170:171], v[170:171], s[44:45]
	v_exp_f32_e32 v164, v164
	v_exp_f32_e32 v165, v165
	v_exp_f32_e32 v166, v166
	v_exp_f32_e32 v167, v167
	v_exp_f32_e32 v168, v168
	v_exp_f32_e32 v169, v169
	v_exp_f32_e32 v170, v170
	v_exp_f32_e32 v171, v171
	v_pk_add_f32 v[164:165], v[164:165], 1.0 op_sel_hi:[1,0]
	v_pk_add_f32 v[166:167], v[166:167], 1.0 op_sel_hi:[1,0]
	v_pk_add_f32 v[168:169], v[168:169], 1.0 op_sel_hi:[1,0]
	v_pk_add_f32 v[170:171], v[170:171], 1.0 op_sel_hi:[1,0]
	v_rcp_f32_e32 v164, v164
	v_rcp_f32_e32 v165, v165
	v_rcp_f32_e32 v166, v166
	v_rcp_f32_e32 v167, v167
	v_rcp_f32_e32 v168, v168
	v_rcp_f32_e32 v169, v169
	v_rcp_f32_e32 v170, v170
	v_rcp_f32_e32 v171, v171
	v_pk_mul_f32 v[164:165], v[56:57], v[164:165]
	v_pk_mul_f32 v[166:167], v[58:59], v[166:167]
	v_pk_mul_f32 v[168:169], v[52:53], v[168:169]
	v_pk_mul_f32 v[170:171], v[54:55], v[170:171]
	v_cvt_pk_bf16_f32 v174, v164, v165
	v_cvt_pk_bf16_f32 v175, v166, v167
	v_cvt_pk_bf16_f32 v176, v168, v169
	v_cvt_pk_bf16_f32 v177, v170, v171
	global_store_dwordx4 v1, v[174:177], s[22:23] offset:-4096
	s_waitcnt vmcnt(13)
	v_lshlrev_b32_e32 v164, 16, v182
	v_and_b32_e32 v165, 0xffff0000, v182
	v_lshlrev_b32_e32 v166, 16, v183
	v_and_b32_e32 v167, 0xffff0000, v183
	v_lshlrev_b32_e32 v168, 16, v184
	v_and_b32_e32 v169, 0xffff0000, v184
	v_lshlrev_b32_e32 v170, 16, v185
	v_and_b32_e32 v171, 0xffff0000, v185
	v_med3_f32 v164, v164, s34, v227
	v_med3_f32 v165, v165, s34, v227
	v_med3_f32 v166, v166, s34, v227
	v_med3_f32 v167, v167, s34, v227
	v_med3_f32 v168, v168, s34, v227
	v_med3_f32 v169, v169, s34, v227
	v_med3_f32 v170, v170, s34, v227
	v_med3_f32 v171, v171, s34, v227
	v_pk_mul_f32 v[164:165], v[164:165], s[44:45]
	v_pk_mul_f32 v[166:167], v[166:167], s[44:45]
	v_pk_mul_f32 v[168:169], v[168:169], s[44:45]
	v_pk_mul_f32 v[170:171], v[170:171], s[44:45]
	v_exp_f32_e32 v164, v164
	v_exp_f32_e32 v165, v165
	v_exp_f32_e32 v166, v166
	v_exp_f32_e32 v167, v167
	v_exp_f32_e32 v168, v168
	v_exp_f32_e32 v169, v169
	v_exp_f32_e32 v170, v170
	v_exp_f32_e32 v171, v171
	v_pk_add_f32 v[164:165], v[164:165], 1.0 op_sel_hi:[1,0]
	v_pk_add_f32 v[166:167], v[166:167], 1.0 op_sel_hi:[1,0]
	v_pk_add_f32 v[168:169], v[168:169], 1.0 op_sel_hi:[1,0]
	v_pk_add_f32 v[170:171], v[170:171], 1.0 op_sel_hi:[1,0]
	v_rcp_f32_e32 v164, v164
	v_rcp_f32_e32 v165, v165
	v_rcp_f32_e32 v166, v166
	v_rcp_f32_e32 v167, v167
	v_rcp_f32_e32 v168, v168
	v_rcp_f32_e32 v169, v169
	v_rcp_f32_e32 v170, v170
	v_rcp_f32_e32 v171, v171
	v_pk_mul_f32 v[164:165], v[24:25], v[164:165]
	v_pk_mul_f32 v[166:167], v[26:27], v[166:167]
	v_pk_mul_f32 v[168:169], v[20:21], v[168:169]
	v_pk_mul_f32 v[170:171], v[22:23], v[170:171]
	v_cvt_pk_bf16_f32 v174, v164, v165
	v_cvt_pk_bf16_f32 v175, v166, v167
	v_cvt_pk_bf16_f32 v176, v168, v169
	v_cvt_pk_bf16_f32 v177, v170, v171
	global_store_dwordx4 v1, v[174:177], s[22:23] offset:-3840
	s_mov_b64 s[40:41], 0
	s_branch .LBB0_206

.LBB0_241:
	s_add_u32 s0, s0, 0x40080
	s_addc_u32 s1, s1, 0
	s_add_u32 s20, s44, 0x100
	v_mov_b32_e32 v4, 0
	s_addc_u32 s21, s45, 0
	s_mov_b32 s22, -2
	v_mov_b32_e32 v5, v4
	v_mov_b32_e32 v6, v4
	v_mov_b32_e32 v7, v4
	v_mov_b32_e32 v8, v4
	v_mov_b32_e32 v9, v4
	v_mov_b32_e32 v10, v4
	v_mov_b32_e32 v11, v4
	v_mov_b32_e32 v12, v4
	v_mov_b32_e32 v13, v4
	v_mov_b32_e32 v14, v4
	v_mov_b32_e32 v15, v4
	v_mov_b32_e32 v16, v4
	v_mov_b32_e32 v17, v4
	v_mov_b32_e32 v18, v4
	v_mov_b32_e32 v19, v4
	v_mov_b32_e32 v20, v4
	v_mov_b32_e32 v21, v4
	v_mov_b32_e32 v22, v4
	v_mov_b32_e32 v23, v4
	v_mov_b32_e32 v24, v4
	v_mov_b32_e32 v25, v4
	v_mov_b32_e32 v26, v4
	v_mov_b32_e32 v27, v4
	v_mov_b32_e32 v28, v4
	v_mov_b32_e32 v29, v4
	v_mov_b32_e32 v30, v4
	v_mov_b32_e32 v31, v4
	v_mov_b32_e32 v32, v4
	v_mov_b32_e32 v33, v4
	v_mov_b32_e32 v34, v4
	v_mov_b32_e32 v35, v4
	v_mov_b32_e32 v68, v4
	v_mov_b32_e32 v69, v4
	v_mov_b32_e32 v70, v4
	v_mov_b32_e32 v71, v4
	v_mov_b32_e32 v72, v4
	v_mov_b32_e32 v73, v4
	v_mov_b32_e32 v74, v4
	v_mov_b32_e32 v75, v4
	v_mov_b32_e32 v76, v4
	v_mov_b32_e32 v77, v4
	v_mov_b32_e32 v78, v4
	v_mov_b32_e32 v79, v4
	v_mov_b32_e32 v80, v4
	v_mov_b32_e32 v81, v4
	v_mov_b32_e32 v82, v4
	v_mov_b32_e32 v83, v4
	v_mov_b32_e32 v84, v4
	v_mov_b32_e32 v85, v4
	v_mov_b32_e32 v86, v4
	v_mov_b32_e32 v87, v4
	v_mov_b32_e32 v88, v4
	v_mov_b32_e32 v89, v4
	v_mov_b32_e32 v90, v4
	v_mov_b32_e32 v91, v4
	v_mov_b32_e32 v92, v4
	v_mov_b32_e32 v93, v4
	v_mov_b32_e32 v94, v4
	v_mov_b32_e32 v95, v4
	v_mov_b32_e32 v96, v4
	v_mov_b32_e32 v97, v4
	v_mov_b32_e32 v98, v4
	v_mov_b32_e32 v99, v4
	v_mov_b32_e32 v36, v4
	v_mov_b32_e32 v37, v4
	v_mov_b32_e32 v38, v4
	v_mov_b32_e32 v39, v4
	v_mov_b32_e32 v40, v4
	v_mov_b32_e32 v41, v4
	v_mov_b32_e32 v42, v4
	v_mov_b32_e32 v43, v4
	v_mov_b32_e32 v44, v4
	v_mov_b32_e32 v45, v4
	v_mov_b32_e32 v46, v4
	v_mov_b32_e32 v47, v4
	v_mov_b32_e32 v48, v4
	v_mov_b32_e32 v49, v4
	v_mov_b32_e32 v50, v4
	v_mov_b32_e32 v51, v4
	v_mov_b32_e32 v52, v4
	v_mov_b32_e32 v53, v4
	v_mov_b32_e32 v54, v4
	v_mov_b32_e32 v55, v4
	v_mov_b32_e32 v56, v4
	v_mov_b32_e32 v57, v4
	v_mov_b32_e32 v58, v4
	v_mov_b32_e32 v59, v4
	v_mov_b32_e32 v60, v4
	v_mov_b32_e32 v61, v4
	v_mov_b32_e32 v62, v4
	v_mov_b32_e32 v63, v4
	v_mov_b32_e32 v64, v4
	v_mov_b32_e32 v65, v4
	v_mov_b32_e32 v66, v4
	v_mov_b32_e32 v67, v4
	v_mov_b32_e32 v100, v4
	v_mov_b32_e32 v101, v4
	v_mov_b32_e32 v102, v4
	v_mov_b32_e32 v103, v4
	v_mov_b32_e32 v104, v4
	v_mov_b32_e32 v105, v4
	v_mov_b32_e32 v106, v4
	v_mov_b32_e32 v107, v4
	v_mov_b32_e32 v108, v4
	v_mov_b32_e32 v109, v4
	v_mov_b32_e32 v110, v4
	v_mov_b32_e32 v111, v4
	v_mov_b32_e32 v112, v4
	v_mov_b32_e32 v113, v4
	v_mov_b32_e32 v114, v4
	v_mov_b32_e32 v115, v4
	v_mov_b32_e32 v116, v4
	v_mov_b32_e32 v117, v4
	v_mov_b32_e32 v118, v4
	v_mov_b32_e32 v119, v4
	v_mov_b32_e32 v120, v4
	v_mov_b32_e32 v121, v4
	v_mov_b32_e32 v122, v4
	v_mov_b32_e32 v123, v4
	v_mov_b32_e32 v124, v4
	v_mov_b32_e32 v125, v4
	v_mov_b32_e32 v126, v4
	v_mov_b32_e32 v127, v4
	v_mov_b32_e32 v128, v4
	v_mov_b32_e32 v129, v4
	v_mov_b32_e32 v130, v4
	v_mov_b32_e32 v131, v4
	v_add_u32_e32 v216, 0x10000, v187
.LBB0_242:
	s_add_u32 s23, s0, 0xfffc0080
	s_addc_u32 s24, s1, -1
	s_add_i32 s25, 0, 0x10000
	ds_read_b128 v[132:135], v216
	ds_read_b128 v[136:139], v216 offset:1024
	ds_read_b128 v[140:143], v216 offset:2048
	ds_read_b128 v[144:147], v216 offset:3072
	s_cmp_eq_u32 s22, 12
	s_cselect_b32 s47, s57, s24
	s_cselect_b32 s46, s56, s23
	s_cselect_b32 s45, s59, s21
	s_cselect_b32 s44, s58, s20
	s_add_i32 m0, s67, 0xc000
	ds_read_b128 v[148:151], v240
	ds_read_b128 v[152:155], v240 offset:1024
	ds_read_b128 v[156:159], v240 offset:2048
	ds_read_b128 v[160:163], v240 offset:3072
	ds_read_b128 v[164:167], v240 offset:4096
	ds_read_b128 v[168:171], v240 offset:5120
	ds_read_b128 v[172:175], v240 offset:6144
	global_load_lds_dwordx4 v194, s[0:1]
	s_add_i32 m0, s67, 0xe000
	ds_read_b128 v[204:207], v240 offset:7168
	global_load_lds_dwordx4 v202, s[0:1]
	s_waitcnt lgkmcnt(8)
	s_barrier
	s_waitcnt lgkmcnt(0)
	v_mfma_f32_16x16x32_bf16 v[128:131], v[132:135], v[148:151], v[128:131]
	v_mfma_f32_16x16x32_bf16 v[124:127], v[140:143], v[148:151], v[124:127]
	v_mfma_f32_16x16x32_bf16 v[120:123], v[132:135], v[156:159], v[120:123]
	v_mfma_f32_16x16x32_bf16 v[116:119], v[140:143], v[156:159], v[116:119]
	v_mfma_f32_16x16x32_bf16 v[112:115], v[132:135], v[164:167], v[112:115]
	v_mfma_f32_16x16x32_bf16 v[108:111], v[140:143], v[164:167], v[108:111]
	v_mfma_f32_16x16x32_bf16 v[104:107], v[132:135], v[172:175], v[104:107]
	v_mfma_f32_16x16x32_bf16 v[100:103], v[140:143], v[172:175], v[100:103]
	v_mfma_f32_16x16x32_bf16 v[128:131], v[136:139], v[152:155], v[128:131]
	v_mfma_f32_16x16x32_bf16 v[124:127], v[144:147], v[152:155], v[124:127]
	v_mfma_f32_16x16x32_bf16 v[120:123], v[136:139], v[160:163], v[120:123]
	v_mfma_f32_16x16x32_bf16 v[116:119], v[144:147], v[160:163], v[116:119]
	v_mfma_f32_16x16x32_bf16 v[112:115], v[136:139], v[168:171], v[112:115]
	v_mfma_f32_16x16x32_bf16 v[108:111], v[144:147], v[168:171], v[108:111]
	v_mfma_f32_16x16x32_bf16 v[104:107], v[136:139], v[204:207], v[104:107]
	v_mfma_f32_16x16x32_bf16 v[100:103], v[144:147], v[204:207], v[100:103]
	s_barrier
	s_add_i32 s23, 0, 0x14000
	s_add_i32 s24, s25, s61
	s_mov_b32 m0, s24
	ds_read_b128 v[208:211], v216 offset:16384
	ds_read_b128 v[212:215], v216 offset:17408
	ds_read_b128 v[242:245], v216 offset:18432
	global_load_lds_dwordx4 v176, s[44:45]
	s_add_i32 m0, s24, 0x2000
	ds_read_b128 v[246:249], v216 offset:19456
	global_load_lds_dwordx4 v180, s[44:45]
	s_barrier
	s_waitcnt lgkmcnt(0)
	v_mfma_f32_16x16x32_bf16 v[64:67], v[208:211], v[148:151], v[64:67]
	v_mfma_f32_16x16x32_bf16 v[60:63], v[242:245], v[148:151], v[60:63]
	v_mfma_f32_16x16x32_bf16 v[56:59], v[208:211], v[156:159], v[56:59]
	v_mfma_f32_16x16x32_bf16 v[52:55], v[242:245], v[156:159], v[52:55]
	v_mfma_f32_16x16x32_bf16 v[48:51], v[208:211], v[164:167], v[48:51]
	v_mfma_f32_16x16x32_bf16 v[44:47], v[242:245], v[164:167], v[44:47]
	v_mfma_f32_16x16x32_bf16 v[40:43], v[208:211], v[172:175], v[40:43]
	v_mfma_f32_16x16x32_bf16 v[36:39], v[242:245], v[172:175], v[36:39]
	v_mfma_f32_16x16x32_bf16 v[64:67], v[212:215], v[152:155], v[64:67]
	v_mfma_f32_16x16x32_bf16 v[60:63], v[246:249], v[152:155], v[60:63]
	v_mfma_f32_16x16x32_bf16 v[56:59], v[212:215], v[160:163], v[56:59]
	v_mfma_f32_16x16x32_bf16 v[52:55], v[246:249], v[160:163], v[52:55]
	v_mfma_f32_16x16x32_bf16 v[48:51], v[212:215], v[168:171], v[48:51]
	v_mfma_f32_16x16x32_bf16 v[44:47], v[246:249], v[168:171], v[44:47]
	v_mfma_f32_16x16x32_bf16 v[40:43], v[212:215], v[204:207], v[40:43]
	v_mfma_f32_16x16x32_bf16 v[36:39], v[246:249], v[204:207], v[36:39]
	s_mov_b32 m0, s67
	s_barrier
	ds_read_b128 v[148:151], v240 offset:16384
	ds_read_b128 v[152:155], v240 offset:17408
	ds_read_b128 v[156:159], v240 offset:18432
	ds_read_b128 v[160:163], v240 offset:19456
	ds_read_b128 v[164:167], v240 offset:20480
	ds_read_b128 v[168:171], v240 offset:21504
	ds_read_b128 v[172:175], v240 offset:22528
	global_load_lds_dwordx4 v0, s[46:47]
	s_mov_b32 m0, s74
	ds_read_b128 v[204:207], v240 offset:23552
	global_load_lds_dwordx4 v178, s[46:47]
	s_barrier
	s_waitcnt lgkmcnt(0)
	v_mfma_f32_16x16x32_bf16 v[96:99], v[132:135], v[148:151], v[96:99]
	v_mfma_f32_16x16x32_bf16 v[92:95], v[140:143], v[148:151], v[92:95]
	v_mfma_f32_16x16x32_bf16 v[88:91], v[132:135], v[156:159], v[88:91]
	v_mfma_f32_16x16x32_bf16 v[84:87], v[140:143], v[156:159], v[84:87]
	v_mfma_f32_16x16x32_bf16 v[80:83], v[132:135], v[164:167], v[80:83]
	v_mfma_f32_16x16x32_bf16 v[76:79], v[140:143], v[164:167], v[76:79]
	v_mfma_f32_16x16x32_bf16 v[72:75], v[132:135], v[172:175], v[72:75]
	v_mfma_f32_16x16x32_bf16 v[68:71], v[140:143], v[172:175], v[68:71]
	v_mfma_f32_16x16x32_bf16 v[96:99], v[136:139], v[152:155], v[96:99]
	v_mfma_f32_16x16x32_bf16 v[92:95], v[144:147], v[152:155], v[92:95]
	v_mfma_f32_16x16x32_bf16 v[88:91], v[136:139], v[160:163], v[88:91]
	v_mfma_f32_16x16x32_bf16 v[84:87], v[144:147], v[160:163], v[84:87]
	v_mfma_f32_16x16x32_bf16 v[80:83], v[136:139], v[168:171], v[80:83]
	v_mfma_f32_16x16x32_bf16 v[76:79], v[144:147], v[168:171], v[76:79]
	v_mfma_f32_16x16x32_bf16 v[72:75], v[136:139], v[204:207], v[72:75]
	v_mfma_f32_16x16x32_bf16 v[68:71], v[144:147], v[204:207], v[68:71]
	s_barrier
	s_add_i32 s23, s23, s61
	s_mov_b32 m0, s23
	s_add_u32 s24, s44, 0x40000
	s_addc_u32 s25, s45, 0
	global_load_lds_dwordx4 v176, s[24:25]
	s_add_i32 m0, s23, 0x2000
	s_waitcnt vmcnt(5)
	global_load_lds_dwordx4 v180, s[24:25]
	s_barrier
	v_mfma_f32_16x16x32_bf16 v[32:35], v[208:211], v[148:151], v[32:35]
	v_mfma_f32_16x16x32_bf16 v[28:31], v[242:245], v[148:151], v[28:31]
	v_mfma_f32_16x16x32_bf16 v[24:27], v[208:211], v[156:159], v[24:27]
	v_mfma_f32_16x16x32_bf16 v[20:23], v[242:245], v[156:159], v[20:23]
	v_mfma_f32_16x16x32_bf16 v[16:19], v[208:211], v[164:167], v[16:19]
	v_mfma_f32_16x16x32_bf16 v[12:15], v[242:245], v[164:167], v[12:15]
	v_mfma_f32_16x16x32_bf16 v[8:11], v[208:211], v[172:175], v[8:11]
	v_mfma_f32_16x16x32_bf16 v[4:7], v[242:245], v[172:175], v[4:7]
	v_mfma_f32_16x16x32_bf16 v[32:35], v[212:215], v[152:155], v[32:35]
	v_mfma_f32_16x16x32_bf16 v[28:31], v[246:249], v[152:155], v[28:31]
	v_mfma_f32_16x16x32_bf16 v[24:27], v[212:215], v[160:163], v[24:27]
	v_mfma_f32_16x16x32_bf16 v[20:23], v[246:249], v[160:163], v[20:23]
	v_mfma_f32_16x16x32_bf16 v[16:19], v[212:215], v[168:171], v[16:19]
	v_mfma_f32_16x16x32_bf16 v[12:15], v[246:249], v[168:171], v[12:15]
	v_mfma_f32_16x16x32_bf16 v[8:11], v[212:215], v[204:207], v[8:11]
	v_mfma_f32_16x16x32_bf16 v[4:7], v[246:249], v[204:207], v[4:7]
	s_add_i32 s23, 0, 0x18000
	s_barrier
	ds_read_b128 v[132:135], v216 offset:32768
	ds_read_b128 v[136:139], v216 offset:33792
	ds_read_b128 v[140:143], v216 offset:34816
	ds_read_b128 v[144:147], v216 offset:35840
	s_add_u32 s24, s46, 0x40000
	s_addc_u32 s25, s47, 0
	s_mov_b32 m0, s75
	ds_read_b128 v[148:151], v240 offset:32768
	ds_read_b128 v[152:155], v240 offset:33792
	ds_read_b128 v[156:159], v240 offset:34816
	ds_read_b128 v[160:163], v240 offset:35840
	ds_read_b128 v[164:167], v240 offset:36864
	ds_read_b128 v[168:171], v240 offset:37888
	ds_read_b128 v[172:175], v240 offset:38912
	global_load_lds_dwordx4 v0, s[24:25]
	s_mov_b32 m0, s82
	ds_read_b128 v[204:207], v240 offset:39936
	global_load_lds_dwordx4 v178, s[24:25]
	s_waitcnt lgkmcnt(8)
	s_barrier
	s_waitcnt lgkmcnt(0)
	v_mfma_f32_16x16x32_bf16 v[128:131], v[132:135], v[148:151], v[128:131]
	v_mfma_f32_16x16x32_bf16 v[124:127], v[140:143], v[148:151], v[124:127]
	v_mfma_f32_16x16x32_bf16 v[120:123], v[132:135], v[156:159], v[120:123]
	v_mfma_f32_16x16x32_bf16 v[116:119], v[140:143], v[156:159], v[116:119]
	v_mfma_f32_16x16x32_bf16 v[112:115], v[132:135], v[164:167], v[112:115]
	v_mfma_f32_16x16x32_bf16 v[108:111], v[140:143], v[164:167], v[108:111]
	v_mfma_f32_16x16x32_bf16 v[104:107], v[132:135], v[172:175], v[104:107]
	v_mfma_f32_16x16x32_bf16 v[100:103], v[140:143], v[172:175], v[100:103]
	v_mfma_f32_16x16x32_bf16 v[128:131], v[136:139], v[152:155], v[128:131]
	v_mfma_f32_16x16x32_bf16 v[124:127], v[144:147], v[152:155], v[124:127]
	v_mfma_f32_16x16x32_bf16 v[120:123], v[136:139], v[160:163], v[120:123]
	v_mfma_f32_16x16x32_bf16 v[116:119], v[144:147], v[160:163], v[116:119]
	v_mfma_f32_16x16x32_bf16 v[112:115], v[136:139], v[168:171], v[112:115]
	v_mfma_f32_16x16x32_bf16 v[108:111], v[144:147], v[168:171], v[108:111]
	v_mfma_f32_16x16x32_bf16 v[104:107], v[136:139], v[204:207], v[104:107]
	v_mfma_f32_16x16x32_bf16 v[100:103], v[144:147], v[204:207], v[100:103]
	s_barrier
	s_add_i32 s26, 0, 0x1c000
	s_add_i32 s23, s23, s61
	s_mov_b32 m0, s23
	ds_read_b128 v[208:211], v216 offset:49152
	ds_read_b128 v[212:215], v216 offset:50176
	ds_read_b128 v[242:245], v216 offset:51200
	s_add_u32 s98, s44, 0x80
	s_addc_u32 s99, s45, 0
	global_load_lds_dwordx4 v176, s[98:99]
	s_add_i32 m0, s23, 0x2000
	ds_read_b128 v[246:249], v216 offset:52224
	global_load_lds_dwordx4 v180, s[98:99]
	s_barrier
	s_waitcnt lgkmcnt(0)
	v_mfma_f32_16x16x32_bf16 v[64:67], v[208:211], v[148:151], v[64:67]
	v_mfma_f32_16x16x32_bf16 v[60:63], v[242:245], v[148:151], v[60:63]
	v_mfma_f32_16x16x32_bf16 v[56:59], v[208:211], v[156:159], v[56:59]
	v_mfma_f32_16x16x32_bf16 v[52:55], v[242:245], v[156:159], v[52:55]
	v_mfma_f32_16x16x32_bf16 v[48:51], v[208:211], v[164:167], v[48:51]
	v_mfma_f32_16x16x32_bf16 v[44:47], v[242:245], v[164:167], v[44:47]
	v_mfma_f32_16x16x32_bf16 v[40:43], v[208:211], v[172:175], v[40:43]
	v_mfma_f32_16x16x32_bf16 v[36:39], v[242:245], v[172:175], v[36:39]
	v_mfma_f32_16x16x32_bf16 v[64:67], v[212:215], v[152:155], v[64:67]
	v_mfma_f32_16x16x32_bf16 v[60:63], v[246:249], v[152:155], v[60:63]
	v_mfma_f32_16x16x32_bf16 v[56:59], v[212:215], v[160:163], v[56:59]
	v_mfma_f32_16x16x32_bf16 v[52:55], v[246:249], v[160:163], v[52:55]
	v_mfma_f32_16x16x32_bf16 v[48:51], v[212:215], v[168:171], v[48:51]
	v_mfma_f32_16x16x32_bf16 v[44:47], v[246:249], v[168:171], v[44:47]
	v_mfma_f32_16x16x32_bf16 v[40:43], v[212:215], v[204:207], v[40:43]
	v_mfma_f32_16x16x32_bf16 v[36:39], v[246:249], v[204:207], v[36:39]
	s_mov_b32 m0, s48
	s_barrier
	ds_read_b128 v[148:151], v240 offset:49152
	ds_read_b128 v[152:155], v240 offset:50176
	ds_read_b128 v[156:159], v240 offset:51200
	ds_read_b128 v[160:163], v240 offset:52224
	ds_read_b128 v[164:167], v240 offset:53248
	ds_read_b128 v[168:171], v240 offset:54272
	ds_read_b128 v[172:175], v240 offset:55296
	s_add_u32 s98, s46, 0x80
	s_addc_u32 s99, s47, 0
	global_load_lds_dwordx4 v0, s[98:99]
	s_mov_b32 m0, s50
	ds_read_b128 v[204:207], v240 offset:56320
	global_load_lds_dwordx4 v178, s[98:99]
	s_barrier
	s_waitcnt lgkmcnt(0)
	v_mfma_f32_16x16x32_bf16 v[96:99], v[132:135], v[148:151], v[96:99]
	v_mfma_f32_16x16x32_bf16 v[92:95], v[140:143], v[148:151], v[92:95]
	v_mfma_f32_16x16x32_bf16 v[88:91], v[132:135], v[156:159], v[88:91]
	v_mfma_f32_16x16x32_bf16 v[84:87], v[140:143], v[156:159], v[84:87]
	v_mfma_f32_16x16x32_bf16 v[80:83], v[132:135], v[164:167], v[80:83]
	v_mfma_f32_16x16x32_bf16 v[76:79], v[140:143], v[164:167], v[76:79]
	v_mfma_f32_16x16x32_bf16 v[72:75], v[132:135], v[172:175], v[72:75]
	v_mfma_f32_16x16x32_bf16 v[68:71], v[140:143], v[172:175], v[68:71]
	v_mfma_f32_16x16x32_bf16 v[96:99], v[136:139], v[152:155], v[96:99]
	v_mfma_f32_16x16x32_bf16 v[92:95], v[144:147], v[152:155], v[92:95]
	v_mfma_f32_16x16x32_bf16 v[88:91], v[136:139], v[160:163], v[88:91]
	v_mfma_f32_16x16x32_bf16 v[84:87], v[144:147], v[160:163], v[84:87]
	v_mfma_f32_16x16x32_bf16 v[80:83], v[136:139], v[168:171], v[80:83]
	v_mfma_f32_16x16x32_bf16 v[76:79], v[144:147], v[168:171], v[76:79]
	v_mfma_f32_16x16x32_bf16 v[72:75], v[136:139], v[204:207], v[72:75]
	v_mfma_f32_16x16x32_bf16 v[68:71], v[144:147], v[204:207], v[68:71]
	s_barrier
	s_add_i32 s23, s26, s61
	s_mov_b32 m0, s23
	s_add_u32 s24, s44, 0x40080
	s_addc_u32 s25, s45, 0
	global_load_lds_dwordx4 v176, s[24:25]
	s_add_i32 m0, s23, 0x2000
	s_waitcnt vmcnt(5)
	global_load_lds_dwordx4 v180, s[24:25]
	s_barrier
	v_mfma_f32_16x16x32_bf16 v[32:35], v[208:211], v[148:151], v[32:35]
	v_mfma_f32_16x16x32_bf16 v[28:31], v[242:245], v[148:151], v[28:31]
	v_mfma_f32_16x16x32_bf16 v[24:27], v[208:211], v[156:159], v[24:27]
	v_mfma_f32_16x16x32_bf16 v[20:23], v[242:245], v[156:159], v[20:23]
	v_mfma_f32_16x16x32_bf16 v[16:19], v[208:211], v[164:167], v[16:19]
	v_mfma_f32_16x16x32_bf16 v[12:15], v[242:245], v[164:167], v[12:15]
	v_mfma_f32_16x16x32_bf16 v[8:11], v[208:211], v[172:175], v[8:11]
	v_mfma_f32_16x16x32_bf16 v[4:7], v[242:245], v[172:175], v[4:7]
	v_mfma_f32_16x16x32_bf16 v[32:35], v[212:215], v[152:155], v[32:35]
	v_mfma_f32_16x16x32_bf16 v[28:31], v[246:249], v[152:155], v[28:31]
	v_mfma_f32_16x16x32_bf16 v[24:27], v[212:215], v[160:163], v[24:27]
	v_mfma_f32_16x16x32_bf16 v[20:23], v[246:249], v[160:163], v[20:23]
	v_mfma_f32_16x16x32_bf16 v[16:19], v[212:215], v[168:171], v[16:19]
	v_mfma_f32_16x16x32_bf16 v[12:15], v[246:249], v[168:171], v[12:15]
	v_mfma_f32_16x16x32_bf16 v[8:11], v[212:215], v[204:207], v[8:11]
	v_mfma_f32_16x16x32_bf16 v[4:7], v[246:249], v[204:207], v[4:7]
	s_add_i32 s22, s22, 2
	s_add_u32 s0, s0, 0x100
	s_addc_u32 s1, s1, 0
	s_add_u32 s20, s20, 0x100
	s_addc_u32 s21, s21, 0
	s_cmp_gt_u32 s22, 13
	s_barrier
	s_cbranch_scc0 .LBB0_242
	s_add_i32 s0, s66, -8
	s_cmp_lt_u32 s0, 12
	s_mov_b64 s[0:1], -1
	s_cbranch_scc1 .LBB0_266
	s_cmp_gt_i32 s66, 33
	s_cselect_b64 s[64:65], -1, 0
	s_lshl_b32 s0, s66, 8
	s_lshl_b32 s53, s60, 8
	s_add_i32 s1, s0, 0xffffee00
	s_cmp_lt_i32 s66, 26
	v_cndmask_b32_e64 v2, 0, 1, s[80:81]
	s_cselect_b32 s62, s0, s1
	s_mov_b64 s[0:1], -1
	s_and_b64 vcc, exec, s[64:65]
	v_cmp_ne_u32_e64 s[44:45], 1, v2
	s_cbranch_vccz .LBB0_248
	s_and_b64 vcc, exec, s[44:45]
	s_cbranch_vccnz .LBB0_247
	v_add_u32_e32 v132, s53, v185
	v_ashrrev_i32_e32 v133, 31, v132
	v_lshlrev_b64 v[140:141], 7, v[132:133]
	global_load_dwordx4 v[132:135], v[188:189], off offset:16
	global_load_dwordx4 v[136:139], v[188:189], off
	s_mov_b32 s3, 0xbfb8aa3b
	s_mov_b32 s2, 0x800000
	s_mov_b32 s5, 0x3f317217
	s_mov_b32 s6, 0x7f800000
	s_waitcnt vmcnt(0)
	v_add_f32_e32 v147, v126, v134
	v_add_f32_e32 v2, v128, v136
	v_max_f32_e32 v142, 0, v2
	v_mul_f32_e64 v2, |v2|, s3
	v_exp_f32_e32 v2, v2
	v_add_f32_e32 v136, v124, v132
	v_add_f32_e32 v149, v127, v135
	v_add_f32_e32 v2, 1.0, v2
	v_cmp_gt_f32_e32 vcc, s2, v2
	s_nop 1
	v_cndmask_b32_e64 v132, 0, 32, vcc
	v_ldexp_f32 v2, v2, v132
	v_log_f32_e32 v2, v2
	s_nop 0
	v_mul_f32_e32 v132, 0x3f317217, v2
	v_fma_f32 v132, v2, s5, -v132
	v_fmac_f32_e32 v132, 0x3377d1cf, v2
	v_fmac_f32_e32 v132, 0x3f317217, v2
	v_cmp_lt_f32_e64 s[0:1], |v2|, s6
	s_nop 1
	v_cndmask_b32_e64 v2, v2, v132, s[0:1]
	v_cndmask_b32_e32 v132, 0, v228, vcc
	v_sub_f32_e32 v144, v2, v132
	v_mul_f32_e64 v2, |v136|, s3
	v_exp_f32_e32 v2, v2
	v_max_f32_e32 v132, 0, v136
	v_add_f32_e32 v2, 1.0, v2
	v_cmp_gt_f32_e32 vcc, s2, v2
	s_nop 1
	v_cndmask_b32_e64 v136, 0, 32, vcc
	v_ldexp_f32 v2, v2, v136
	v_log_f32_e32 v2, v2
	s_nop 0
	v_mul_f32_e32 v136, 0x3f317217, v2
	v_fma_f32 v136, v2, s5, -v136
	v_fmac_f32_e32 v136, 0x3377d1cf, v2
	v_fmac_f32_e32 v136, 0x3f317217, v2
	v_cmp_lt_f32_e64 s[0:1], |v2|, s6
	s_nop 1
	v_cndmask_b32_e64 v2, v2, v136, s[0:1]
	v_cndmask_b32_e32 v136, 0, v228, vcc
	v_sub_f32_e32 v136, v2, v136
	v_add_f32_e32 v2, v129, v137
	v_max_f32_e32 v143, 0, v2
	v_mul_f32_e64 v2, |v2|, s3
	v_exp_f32_e32 v2, v2
	v_add_f32_e32 v137, v125, v133
	v_add_f32_e32 v2, 1.0, v2
	v_cmp_gt_f32_e32 vcc, s2, v2
	s_nop 1
	v_cndmask_b32_e64 v133, 0, 32, vcc
	v_ldexp_f32 v2, v2, v133
	v_log_f32_e32 v2, v2
	s_nop 0
	v_mul_f32_e32 v133, 0x3f317217, v2
	v_fma_f32 v133, v2, s5, -v133
	v_fmac_f32_e32 v133, 0x3377d1cf, v2
	v_fmac_f32_e32 v133, 0x3f317217, v2
	v_cmp_lt_f32_e64 s[0:1], |v2|, s6
	s_nop 1
	v_cndmask_b32_e64 v2, v2, v133, s[0:1]
	v_cndmask_b32_e32 v133, 0, v228, vcc
	v_sub_f32_e32 v145, v2, v133
	v_mul_f32_e64 v2, |v137|, s3
	v_exp_f32_e32 v2, v2
	v_max_f32_e32 v133, 0, v137
	v_pk_add_f32 v[142:143], v[142:143], v[144:145]
	v_add_f32_e32 v2, 1.0, v2
	v_cmp_gt_f32_e32 vcc, s2, v2
	s_nop 1
	v_cndmask_b32_e64 v137, 0, 32, vcc
	v_ldexp_f32 v2, v2, v137
	v_log_f32_e32 v2, v2
	s_nop 0
	v_mul_f32_e32 v137, 0x3f317217, v2
	v_fma_f32 v137, v2, s5, -v137
	v_fmac_f32_e32 v137, 0x3377d1cf, v2
	v_fmac_f32_e32 v137, 0x3f317217, v2
	v_cmp_lt_f32_e64 s[0:1], |v2|, s6
	s_nop 1
	v_cndmask_b32_e64 v2, v2, v137, s[0:1]
	v_cndmask_b32_e32 v137, 0, v228, vcc
	v_sub_f32_e32 v137, v2, v137
	v_add_f32_e32 v2, v130, v138
	v_max_f32_e32 v138, 0, v2
	v_mul_f32_e64 v2, |v2|, s3
	v_exp_f32_e32 v2, v2
	v_pk_add_f32 v[132:133], v[132:133], v[136:137]
	v_lshl_add_u64 v[136:137], v[190:191], 0, v[140:141]
	v_add_f32_e32 v2, 1.0, v2
	v_cmp_gt_f32_e32 vcc, s2, v2
	s_nop 1
	v_cndmask_b32_e64 v134, 0, 32, vcc
	v_ldexp_f32 v2, v2, v134
	v_log_f32_e32 v2, v2
	s_nop 0
	v_mul_f32_e32 v134, 0x3f317217, v2
	v_fma_f32 v134, v2, s5, -v134
	v_fmac_f32_e32 v134, 0x3377d1cf, v2
	v_fmac_f32_e32 v134, 0x3f317217, v2
	v_cmp_lt_f32_e64 s[0:1], |v2|, s6
	s_nop 1
	v_cndmask_b32_e64 v2, v2, v134, s[0:1]
	v_cndmask_b32_e32 v134, 0, v228, vcc
	v_sub_f32_e32 v146, v2, v134
	v_mul_f32_e64 v2, |v147|, s3
	v_exp_f32_e32 v2, v2
	v_max_f32_e32 v134, 0, v147
	v_add_f32_e32 v2, 1.0, v2
	v_cmp_gt_f32_e32 vcc, s2, v2
	s_nop 1
	v_cndmask_b32_e64 v147, 0, 32, vcc
	v_ldexp_f32 v2, v2, v147
	v_log_f32_e32 v2, v2
	s_nop 0
	v_mul_f32_e32 v147, 0x3f317217, v2
	v_fma_f32 v147, v2, s5, -v147
	v_fmac_f32_e32 v147, 0x3377d1cf, v2
	v_fmac_f32_e32 v147, 0x3f317217, v2
	v_cmp_lt_f32_e64 s[0:1], |v2|, s6
	s_nop 1
	v_cndmask_b32_e64 v2, v2, v147, s[0:1]
	v_cndmask_b32_e32 v147, 0, v228, vcc
	v_sub_f32_e32 v148, v2, v147
	v_add_f32_e32 v2, v131, v139
	v_max_f32_e32 v139, 0, v2
	v_mul_f32_e64 v2, |v2|, s3
	v_exp_f32_e32 v2, v2
	s_nop 0
	v_add_f32_e32 v2, 1.0, v2
	v_cmp_gt_f32_e32 vcc, s2, v2
	s_nop 1
	v_cndmask_b32_e64 v135, 0, 32, vcc
	v_ldexp_f32 v2, v2, v135
	v_log_f32_e32 v2, v2
	s_nop 0
	v_mul_f32_e32 v135, 0x3f317217, v2
	v_fma_f32 v135, v2, s5, -v135
	v_fmac_f32_e32 v135, 0x3377d1cf, v2
	v_fmac_f32_e32 v135, 0x3f317217, v2
	v_cmp_lt_f32_e64 s[0:1], |v2|, s6
	s_nop 1
	v_cndmask_b32_e64 v2, v2, v135, s[0:1]
	v_cndmask_b32_e32 v135, 0, v228, vcc
	v_sub_f32_e32 v147, v2, v135
	v_mul_f32_e64 v2, |v149|, s3
	v_exp_f32_e32 v2, v2
	v_pk_add_f32 v[144:145], v[138:139], v[146:147]
	v_max_f32_e32 v135, 0, v149
	v_add_f32_e32 v2, 1.0, v2
	v_cmp_gt_f32_e32 vcc, s2, v2
	s_nop 1
	v_cndmask_b32_e64 v138, 0, 32, vcc
	v_ldexp_f32 v2, v2, v138
	v_log_f32_e32 v2, v2
	s_nop 0
	v_mul_f32_e32 v138, 0x3f317217, v2
	v_fma_f32 v138, v2, s5, -v138
	v_fmac_f32_e32 v138, 0x3377d1cf, v2
	v_fmac_f32_e32 v138, 0x3f317217, v2
	v_cmp_lt_f32_e64 s[0:1], |v2|, s6
	s_nop 1
	v_cndmask_b32_e64 v2, v2, v138, s[0:1]
	v_cndmask_b32_e32 v138, 0, v228, vcc
	v_sub_f32_e32 v149, v2, v138
	v_pk_add_f32 v[134:135], v[134:135], v[148:149]
	global_store_dwordx4 v[136:137], v[142:145], off
	global_store_dwordx4 v[136:137], v[132:135], off offset:16

.LBB0_427:
	s_add_u32 s23, s0, 0xfffc0080
	s_addc_u32 s24, s1, -1
	s_add_i32 s25, 0, 0x10000
	ds_read_b128 v[132:135], v216
	ds_read_b128 v[136:139], v216 offset:1024
	ds_read_b128 v[140:143], v216 offset:2048
	ds_read_b128 v[144:147], v216 offset:3072
	s_cmp_eq_u32 s22, 12
	s_cselect_b32 s47, s57, s24
	s_cselect_b32 s46, s56, s23
	s_cselect_b32 s45, s59, s21
	s_cselect_b32 s44, s58, s20
	s_add_i32 m0, s74, 0xc000
	ds_read_b128 v[148:151], v240
	ds_read_b128 v[152:155], v240 offset:1024
	ds_read_b128 v[156:159], v240 offset:2048
	ds_read_b128 v[160:163], v240 offset:3072
	ds_read_b128 v[164:167], v240 offset:4096
	ds_read_b128 v[168:171], v240 offset:5120
	ds_read_b128 v[172:175], v240 offset:6144
	global_load_lds_dwordx4 v194, s[0:1]
	s_add_i32 m0, s74, 0xe000
	ds_read_b128 v[204:207], v240 offset:7168
	global_load_lds_dwordx4 v202, s[0:1]
	s_waitcnt lgkmcnt(8)
	s_barrier
	s_waitcnt lgkmcnt(0)
	v_mfma_f32_16x16x32_bf16 v[128:131], v[132:135], v[148:151], v[128:131]
	v_mfma_f32_16x16x32_bf16 v[124:127], v[140:143], v[148:151], v[124:127]
	v_mfma_f32_16x16x32_bf16 v[120:123], v[132:135], v[156:159], v[120:123]
	v_mfma_f32_16x16x32_bf16 v[116:119], v[140:143], v[156:159], v[116:119]
	v_mfma_f32_16x16x32_bf16 v[112:115], v[132:135], v[164:167], v[112:115]
	v_mfma_f32_16x16x32_bf16 v[108:111], v[140:143], v[164:167], v[108:111]
	v_mfma_f32_16x16x32_bf16 v[104:107], v[132:135], v[172:175], v[104:107]
	v_mfma_f32_16x16x32_bf16 v[100:103], v[140:143], v[172:175], v[100:103]
	v_mfma_f32_16x16x32_bf16 v[128:131], v[136:139], v[152:155], v[128:131]
	v_mfma_f32_16x16x32_bf16 v[124:127], v[144:147], v[152:155], v[124:127]
	v_mfma_f32_16x16x32_bf16 v[120:123], v[136:139], v[160:163], v[120:123]
	v_mfma_f32_16x16x32_bf16 v[116:119], v[144:147], v[160:163], v[116:119]
	v_mfma_f32_16x16x32_bf16 v[112:115], v[136:139], v[168:171], v[112:115]
	v_mfma_f32_16x16x32_bf16 v[108:111], v[144:147], v[168:171], v[108:111]
	v_mfma_f32_16x16x32_bf16 v[104:107], v[136:139], v[204:207], v[104:107]
	v_mfma_f32_16x16x32_bf16 v[100:103], v[144:147], v[204:207], v[100:103]
	s_barrier
	s_add_i32 s23, 0, 0x14000
	s_add_i32 s24, s25, s67
	s_mov_b32 m0, s24
	ds_read_b128 v[208:211], v216 offset:16384
	ds_read_b128 v[212:215], v216 offset:17408
	ds_read_b128 v[242:245], v216 offset:18432
	global_load_lds_dwordx4 v176, s[44:45]
	s_add_i32 m0, s24, 0x2000
	ds_read_b128 v[246:249], v216 offset:19456
	global_load_lds_dwordx4 v180, s[44:45]
	s_barrier
	s_waitcnt lgkmcnt(0)
	v_mfma_f32_16x16x32_bf16 v[64:67], v[208:211], v[148:151], v[64:67]
	v_mfma_f32_16x16x32_bf16 v[60:63], v[242:245], v[148:151], v[60:63]
	v_mfma_f32_16x16x32_bf16 v[56:59], v[208:211], v[156:159], v[56:59]
	v_mfma_f32_16x16x32_bf16 v[52:55], v[242:245], v[156:159], v[52:55]
	v_mfma_f32_16x16x32_bf16 v[48:51], v[208:211], v[164:167], v[48:51]
	v_mfma_f32_16x16x32_bf16 v[44:47], v[242:245], v[164:167], v[44:47]
	v_mfma_f32_16x16x32_bf16 v[40:43], v[208:211], v[172:175], v[40:43]
	v_mfma_f32_16x16x32_bf16 v[36:39], v[242:245], v[172:175], v[36:39]
	v_mfma_f32_16x16x32_bf16 v[64:67], v[212:215], v[152:155], v[64:67]
	v_mfma_f32_16x16x32_bf16 v[60:63], v[246:249], v[152:155], v[60:63]
	v_mfma_f32_16x16x32_bf16 v[56:59], v[212:215], v[160:163], v[56:59]
	v_mfma_f32_16x16x32_bf16 v[52:55], v[246:249], v[160:163], v[52:55]
	v_mfma_f32_16x16x32_bf16 v[48:51], v[212:215], v[168:171], v[48:51]
	v_mfma_f32_16x16x32_bf16 v[44:47], v[246:249], v[168:171], v[44:47]
	v_mfma_f32_16x16x32_bf16 v[40:43], v[212:215], v[204:207], v[40:43]
	v_mfma_f32_16x16x32_bf16 v[36:39], v[246:249], v[204:207], v[36:39]
	s_mov_b32 m0, s74
	s_barrier
	ds_read_b128 v[148:151], v240 offset:16384
	ds_read_b128 v[152:155], v240 offset:17408
	ds_read_b128 v[156:159], v240 offset:18432
	ds_read_b128 v[160:163], v240 offset:19456
	ds_read_b128 v[164:167], v240 offset:20480
	ds_read_b128 v[168:171], v240 offset:21504
	ds_read_b128 v[172:175], v240 offset:22528
	global_load_lds_dwordx4 v0, s[46:47]
	s_mov_b32 m0, s75
	ds_read_b128 v[204:207], v240 offset:23552
	global_load_lds_dwordx4 v178, s[46:47]
	s_barrier
	s_waitcnt lgkmcnt(0)
	v_mfma_f32_16x16x32_bf16 v[96:99], v[132:135], v[148:151], v[96:99]
	v_mfma_f32_16x16x32_bf16 v[92:95], v[140:143], v[148:151], v[92:95]
	v_mfma_f32_16x16x32_bf16 v[88:91], v[132:135], v[156:159], v[88:91]
	v_mfma_f32_16x16x32_bf16 v[84:87], v[140:143], v[156:159], v[84:87]
	v_mfma_f32_16x16x32_bf16 v[80:83], v[132:135], v[164:167], v[80:83]
	v_mfma_f32_16x16x32_bf16 v[76:79], v[140:143], v[164:167], v[76:79]
	v_mfma_f32_16x16x32_bf16 v[72:75], v[132:135], v[172:175], v[72:75]
	v_mfma_f32_16x16x32_bf16 v[68:71], v[140:143], v[172:175], v[68:71]
	v_mfma_f32_16x16x32_bf16 v[96:99], v[136:139], v[152:155], v[96:99]
	v_mfma_f32_16x16x32_bf16 v[92:95], v[144:147], v[152:155], v[92:95]
	v_mfma_f32_16x16x32_bf16 v[88:91], v[136:139], v[160:163], v[88:91]
	v_mfma_f32_16x16x32_bf16 v[84:87], v[144:147], v[160:163], v[84:87]
	v_mfma_f32_16x16x32_bf16 v[80:83], v[136:139], v[168:171], v[80:83]
	v_mfma_f32_16x16x32_bf16 v[76:79], v[144:147], v[168:171], v[76:79]
	v_mfma_f32_16x16x32_bf16 v[72:75], v[136:139], v[204:207], v[72:75]
	v_mfma_f32_16x16x32_bf16 v[68:71], v[144:147], v[204:207], v[68:71]
	s_barrier
	s_add_i32 s23, s23, s67
	s_mov_b32 m0, s23
	s_add_u32 s24, s44, 0x40000
	s_addc_u32 s25, s45, 0
	global_load_lds_dwordx4 v176, s[24:25]
	s_add_i32 m0, s23, 0x2000
	s_waitcnt vmcnt(5)
	global_load_lds_dwordx4 v180, s[24:25]
	s_barrier
	v_mfma_f32_16x16x32_bf16 v[32:35], v[208:211], v[148:151], v[32:35]
	v_mfma_f32_16x16x32_bf16 v[28:31], v[242:245], v[148:151], v[28:31]
	v_mfma_f32_16x16x32_bf16 v[24:27], v[208:211], v[156:159], v[24:27]
	v_mfma_f32_16x16x32_bf16 v[20:23], v[242:245], v[156:159], v[20:23]
	v_mfma_f32_16x16x32_bf16 v[16:19], v[208:211], v[164:167], v[16:19]
	v_mfma_f32_16x16x32_bf16 v[12:15], v[242:245], v[164:167], v[12:15]
	v_mfma_f32_16x16x32_bf16 v[8:11], v[208:211], v[172:175], v[8:11]
	v_mfma_f32_16x16x32_bf16 v[4:7], v[242:245], v[172:175], v[4:7]
	v_mfma_f32_16x16x32_bf16 v[32:35], v[212:215], v[152:155], v[32:35]
	v_mfma_f32_16x16x32_bf16 v[28:31], v[246:249], v[152:155], v[28:31]
	v_mfma_f32_16x16x32_bf16 v[24:27], v[212:215], v[160:163], v[24:27]
	v_mfma_f32_16x16x32_bf16 v[20:23], v[246:249], v[160:163], v[20:23]
	v_mfma_f32_16x16x32_bf16 v[16:19], v[212:215], v[168:171], v[16:19]
	v_mfma_f32_16x16x32_bf16 v[12:15], v[246:249], v[168:171], v[12:15]
	v_mfma_f32_16x16x32_bf16 v[8:11], v[212:215], v[204:207], v[8:11]
	v_mfma_f32_16x16x32_bf16 v[4:7], v[246:249], v[204:207], v[4:7]
	s_add_i32 s23, 0, 0x18000
	s_barrier
	ds_read_b128 v[132:135], v216 offset:32768
	ds_read_b128 v[136:139], v216 offset:33792
	ds_read_b128 v[140:143], v216 offset:34816
	ds_read_b128 v[144:147], v216 offset:35840
	s_add_u32 s24, s46, 0x40000
	s_addc_u32 s25, s47, 0
	s_mov_b32 m0, s82
	ds_read_b128 v[148:151], v240 offset:32768
	ds_read_b128 v[152:155], v240 offset:33792
	ds_read_b128 v[156:159], v240 offset:34816
	ds_read_b128 v[160:163], v240 offset:35840
	ds_read_b128 v[164:167], v240 offset:36864
	ds_read_b128 v[168:171], v240 offset:37888
	ds_read_b128 v[172:175], v240 offset:38912
	global_load_lds_dwordx4 v0, s[24:25]
	s_mov_b32 m0, s83
	ds_read_b128 v[204:207], v240 offset:39936
	global_load_lds_dwordx4 v178, s[24:25]
	s_waitcnt lgkmcnt(8)
	s_barrier
	s_waitcnt lgkmcnt(0)
	v_mfma_f32_16x16x32_bf16 v[128:131], v[132:135], v[148:151], v[128:131]
	v_mfma_f32_16x16x32_bf16 v[124:127], v[140:143], v[148:151], v[124:127]
	v_mfma_f32_16x16x32_bf16 v[120:123], v[132:135], v[156:159], v[120:123]
	v_mfma_f32_16x16x32_bf16 v[116:119], v[140:143], v[156:159], v[116:119]
	v_mfma_f32_16x16x32_bf16 v[112:115], v[132:135], v[164:167], v[112:115]
	v_mfma_f32_16x16x32_bf16 v[108:111], v[140:143], v[164:167], v[108:111]
	v_mfma_f32_16x16x32_bf16 v[104:107], v[132:135], v[172:175], v[104:107]
	v_mfma_f32_16x16x32_bf16 v[100:103], v[140:143], v[172:175], v[100:103]
	v_mfma_f32_16x16x32_bf16 v[128:131], v[136:139], v[152:155], v[128:131]
	v_mfma_f32_16x16x32_bf16 v[124:127], v[144:147], v[152:155], v[124:127]
	v_mfma_f32_16x16x32_bf16 v[120:123], v[136:139], v[160:163], v[120:123]
	v_mfma_f32_16x16x32_bf16 v[116:119], v[144:147], v[160:163], v[116:119]
	v_mfma_f32_16x16x32_bf16 v[112:115], v[136:139], v[168:171], v[112:115]
	v_mfma_f32_16x16x32_bf16 v[108:111], v[144:147], v[168:171], v[108:111]
	v_mfma_f32_16x16x32_bf16 v[104:107], v[136:139], v[204:207], v[104:107]
	v_mfma_f32_16x16x32_bf16 v[100:103], v[144:147], v[204:207], v[100:103]
	s_barrier
	s_add_i32 s26, 0, 0x1c000
	s_add_i32 s23, s23, s67
	s_mov_b32 m0, s23
	ds_read_b128 v[208:211], v216 offset:49152
	ds_read_b128 v[212:215], v216 offset:50176
	ds_read_b128 v[242:245], v216 offset:51200
	s_add_u32 s98, s44, 0x80
	s_addc_u32 s99, s45, 0
	global_load_lds_dwordx4 v176, s[98:99]
	s_add_i32 m0, s23, 0x2000
	ds_read_b128 v[246:249], v216 offset:52224
	global_load_lds_dwordx4 v180, s[98:99]
	s_barrier
	s_waitcnt lgkmcnt(0)
	v_mfma_f32_16x16x32_bf16 v[64:67], v[208:211], v[148:151], v[64:67]
	v_mfma_f32_16x16x32_bf16 v[60:63], v[242:245], v[148:151], v[60:63]
	v_mfma_f32_16x16x32_bf16 v[56:59], v[208:211], v[156:159], v[56:59]
	v_mfma_f32_16x16x32_bf16 v[52:55], v[242:245], v[156:159], v[52:55]
	v_mfma_f32_16x16x32_bf16 v[48:51], v[208:211], v[164:167], v[48:51]
	v_mfma_f32_16x16x32_bf16 v[44:47], v[242:245], v[164:167], v[44:47]
	v_mfma_f32_16x16x32_bf16 v[40:43], v[208:211], v[172:175], v[40:43]
	v_mfma_f32_16x16x32_bf16 v[36:39], v[242:245], v[172:175], v[36:39]
	v_mfma_f32_16x16x32_bf16 v[64:67], v[212:215], v[152:155], v[64:67]
	v_mfma_f32_16x16x32_bf16 v[60:63], v[246:249], v[152:155], v[60:63]
	v_mfma_f32_16x16x32_bf16 v[56:59], v[212:215], v[160:163], v[56:59]
	v_mfma_f32_16x16x32_bf16 v[52:55], v[246:249], v[160:163], v[52:55]
	v_mfma_f32_16x16x32_bf16 v[48:51], v[212:215], v[168:171], v[48:51]
	v_mfma_f32_16x16x32_bf16 v[44:47], v[246:249], v[168:171], v[44:47]
	v_mfma_f32_16x16x32_bf16 v[40:43], v[212:215], v[204:207], v[40:43]
	v_mfma_f32_16x16x32_bf16 v[36:39], v[246:249], v[204:207], v[36:39]
	s_mov_b32 m0, s48
	s_barrier
	ds_read_b128 v[148:151], v240 offset:49152
	ds_read_b128 v[152:155], v240 offset:50176
	ds_read_b128 v[156:159], v240 offset:51200
	ds_read_b128 v[160:163], v240 offset:52224
	ds_read_b128 v[164:167], v240 offset:53248
	ds_read_b128 v[168:171], v240 offset:54272
	ds_read_b128 v[172:175], v240 offset:55296
	s_add_u32 s98, s46, 0x80
	s_addc_u32 s99, s47, 0
	global_load_lds_dwordx4 v0, s[98:99]
	s_mov_b32 m0, s50
	ds_read_b128 v[204:207], v240 offset:56320
	global_load_lds_dwordx4 v178, s[98:99]
	s_barrier
	s_waitcnt lgkmcnt(0)
	v_mfma_f32_16x16x32_bf16 v[96:99], v[132:135], v[148:151], v[96:99]
	v_mfma_f32_16x16x32_bf16 v[92:95], v[140:143], v[148:151], v[92:95]
	v_mfma_f32_16x16x32_bf16 v[88:91], v[132:135], v[156:159], v[88:91]
	v_mfma_f32_16x16x32_bf16 v[84:87], v[140:143], v[156:159], v[84:87]
	v_mfma_f32_16x16x32_bf16 v[80:83], v[132:135], v[164:167], v[80:83]
	v_mfma_f32_16x16x32_bf16 v[76:79], v[140:143], v[164:167], v[76:79]
	v_mfma_f32_16x16x32_bf16 v[72:75], v[132:135], v[172:175], v[72:75]
	v_mfma_f32_16x16x32_bf16 v[68:71], v[140:143], v[172:175], v[68:71]
	v_mfma_f32_16x16x32_bf16 v[96:99], v[136:139], v[152:155], v[96:99]
	v_mfma_f32_16x16x32_bf16 v[92:95], v[144:147], v[152:155], v[92:95]
	v_mfma_f32_16x16x32_bf16 v[88:91], v[136:139], v[160:163], v[88:91]
	v_mfma_f32_16x16x32_bf16 v[84:87], v[144:147], v[160:163], v[84:87]
	v_mfma_f32_16x16x32_bf16 v[80:83], v[136:139], v[168:171], v[80:83]
	v_mfma_f32_16x16x32_bf16 v[76:79], v[144:147], v[168:171], v[76:79]
	v_mfma_f32_16x16x32_bf16 v[72:75], v[136:139], v[204:207], v[72:75]
	v_mfma_f32_16x16x32_bf16 v[68:71], v[144:147], v[204:207], v[68:71]
	s_barrier
	s_add_i32 s23, s26, s67
	s_mov_b32 m0, s23
	s_add_u32 s24, s44, 0x40080
	s_addc_u32 s25, s45, 0
	global_load_lds_dwordx4 v176, s[24:25]
	s_add_i32 m0, s23, 0x2000
	s_waitcnt vmcnt(5)
	global_load_lds_dwordx4 v180, s[24:25]
	s_barrier
	v_mfma_f32_16x16x32_bf16 v[32:35], v[208:211], v[148:151], v[32:35]
	v_mfma_f32_16x16x32_bf16 v[28:31], v[242:245], v[148:151], v[28:31]
	v_mfma_f32_16x16x32_bf16 v[24:27], v[208:211], v[156:159], v[24:27]
	v_mfma_f32_16x16x32_bf16 v[20:23], v[242:245], v[156:159], v[20:23]
	v_mfma_f32_16x16x32_bf16 v[16:19], v[208:211], v[164:167], v[16:19]
	v_mfma_f32_16x16x32_bf16 v[12:15], v[242:245], v[164:167], v[12:15]
	v_mfma_f32_16x16x32_bf16 v[8:11], v[208:211], v[172:175], v[8:11]
	v_mfma_f32_16x16x32_bf16 v[4:7], v[242:245], v[172:175], v[4:7]
	v_mfma_f32_16x16x32_bf16 v[32:35], v[212:215], v[152:155], v[32:35]
	v_mfma_f32_16x16x32_bf16 v[28:31], v[246:249], v[152:155], v[28:31]
	v_mfma_f32_16x16x32_bf16 v[24:27], v[212:215], v[160:163], v[24:27]
	v_mfma_f32_16x16x32_bf16 v[20:23], v[246:249], v[160:163], v[20:23]
	v_mfma_f32_16x16x32_bf16 v[16:19], v[212:215], v[168:171], v[16:19]
	v_mfma_f32_16x16x32_bf16 v[12:15], v[246:249], v[168:171], v[12:15]
	v_mfma_f32_16x16x32_bf16 v[8:11], v[212:215], v[204:207], v[8:11]
	v_mfma_f32_16x16x32_bf16 v[4:7], v[246:249], v[204:207], v[4:7]
	s_add_i32 s22, s22, 2
	s_add_u32 s0, s0, 0x100
	s_addc_u32 s1, s1, 0
	s_add_u32 s20, s20, 0x100
	s_addc_u32 s21, s21, 0
	s_cmp_gt_u32 s22, 13
	s_barrier
	s_cbranch_scc0 .LBB0_427
	s_add_i32 s0, s61, -8
	s_cmp_lt_u32 s0, 12
	s_mov_b64 s[0:1], -1
	s_cbranch_scc1 .LBB0_451
	s_cmp_gt_i32 s61, 33
	s_cselect_b64 s[64:65], -1, 0
	s_lshl_b32 s0, s61, 8
	s_lshl_b32 s53, s60, 8
	s_add_i32 s1, s0, 0xffffee00
	s_cmp_lt_i32 s61, 26
	v_cndmask_b32_e64 v2, 0, 1, s[36:37]
	s_cselect_b32 s62, s0, s1
	s_mov_b64 s[0:1], -1
	s_and_b64 vcc, exec, s[64:65]
	v_cmp_ne_u32_e64 s[44:45], 1, v2
	s_cbranch_vccz .LBB0_433
	s_and_b64 vcc, exec, s[44:45]
	s_cbranch_vccnz .LBB0_432
	v_add_u32_e32 v132, s53, v185
	v_ashrrev_i32_e32 v133, 31, v132
	v_lshlrev_b64 v[140:141], 7, v[132:133]
	global_load_dwordx4 v[204:207], v[188:189], off offset:16
	global_load_dwordx4 v[208:211], v[188:189], off
	s_mov_b32 s3, 0xbfb8aa3b
	s_mov_b32 s2, 0x800000
	s_mov_b32 s4, 0x3f317217
	s_mov_b32 s5, 0x7f800000
	s_waitcnt vmcnt(0)
	v_mov_b32_e32 v132, v204
	v_mov_b32_e32 v133, v205
	v_mov_b32_e32 v134, v206
	v_mov_b32_e32 v135, v207
	v_mov_b32_e32 v136, v208
	v_mov_b32_e32 v137, v209
	v_mov_b32_e32 v138, v210
	v_mov_b32_e32 v139, v211
	v_add_f32_e32 v147, v126, v134
	v_add_f32_e32 v2, v128, v136
	v_max_f32_e32 v142, 0, v2
	v_mul_f32_e64 v2, |v2|, s3
	v_exp_f32_e32 v2, v2
	v_add_f32_e32 v136, v124, v132
	v_add_f32_e32 v149, v127, v135
	v_add_f32_e32 v2, 1.0, v2
	v_cmp_gt_f32_e32 vcc, s2, v2
	s_nop 1
	v_cndmask_b32_e64 v132, 0, 32, vcc
	v_ldexp_f32 v2, v2, v132
	v_log_f32_e32 v2, v2
	s_nop 0
	v_mul_f32_e32 v132, 0x3f317217, v2
	v_fma_f32 v132, v2, s4, -v132
	v_fmac_f32_e32 v132, 0x3377d1cf, v2
	v_fmac_f32_e32 v132, 0x3f317217, v2
	v_cmp_lt_f32_e64 s[0:1], |v2|, s5
	s_nop 1
	v_cndmask_b32_e64 v2, v2, v132, s[0:1]
	v_cndmask_b32_e32 v132, 0, v228, vcc
	v_sub_f32_e32 v144, v2, v132
	v_mul_f32_e64 v2, |v136|, s3
	v_exp_f32_e32 v2, v2
	v_max_f32_e32 v132, 0, v136
	v_add_f32_e32 v2, 1.0, v2
	v_cmp_gt_f32_e32 vcc, s2, v2
	s_nop 1
	v_cndmask_b32_e64 v136, 0, 32, vcc
	v_ldexp_f32 v2, v2, v136
	v_log_f32_e32 v2, v2
	s_nop 0
	v_mul_f32_e32 v136, 0x3f317217, v2
	v_fma_f32 v136, v2, s4, -v136
	v_fmac_f32_e32 v136, 0x3377d1cf, v2
	v_fmac_f32_e32 v136, 0x3f317217, v2
	v_cmp_lt_f32_e64 s[0:1], |v2|, s5
	s_nop 1
	v_cndmask_b32_e64 v2, v2, v136, s[0:1]
	v_cndmask_b32_e32 v136, 0, v228, vcc
	v_sub_f32_e32 v136, v2, v136
	v_add_f32_e32 v2, v129, v137
	v_max_f32_e32 v143, 0, v2
	v_mul_f32_e64 v2, |v2|, s3
	v_exp_f32_e32 v2, v2
	v_add_f32_e32 v137, v125, v133
	v_add_f32_e32 v2, 1.0, v2
	v_cmp_gt_f32_e32 vcc, s2, v2
	s_nop 1
	v_cndmask_b32_e64 v133, 0, 32, vcc
	v_ldexp_f32 v2, v2, v133
	v_log_f32_e32 v2, v2
	s_nop 0
	v_mul_f32_e32 v133, 0x3f317217, v2
	v_fma_f32 v133, v2, s4, -v133
	v_fmac_f32_e32 v133, 0x3377d1cf, v2
	v_fmac_f32_e32 v133, 0x3f317217, v2
	v_cmp_lt_f32_e64 s[0:1], |v2|, s5
	s_nop 1
	v_cndmask_b32_e64 v2, v2, v133, s[0:1]
	v_cndmask_b32_e32 v133, 0, v228, vcc
	v_sub_f32_e32 v145, v2, v133
	v_mul_f32_e64 v2, |v137|, s3
	v_exp_f32_e32 v2, v2
	v_max_f32_e32 v133, 0, v137
	v_pk_add_f32 v[142:143], v[142:143], v[144:145]
	v_add_f32_e32 v2, 1.0, v2
	v_cmp_gt_f32_e32 vcc, s2, v2
	s_nop 1
	v_cndmask_b32_e64 v137, 0, 32, vcc
	v_ldexp_f32 v2, v2, v137
	v_log_f32_e32 v2, v2
	s_nop 0
	v_mul_f32_e32 v137, 0x3f317217, v2
	v_fma_f32 v137, v2, s4, -v137
	v_fmac_f32_e32 v137, 0x3377d1cf, v2
	v_fmac_f32_e32 v137, 0x3f317217, v2
	v_cmp_lt_f32_e64 s[0:1], |v2|, s5
	s_nop 1
	v_cndmask_b32_e64 v2, v2, v137, s[0:1]
	v_cndmask_b32_e32 v137, 0, v228, vcc
	v_sub_f32_e32 v137, v2, v137
	v_add_f32_e32 v2, v130, v138
	v_max_f32_e32 v138, 0, v2
	v_mul_f32_e64 v2, |v2|, s3
	v_exp_f32_e32 v2, v2
	v_pk_add_f32 v[132:133], v[132:133], v[136:137]
	v_lshl_add_u64 v[136:137], v[190:191], 0, v[140:141]
	v_add_f32_e32 v2, 1.0, v2
	v_cmp_gt_f32_e32 vcc, s2, v2
	s_nop 1
	v_cndmask_b32_e64 v134, 0, 32, vcc
	v_ldexp_f32 v2, v2, v134
	v_log_f32_e32 v2, v2
	s_nop 0
	v_mul_f32_e32 v134, 0x3f317217, v2
	v_fma_f32 v134, v2, s4, -v134
	v_fmac_f32_e32 v134, 0x3377d1cf, v2
	v_fmac_f32_e32 v134, 0x3f317217, v2
	v_cmp_lt_f32_e64 s[0:1], |v2|, s5
	s_nop 1
	v_cndmask_b32_e64 v2, v2, v134, s[0:1]
	v_cndmask_b32_e32 v134, 0, v228, vcc
	v_sub_f32_e32 v146, v2, v134
	v_mul_f32_e64 v2, |v147|, s3
	v_exp_f32_e32 v2, v2
	v_max_f32_e32 v134, 0, v147
	v_add_f32_e32 v2, 1.0, v2
	v_cmp_gt_f32_e32 vcc, s2, v2
	s_nop 1
	v_cndmask_b32_e64 v147, 0, 32, vcc
	v_ldexp_f32 v2, v2, v147
	v_log_f32_e32 v2, v2
	s_nop 0
	v_mul_f32_e32 v147, 0x3f317217, v2
	v_fma_f32 v147, v2, s4, -v147
	v_fmac_f32_e32 v147, 0x3377d1cf, v2
	v_fmac_f32_e32 v147, 0x3f317217, v2
	v_cmp_lt_f32_e64 s[0:1], |v2|, s5
	s_nop 1
	v_cndmask_b32_e64 v2, v2, v147, s[0:1]
	v_cndmask_b32_e32 v147, 0, v228, vcc
	v_sub_f32_e32 v148, v2, v147
	v_add_f32_e32 v2, v131, v139
	v_max_f32_e32 v139, 0, v2
	v_mul_f32_e64 v2, |v2|, s3
	v_exp_f32_e32 v2, v2
	s_nop 0
	v_add_f32_e32 v2, 1.0, v2
	v_cmp_gt_f32_e32 vcc, s2, v2
	s_nop 1
	v_cndmask_b32_e64 v135, 0, 32, vcc
	v_ldexp_f32 v2, v2, v135
	v_log_f32_e32 v2, v2
	s_nop 0
	v_mul_f32_e32 v135, 0x3f317217, v2
	v_fma_f32 v135, v2, s4, -v135
	v_fmac_f32_e32 v135, 0x3377d1cf, v2
	v_fmac_f32_e32 v135, 0x3f317217, v2
	v_cmp_lt_f32_e64 s[0:1], |v2|, s5
	s_nop 1
	v_cndmask_b32_e64 v2, v2, v135, s[0:1]
	v_cndmask_b32_e32 v135, 0, v228, vcc
	v_sub_f32_e32 v147, v2, v135
	v_mul_f32_e64 v2, |v149|, s3
	v_exp_f32_e32 v2, v2
	v_pk_add_f32 v[144:145], v[138:139], v[146:147]
	v_max_f32_e32 v135, 0, v149
	v_add_f32_e32 v2, 1.0, v2
	v_cmp_gt_f32_e32 vcc, s2, v2
	s_nop 1
	v_cndmask_b32_e64 v138, 0, 32, vcc
	v_ldexp_f32 v2, v2, v138
	v_log_f32_e32 v2, v2
	s_nop 0
	v_mul_f32_e32 v138, 0x3f317217, v2
	v_fma_f32 v138, v2, s4, -v138
	v_fmac_f32_e32 v138, 0x3377d1cf, v2
	v_fmac_f32_e32 v138, 0x3f317217, v2
	v_cmp_lt_f32_e64 s[0:1], |v2|, s5
	s_nop 1
	v_cndmask_b32_e64 v2, v2, v138, s[0:1]
	v_cndmask_b32_e32 v138, 0, v228, vcc
	v_sub_f32_e32 v149, v2, v138
	v_pk_add_f32 v[134:135], v[134:135], v[148:149]
	global_store_dwordx4 v[136:137], v[142:145], off
	global_store_dwordx4 v[136:137], v[132:135], off offset:16
